# PEER token header: next token's row-scale pointer math (and its two vmcnt waits) moved from the header to its use in the e0==64 block (on top of v66)
# baseline (speedup 1.0000x reference)
.LBB0_901:
	v_mov_b32_e32 v8, v128
	v_add_u32_e32 v9, 0xffffe000, v8
	v_lshrrev_b32_e32 v9, 12, v9
	v_add_u32_e32 v9, 1, v9
	v_cmp_lt_i32_e32 vcc, s29, v8
	v_lshlrev_b32_e32 v158, 16, v2
	v_and_b32_e32 v159, 0xffff0000, v2
	v_cndmask_b32_e32 v144, 0, v9, vcc
	v_accvgpr_read_b32 v9, a70
	v_add_u32_e32 v128, v8, v9
	v_min_i32_e32 v10, 0x5fff, v128
	v_lshlrev_b32_e32 v160, 16, v3
	v_and_b32_e32 v161, 0xffff0000, v3
	v_ashrrev_i32_e32 v9, 31, v8
	v_accvgpr_read_b32 v2, a72
	v_ashrrev_i32_e32 v11, 31, v10
	v_lshlrev_b32_e32 v154, 16, v0
	v_and_b32_e32 v155, 0xffff0000, v0
	v_lshlrev_b32_e32 v156, 16, v1
	v_and_b32_e32 v157, 0xffff0000, v1
	v_lshlrev_b64 v[0:1], 12, v[8:9]
	v_accvgpr_read_b32 v3, a73
	v_lshlrev_b64 v[12:13], 11, v[10:11]
	v_lshl_add_u64 v[162:163], v[2:3], 0, v[0:1]
	v_accvgpr_read_b32 v2, a230
	v_lshl_add_u64 v[12:13], v[104:105], 0, v[12:13]
	v_lshlrev_b64 v[10:11], 9, v[10:11]
	v_mad_u64_u32 v[0:1], s[10:11], v144, s27, v[114:115]
	v_accvgpr_read_b32 v3, a231
	global_load_dwordx4 a[32:35], v[12:13], off offset:16
	global_load_dwordx4 a[36:39], v[12:13], off
	v_lshl_add_u64 v[12:13], v[110:111], 0, v[10:11]
	v_lshl_add_u64 v[16:17], v[0:1], 0, v[2:3]
	global_load_dword v118, v[12:13], off
	global_load_dword v120, v[12:13], off offset:256
	v_lshl_add_u64 v[24:25], v[16:17], 0, s[20:21]
	v_add_co_u32_e32 v16, vcc, s33, v16
	v_lshl_add_u64 v[10:11], v[112:113], 0, v[10:11]
	s_nop 0
	v_addc_co_u32_e32 v17, vcc, 0, v17, vcc
	s_waitcnt vmcnt(6)
	v_mov_b32_e32 v32, v254
	s_waitcnt vmcnt(4)
	v_mov_b32_e32 v33, v147
	global_load_dword v147, v[10:11], off
	global_load_dword v254, v[10:11], off offset:256
	v_lshlrev_b32_e32 v124, 16, v4
	v_and_b32_e32 v125, 0xffff0000, v4
	v_lshlrev_b32_e32 v126, 16, v5
	v_and_b32_e32 v127, 0xffff0000, v5
	v_lshlrev_b32_e32 v150, 16, v6
	v_and_b32_e32 v151, 0xffff0000, v6
	v_lshlrev_b32_e32 v152, 16, v7
	v_and_b32_e32 v153, 0xffff0000, v7
	v_lshlrev_b64 v[122:123], 10, v[8:9]
	global_load_dwordx4 v[0:3], v[162:163], off offset:48
	global_load_dwordx4 v[4:7], v[162:163], off offset:32
	global_load_dwordx4 v[8:11], v[162:163], off offset:16
	global_load_dwordx4 v[12:15], v[162:163], off
	global_load_dwordx4 v[28:31], v[16:17], off
	s_nop 0
	global_load_dwordx4 v[16:19], v[24:25], off offset:48
	global_load_dwordx4 v[20:23], v[24:25], off offset:32
	s_nop 0
	global_load_dwordx4 v[24:27], v[24:25], off offset:16
	v_mul_f32_e32 v145, v33, v117
	v_mul_f32_e32 v146, v32, v103
	v_mov_b32_e32 v200, 0
	v_accvgpr_read_b32 v205, a43
	v_accvgpr_read_b32 v203, a45
	v_accvgpr_read_b32 v199, a47
	v_accvgpr_read_b32 v197, a49
	v_accvgpr_read_b32 v195, a51
	v_accvgpr_read_b32 v193, a53
	v_accvgpr_read_b32 v191, a55
	v_accvgpr_read_b32 v189, a57
	v_accvgpr_read_b32 v187, a59
	v_accvgpr_read_b32 v185, a61
	v_accvgpr_read_b32 v183, a63
	v_accvgpr_read_b32 v181, a65
	v_accvgpr_read_b32 v179, a67
	v_accvgpr_read_b32 v173, a41
	v_accvgpr_read_b32 v95, a23
	v_accvgpr_read_b32 v91, a27
	v_accvgpr_read_b32 v87, a31
	v_mov_b64_e32 v[80:81], v[232:233]
	v_mov_b64_e32 v[76:77], v[236:237]
	v_mov_b64_e32 v[72:73], v[240:241]
	v_mov_b64_e32 v[68:69], v[244:245]
	v_mov_b64_e32 v[64:65], v[248:249]
	v_accvgpr_read_b32 v63, a3
	v_accvgpr_read_b32 v59, a7
	v_accvgpr_read_b32 v55, a11
	v_accvgpr_read_b32 v51, a15
	v_accvgpr_read_b32 v47, a19
	v_mov_b64_e32 v[40:41], v[220:221]
	v_mov_b64_e32 v[36:37], v[224:225]
	s_mov_b32 s26, 0
	v_accvgpr_read_b32 v204, a42
	v_accvgpr_read_b32 v202, a44
	v_accvgpr_read_b32 v198, a46
	v_accvgpr_read_b32 v196, a48
	v_accvgpr_read_b32 v194, a50
	v_accvgpr_read_b32 v192, a52
	v_accvgpr_read_b32 v190, a54
	v_accvgpr_read_b32 v188, a56
	v_accvgpr_read_b32 v186, a58
	v_accvgpr_read_b32 v184, a60
	v_accvgpr_read_b32 v182, a62
	v_accvgpr_read_b32 v180, a64
	v_accvgpr_read_b32 v178, a66
	v_mov_b64_e32 v[176:177], v[148:149]
	v_mov_b64_e32 v[174:175], v[252:253]
	v_accvgpr_read_b32 v172, a40
	v_accvgpr_read_b32 v94, a22
	v_accvgpr_read_b32 v93, a21
	v_accvgpr_read_b32 v92, a20
	v_accvgpr_read_b32 v90, a26
	v_accvgpr_read_b32 v89, a25
	v_accvgpr_read_b32 v88, a24
	v_accvgpr_read_b32 v86, a30
	v_accvgpr_read_b32 v85, a29
	v_accvgpr_read_b32 v84, a28
	v_mov_b64_e32 v[32:33], v[228:229]
	v_mov_b64_e32 v[82:83], v[234:235]
	v_mov_b64_e32 v[78:79], v[238:239]
	v_mov_b64_e32 v[74:75], v[242:243]
	v_mov_b64_e32 v[70:71], v[246:247]
	v_mov_b64_e32 v[66:67], v[250:251]
	v_accvgpr_read_b32 v62, a2
	v_accvgpr_read_b32 v61, a1
	v_accvgpr_read_b32 v60, a0
	v_accvgpr_read_b32 v58, a6
	v_accvgpr_read_b32 v57, a5
	v_accvgpr_read_b32 v56, a4
	v_accvgpr_read_b32 v54, a10
	v_accvgpr_read_b32 v53, a9
	v_accvgpr_read_b32 v52, a8
	v_accvgpr_read_b32 v50, a14
	v_accvgpr_read_b32 v49, a13
	v_accvgpr_read_b32 v48, a12
	v_accvgpr_read_b32 v46, a18
	v_accvgpr_read_b32 v45, a17
	v_accvgpr_read_b32 v44, a16
	v_mov_b64_e32 v[42:43], v[222:223]
	v_mov_b64_e32 v[38:39], v[226:227]
	v_mov_b64_e32 v[34:35], v[230:231]
	v_mov_b32_e32 v201, v200
	v_mov_b32_e32 v218, v200
	v_mov_b32_e32 v219, v200
	v_mov_b32_e32 v216, v200
	v_mov_b32_e32 v217, v200
	v_mov_b32_e32 v214, v200
	v_mov_b32_e32 v215, v200
	v_mov_b32_e32 v212, v200
	v_mov_b32_e32 v213, v200
	v_mov_b32_e32 v210, v200
	v_mov_b32_e32 v211, v200
	v_mov_b32_e32 v208, v200
	v_mov_b32_e32 v209, v200
	v_mov_b32_e32 v206, v200
	v_mov_b32_e32 v207, v200
.LBB0_902:
	s_add_i32 s58, s26, 16
	s_cmpk_gt_u32 s26, 0x6f
	s_cselect_b64 s[24:25], -1, 0
	s_cmpk_lt_u32 s26, 0x70
	s_cselect_b64 vcc, -1, 0
	s_bitcmp0_b32 s58, 6
	s_cselect_b64 s[10:11], -1, 0
	v_cndmask_b32_e64 v100, v116, v102, s[10:11]
	v_cndmask_b32_e32 v100, v118, v100, vcc
	s_nop 0
	v_readlane_b32 s28, v100, s58
	s_nop 1
	v_mad_i64_i32 v[148:149], s[10:11], s28, v130, v[96:97]
	global_load_dwordx4 a[20:23], v[148:149], off
	v_mad_i64_i32 v[148:149], s[10:11], s28, v130, v[98:99]
	s_add_i32 s10, s26, 17
	global_load_dwordx2 a[42:43], v[148:149], off
	s_nop 1
	v_readlane_b32 s28, v100, s10
	s_nop 1
	v_mad_i64_i32 v[148:149], s[10:11], s28, v130, v[96:97]
	global_load_dwordx4 a[24:27], v[148:149], off
	v_mad_i64_i32 v[148:149], s[10:11], s28, v130, v[98:99]
	s_add_i32 s10, s26, 18
	global_load_dwordx2 a[44:45], v[148:149], off
	s_nop 1
	v_readlane_b32 s28, v100, s10
	s_nop 1
	v_mad_i64_i32 v[148:149], s[10:11], s28, v130, v[96:97]
	global_load_dwordx4 a[28:31], v[148:149], off
	v_mad_i64_i32 v[148:149], s[10:11], s28, v130, v[98:99]
	s_add_i32 s10, s26, 19
	global_load_dwordx2 a[46:47], v[148:149], off
	s_nop 1
	v_readlane_b32 s28, v100, s10
	s_nop 1
	v_mad_i64_i32 v[148:149], s[10:11], s28, v130, v[96:97]
	global_load_dwordx4 v[232:235], v[148:149], off
	v_mad_i64_i32 v[148:149], s[10:11], s28, v130, v[98:99]
	s_add_i32 s10, s26, 20
	global_load_dwordx2 a[48:49], v[148:149], off
	s_nop 1
	v_readlane_b32 s28, v100, s10
	s_nop 1
	v_mad_i64_i32 v[148:149], s[10:11], s28, v130, v[96:97]
	global_load_dwordx4 v[236:239], v[148:149], off
	v_mad_i64_i32 v[148:149], s[10:11], s28, v130, v[98:99]
	s_add_i32 s10, s26, 21
	global_load_dwordx2 a[50:51], v[148:149], off
	s_nop 1
	v_readlane_b32 s28, v100, s10
	s_nop 1
	v_mad_i64_i32 v[148:149], s[10:11], s28, v130, v[96:97]
	global_load_dwordx4 v[240:243], v[148:149], off
	v_mad_i64_i32 v[148:149], s[10:11], s28, v130, v[98:99]
	s_add_i32 s10, s26, 22
	global_load_dwordx2 a[52:53], v[148:149], off
	s_nop 1
	v_readlane_b32 s28, v100, s10
	s_nop 1
	v_mad_i64_i32 v[148:149], s[10:11], s28, v130, v[96:97]
	global_load_dwordx4 v[244:247], v[148:149], off
	v_mad_i64_i32 v[148:149], s[10:11], s28, v130, v[98:99]
	s_add_i32 s10, s26, 23
	global_load_dwordx2 a[54:55], v[148:149], off
	s_nop 1
	v_readlane_b32 s28, v100, s10
	s_nop 1
	v_mad_i64_i32 v[148:149], s[10:11], s28, v130, v[96:97]
	global_load_dwordx4 v[248:251], v[148:149], off
	v_mad_i64_i32 v[148:149], s[10:11], s28, v130, v[98:99]
	s_add_i32 s10, s26, 24
	global_load_dwordx2 a[56:57], v[148:149], off
	s_nop 1
	v_readlane_b32 s28, v100, s10
	s_nop 1
	v_mad_i64_i32 v[148:149], s[10:11], s28, v130, v[96:97]
	global_load_dwordx4 a[0:3], v[148:149], off
	v_mad_i64_i32 v[148:149], s[10:11], s28, v130, v[98:99]
	s_add_i32 s10, s26, 25
	global_load_dwordx2 a[58:59], v[148:149], off
	s_nop 1
	v_readlane_b32 s28, v100, s10
	s_nop 1
	v_mad_i64_i32 v[148:149], s[10:11], s28, v130, v[96:97]
	global_load_dwordx4 a[4:7], v[148:149], off
	v_mad_i64_i32 v[148:149], s[10:11], s28, v130, v[98:99]
	s_add_i32 s10, s26, 26
	global_load_dwordx2 a[60:61], v[148:149], off
	s_nop 1
	v_readlane_b32 s28, v100, s10
	s_nop 1
	v_mad_i64_i32 v[148:149], s[10:11], s28, v130, v[96:97]
	global_load_dwordx4 a[8:11], v[148:149], off
	v_mad_i64_i32 v[148:149], s[10:11], s28, v130, v[98:99]
	s_add_i32 s10, s26, 27
	global_load_dwordx2 a[62:63], v[148:149], off
	s_nop 1
	v_readlane_b32 s28, v100, s10
	s_nop 1
	v_mad_i64_i32 v[148:149], s[10:11], s28, v130, v[96:97]
	global_load_dwordx4 a[12:15], v[148:149], off
	v_mad_i64_i32 v[148:149], s[10:11], s28, v130, v[98:99]
	s_add_i32 s10, s26, 28
	global_load_dwordx2 a[64:65], v[148:149], off
	s_nop 1
	v_readlane_b32 s28, v100, s10
	s_nop 1
	v_mad_i64_i32 v[148:149], s[10:11], s28, v130, v[96:97]
	global_load_dwordx4 a[16:19], v[148:149], off
	v_mad_i64_i32 v[148:149], s[10:11], s28, v130, v[98:99]
	s_add_i32 s10, s26, 29
	global_load_dwordx2 a[66:67], v[148:149], off
	s_nop 1
	v_readlane_b32 s28, v100, s10
	s_nop 1
	v_mad_i64_i32 v[148:149], s[10:11], s28, v130, v[96:97]
	global_load_dwordx4 v[220:223], v[148:149], off
	v_mad_i64_i32 v[148:149], s[10:11], s28, v130, v[98:99]
	s_add_i32 s10, s26, 30
	global_load_dwordx2 v[148:149], v[148:149], off
	s_nop 1
	v_readlane_b32 s28, v100, s10
	s_nop 1
	v_mad_i64_i32 v[224:225], s[10:11], s28, v130, v[96:97]
	v_mad_i64_i32 v[228:229], s[10:11], s28, v130, v[98:99]
	s_add_i32 s10, s26, 31
	global_load_dwordx4 v[224:227], v[224:225], off
	s_cmp_lg_u32 s26, 64
	s_nop 0
	v_readlane_b32 s28, v100, s10
	global_load_dwordx2 v[252:253], v[228:229], off
	s_nop 0
	v_mad_i64_i32 v[228:229], s[10:11], s28, v130, v[96:97]
	v_mad_i64_i32 v[100:101], s[10:11], s28, v130, v[98:99]
	global_load_dwordx4 v[228:231], v[228:229], off
	s_nop 0
	global_load_dwordx2 a[40:41], v[100:101], off
	s_cbranch_scc1 .LBB0_904
	v_ashrrev_i32_e32 v119, 31, v118
	v_ashrrev_i32_e32 v121, 31, v120
	v_lshlrev_b64 v[164:165], 2, v[120:121]
	v_lshl_add_u64 v[168:169], s[14:15], 0, v[164:165]
	v_lshl_add_u64 v[164:165], s[12:13], 0, v[164:165]
	v_lshlrev_b64 v[166:167], 2, v[118:119]
	v_lshl_add_u64 v[170:171], s[14:15], 0, v[166:167]
	v_lshl_add_u64 v[166:167], s[12:13], 0, v[166:167]
	global_load_dword a68, v[170:171], off
	global_load_dword a69, v[168:169], off
	global_load_dword v117, v[166:167], off
	global_load_dword v103, v[164:165], off

.LBB0_918:
	s_andn2_saveexec_b64 s[50:51], s[50:51]
	v_mul_f32_e32 v34, v33, v33
	v_fmamk_f32 v35, v34, 0xba1345e1, v139
	v_fmaak_f32 v35, v34, v35, 0xbcdac9b8
	v_fmaak_f32 v35, v34, v35, 0x3de703be
	v_fmaak_f32 v35, v34, v35, 0xbec09330
	v_fmaak_f32 v34, v34, v35, 0x3e0375d0
	v_fma_f32 v34, |v33|, v34, |v33|
	s_or_b64 exec, exec, s[50:51]
	v_cvt_scalef32_pk_f32_fp4 v[36:37], v204, 1.0
	v_pk_fma_f32 v[36:37], s[30:31], v[36:37], v[200:201] op_sel_hi:[0,1,1]
	v_cvt_scalef32_pk_f32_fp4 v[38:39], v204, 1.0 op_sel:[1,0,0]
	v_cvt_scalef32_pk_f32_fp4 v[52:53], v202, 1.0
	v_pk_fma_f32 v[38:39], s[30:31], v[38:39], v[218:219] op_sel_hi:[0,1,1]
	v_cvt_scalef32_pk_f32_fp4 v[40:41], v204, 1.0 op_sel:[0,1,0]
	v_pk_fma_f32 v[36:37], s[28:29], v[52:53], v[36:37] op_sel_hi:[0,1,1]
	v_cvt_scalef32_pk_f32_fp4 v[52:53], v202, 1.0 op_sel:[1,0,0]
	v_pk_fma_f32 v[40:41], s[30:31], v[40:41], v[216:217] op_sel_hi:[0,1,1]
	v_cvt_scalef32_pk_f32_fp4 v[42:43], v204, 1.0 op_sel:[1,1,0]
	v_pk_fma_f32 v[38:39], s[28:29], v[52:53], v[38:39] op_sel_hi:[0,1,1]
	v_cvt_scalef32_pk_f32_fp4 v[52:53], v202, 1.0 op_sel:[0,1,0]
	v_pk_fma_f32 v[42:43], s[30:31], v[42:43], v[214:215] op_sel_hi:[0,1,1]
	v_cvt_scalef32_pk_f32_fp4 v[44:45], v205, 1.0
	v_pk_fma_f32 v[40:41], s[28:29], v[52:53], v[40:41] op_sel_hi:[0,1,1]
	v_cvt_scalef32_pk_f32_fp4 v[52:53], v202, 1.0 op_sel:[1,1,0]
	v_pk_fma_f32 v[44:45], s[30:31], v[44:45], v[212:213] op_sel_hi:[0,1,1]
	v_cvt_scalef32_pk_f32_fp4 v[46:47], v205, 1.0 op_sel:[1,0,0]
	v_pk_fma_f32 v[42:43], s[28:29], v[52:53], v[42:43] op_sel_hi:[0,1,1]
	v_cvt_scalef32_pk_f32_fp4 v[52:53], v203, 1.0
	v_pk_fma_f32 v[46:47], s[30:31], v[46:47], v[210:211] op_sel_hi:[0,1,1]
	v_cvt_scalef32_pk_f32_fp4 v[48:49], v205, 1.0 op_sel:[0,1,0]
	v_pk_fma_f32 v[44:45], s[28:29], v[52:53], v[44:45] op_sel_hi:[0,1,1]
	v_cvt_scalef32_pk_f32_fp4 v[52:53], v203, 1.0 op_sel:[1,0,0]
	v_pk_fma_f32 v[48:49], s[30:31], v[48:49], v[208:209] op_sel_hi:[0,1,1]
	v_cvt_scalef32_pk_f32_fp4 v[50:51], v205, 1.0 op_sel:[1,1,0]
	v_pk_fma_f32 v[46:47], s[28:29], v[52:53], v[46:47] op_sel_hi:[0,1,1]
	v_cvt_scalef32_pk_f32_fp4 v[52:53], v203, 1.0 op_sel:[0,1,0]
	v_pk_fma_f32 v[50:51], s[30:31], v[50:51], v[206:207] op_sel_hi:[0,1,1]
	v_pk_fma_f32 v[48:49], s[28:29], v[52:53], v[48:49] op_sel_hi:[0,1,1]
	v_cvt_scalef32_pk_f32_fp4 v[52:53], v203, 1.0 op_sel:[1,1,0]
	v_pk_fma_f32 v[50:51], s[28:29], v[52:53], v[50:51] op_sel_hi:[0,1,1]
	v_cvt_scalef32_pk_f32_fp4 v[52:53], v198, 1.0
	v_pk_fma_f32 v[36:37], s[26:27], v[52:53], v[36:37] op_sel_hi:[0,1,1]
	v_cvt_scalef32_pk_f32_fp4 v[52:53], v198, 1.0 op_sel:[1,0,0]
	v_pk_fma_f32 v[38:39], s[26:27], v[52:53], v[38:39] op_sel_hi:[0,1,1]
	v_cvt_scalef32_pk_f32_fp4 v[52:53], v198, 1.0 op_sel:[0,1,0]
	v_pk_fma_f32 v[40:41], s[26:27], v[52:53], v[40:41] op_sel_hi:[0,1,1]
	v_cvt_scalef32_pk_f32_fp4 v[52:53], v198, 1.0 op_sel:[1,1,0]
	v_pk_fma_f32 v[42:43], s[26:27], v[52:53], v[42:43] op_sel_hi:[0,1,1]
	v_cvt_scalef32_pk_f32_fp4 v[52:53], v199, 1.0
	v_pk_fma_f32 v[44:45], s[26:27], v[52:53], v[44:45] op_sel_hi:[0,1,1]
	v_cvt_scalef32_pk_f32_fp4 v[52:53], v199, 1.0 op_sel:[1,0,0]
	v_pk_fma_f32 v[46:47], s[26:27], v[52:53], v[46:47] op_sel_hi:[0,1,1]
	v_cvt_scalef32_pk_f32_fp4 v[52:53], v199, 1.0 op_sel:[0,1,0]
	v_pk_fma_f32 v[48:49], s[26:27], v[52:53], v[48:49] op_sel_hi:[0,1,1]
	v_cvt_scalef32_pk_f32_fp4 v[52:53], v199, 1.0 op_sel:[1,1,0]
	v_pk_fma_f32 v[50:51], s[26:27], v[52:53], v[50:51] op_sel_hi:[0,1,1]
	v_cvt_scalef32_pk_f32_fp4 v[52:53], v196, 1.0
	v_pk_fma_f32 v[36:37], s[10:11], v[52:53], v[36:37] op_sel_hi:[0,1,1]
	v_cvt_scalef32_pk_f32_fp4 v[52:53], v196, 1.0 op_sel:[1,0,0]
	v_pk_fma_f32 v[38:39], s[10:11], v[52:53], v[38:39] op_sel_hi:[0,1,1]
	v_cvt_scalef32_pk_f32_fp4 v[52:53], v196, 1.0 op_sel:[0,1,0]
	v_pk_fma_f32 v[40:41], s[10:11], v[52:53], v[40:41] op_sel_hi:[0,1,1]
	v_cvt_scalef32_pk_f32_fp4 v[52:53], v196, 1.0 op_sel:[1,1,0]
	v_pk_fma_f32 v[42:43], s[10:11], v[52:53], v[42:43] op_sel_hi:[0,1,1]
	v_cvt_scalef32_pk_f32_fp4 v[52:53], v197, 1.0
	v_pk_fma_f32 v[44:45], s[10:11], v[52:53], v[44:45] op_sel_hi:[0,1,1]
	v_cvt_scalef32_pk_f32_fp4 v[52:53], v197, 1.0 op_sel:[1,0,0]
	v_pk_fma_f32 v[46:47], s[10:11], v[52:53], v[46:47] op_sel_hi:[0,1,1]
	v_cvt_scalef32_pk_f32_fp4 v[52:53], v197, 1.0 op_sel:[0,1,0]
	v_pk_fma_f32 v[48:49], s[10:11], v[52:53], v[48:49] op_sel_hi:[0,1,1]
	v_cvt_scalef32_pk_f32_fp4 v[52:53], v197, 1.0 op_sel:[1,1,0]
	v_pk_fma_f32 v[50:51], s[10:11], v[52:53], v[50:51] op_sel_hi:[0,1,1]
	v_cvt_scalef32_pk_f32_fp4 v[52:53], v194, 1.0
	v_pk_fma_f32 v[36:37], s[40:41], v[52:53], v[36:37] op_sel_hi:[0,1,1]
	v_cvt_scalef32_pk_f32_fp4 v[52:53], v194, 1.0 op_sel:[1,0,0]
	v_pk_fma_f32 v[38:39], s[40:41], v[52:53], v[38:39] op_sel_hi:[0,1,1]
	v_cvt_scalef32_pk_f32_fp4 v[52:53], v194, 1.0 op_sel:[0,1,0]
	v_pk_fma_f32 v[40:41], s[40:41], v[52:53], v[40:41] op_sel_hi:[0,1,1]
	v_cvt_scalef32_pk_f32_fp4 v[52:53], v194, 1.0 op_sel:[1,1,0]
	v_pk_fma_f32 v[42:43], s[40:41], v[52:53], v[42:43] op_sel_hi:[0,1,1]
	v_cvt_scalef32_pk_f32_fp4 v[52:53], v195, 1.0
	v_pk_fma_f32 v[44:45], s[40:41], v[52:53], v[44:45] op_sel_hi:[0,1,1]
	v_cvt_scalef32_pk_f32_fp4 v[52:53], v195, 1.0 op_sel:[1,0,0]
	v_pk_fma_f32 v[46:47], s[40:41], v[52:53], v[46:47] op_sel_hi:[0,1,1]
	v_cvt_scalef32_pk_f32_fp4 v[52:53], v195, 1.0 op_sel:[0,1,0]
	v_pk_fma_f32 v[48:49], s[40:41], v[52:53], v[48:49] op_sel_hi:[0,1,1]
	v_cvt_scalef32_pk_f32_fp4 v[52:53], v195, 1.0 op_sel:[1,1,0]
	v_pk_fma_f32 v[50:51], s[40:41], v[52:53], v[50:51] op_sel_hi:[0,1,1]
	v_cvt_scalef32_pk_f32_fp4 v[52:53], v192, 1.0
	v_pk_fma_f32 v[36:37], s[38:39], v[52:53], v[36:37] op_sel_hi:[0,1,1]
	v_cvt_scalef32_pk_f32_fp4 v[52:53], v192, 1.0 op_sel:[1,0,0]
	v_pk_fma_f32 v[38:39], s[38:39], v[52:53], v[38:39] op_sel_hi:[0,1,1]
	v_cvt_scalef32_pk_f32_fp4 v[52:53], v192, 1.0 op_sel:[0,1,0]
	v_pk_fma_f32 v[40:41], s[38:39], v[52:53], v[40:41] op_sel_hi:[0,1,1]
	v_cvt_scalef32_pk_f32_fp4 v[52:53], v192, 1.0 op_sel:[1,1,0]
	v_pk_fma_f32 v[42:43], s[38:39], v[52:53], v[42:43] op_sel_hi:[0,1,1]
	v_cvt_scalef32_pk_f32_fp4 v[52:53], v193, 1.0
	v_pk_fma_f32 v[44:45], s[38:39], v[52:53], v[44:45] op_sel_hi:[0,1,1]
	v_cvt_scalef32_pk_f32_fp4 v[52:53], v193, 1.0 op_sel:[1,0,0]
	v_pk_fma_f32 v[46:47], s[38:39], v[52:53], v[46:47] op_sel_hi:[0,1,1]
	v_cvt_scalef32_pk_f32_fp4 v[52:53], v193, 1.0 op_sel:[0,1,0]
	v_pk_fma_f32 v[48:49], s[38:39], v[52:53], v[48:49] op_sel_hi:[0,1,1]
	v_cvt_scalef32_pk_f32_fp4 v[52:53], v193, 1.0 op_sel:[1,1,0]
	v_pk_fma_f32 v[50:51], s[38:39], v[52:53], v[50:51] op_sel_hi:[0,1,1]
	v_cvt_scalef32_pk_f32_fp4 v[52:53], v190, 1.0
	v_pk_fma_f32 v[36:37], s[36:37], v[52:53], v[36:37] op_sel_hi:[0,1,1]
	v_cvt_scalef32_pk_f32_fp4 v[52:53], v190, 1.0 op_sel:[1,0,0]
	v_pk_fma_f32 v[38:39], s[36:37], v[52:53], v[38:39] op_sel_hi:[0,1,1]
	v_cvt_scalef32_pk_f32_fp4 v[52:53], v190, 1.0 op_sel:[0,1,0]
	v_pk_fma_f32 v[40:41], s[36:37], v[52:53], v[40:41] op_sel_hi:[0,1,1]
	v_cvt_scalef32_pk_f32_fp4 v[52:53], v190, 1.0 op_sel:[1,1,0]
	v_pk_fma_f32 v[42:43], s[36:37], v[52:53], v[42:43] op_sel_hi:[0,1,1]
	v_cvt_scalef32_pk_f32_fp4 v[52:53], v191, 1.0
	v_pk_fma_f32 v[44:45], s[36:37], v[52:53], v[44:45] op_sel_hi:[0,1,1]
	v_cvt_scalef32_pk_f32_fp4 v[52:53], v191, 1.0 op_sel:[1,0,0]
	v_pk_fma_f32 v[46:47], s[36:37], v[52:53], v[46:47] op_sel_hi:[0,1,1]
	v_cvt_scalef32_pk_f32_fp4 v[52:53], v191, 1.0 op_sel:[0,1,0]
	v_pk_fma_f32 v[48:49], s[36:37], v[52:53], v[48:49] op_sel_hi:[0,1,1]
	v_cvt_scalef32_pk_f32_fp4 v[52:53], v191, 1.0 op_sel:[1,1,0]
	v_pk_fma_f32 v[50:51], s[36:37], v[52:53], v[50:51] op_sel_hi:[0,1,1]
	v_cvt_scalef32_pk_f32_fp4 v[52:53], v188, 1.0
	v_pk_fma_f32 v[36:37], s[34:35], v[52:53], v[36:37] op_sel_hi:[0,1,1]
	v_cvt_scalef32_pk_f32_fp4 v[52:53], v188, 1.0 op_sel:[1,0,0]
	v_pk_fma_f32 v[38:39], s[34:35], v[52:53], v[38:39] op_sel_hi:[0,1,1]
	v_cvt_scalef32_pk_f32_fp4 v[52:53], v188, 1.0 op_sel:[0,1,0]
	v_pk_fma_f32 v[40:41], s[34:35], v[52:53], v[40:41] op_sel_hi:[0,1,1]
	v_cvt_scalef32_pk_f32_fp4 v[52:53], v188, 1.0 op_sel:[1,1,0]
	v_pk_fma_f32 v[42:43], s[34:35], v[52:53], v[42:43] op_sel_hi:[0,1,1]
	v_cvt_scalef32_pk_f32_fp4 v[52:53], v189, 1.0
	v_pk_fma_f32 v[44:45], s[34:35], v[52:53], v[44:45] op_sel_hi:[0,1,1]
	v_cvt_scalef32_pk_f32_fp4 v[52:53], v189, 1.0 op_sel:[1,0,0]
	v_pk_fma_f32 v[46:47], s[34:35], v[52:53], v[46:47] op_sel_hi:[0,1,1]
	v_cvt_scalef32_pk_f32_fp4 v[52:53], v189, 1.0 op_sel:[0,1,0]
	v_pk_fma_f32 v[48:49], s[34:35], v[52:53], v[48:49] op_sel_hi:[0,1,1]
	v_cvt_scalef32_pk_f32_fp4 v[52:53], v189, 1.0 op_sel:[1,1,0]
	v_pk_fma_f32 v[50:51], s[34:35], v[52:53], v[50:51] op_sel_hi:[0,1,1]
	v_cvt_scalef32_pk_f32_fp4 v[52:53], v186, 1.0
	v_pk_fma_f32 v[36:37], s[48:49], v[52:53], v[36:37] op_sel_hi:[0,1,1]
	v_cvt_scalef32_pk_f32_fp4 v[52:53], v186, 1.0 op_sel:[1,0,0]
	v_pk_fma_f32 v[38:39], s[48:49], v[52:53], v[38:39] op_sel_hi:[0,1,1]
	v_cvt_scalef32_pk_f32_fp4 v[52:53], v186, 1.0 op_sel:[0,1,0]
	v_pk_fma_f32 v[40:41], s[48:49], v[52:53], v[40:41] op_sel_hi:[0,1,1]
	v_cvt_scalef32_pk_f32_fp4 v[52:53], v186, 1.0 op_sel:[1,1,0]
	v_pk_fma_f32 v[42:43], s[48:49], v[52:53], v[42:43] op_sel_hi:[0,1,1]
	v_cvt_scalef32_pk_f32_fp4 v[52:53], v187, 1.0
	v_pk_fma_f32 v[44:45], s[48:49], v[52:53], v[44:45] op_sel_hi:[0,1,1]
	v_cvt_scalef32_pk_f32_fp4 v[52:53], v187, 1.0 op_sel:[1,0,0]
	v_pk_fma_f32 v[46:47], s[48:49], v[52:53], v[46:47] op_sel_hi:[0,1,1]
	v_cvt_scalef32_pk_f32_fp4 v[52:53], v187, 1.0 op_sel:[0,1,0]
	v_pk_fma_f32 v[48:49], s[48:49], v[52:53], v[48:49] op_sel_hi:[0,1,1]
	v_cvt_scalef32_pk_f32_fp4 v[52:53], v187, 1.0 op_sel:[1,1,0]
	v_pk_fma_f32 v[50:51], s[48:49], v[52:53], v[50:51] op_sel_hi:[0,1,1]
	v_cvt_scalef32_pk_f32_fp4 v[52:53], v184, 1.0
	v_pk_fma_f32 v[36:37], s[46:47], v[52:53], v[36:37] op_sel_hi:[0,1,1]
	v_cvt_scalef32_pk_f32_fp4 v[52:53], v184, 1.0 op_sel:[1,0,0]
	v_pk_fma_f32 v[38:39], s[46:47], v[52:53], v[38:39] op_sel_hi:[0,1,1]
	v_cvt_scalef32_pk_f32_fp4 v[52:53], v184, 1.0 op_sel:[0,1,0]
	v_pk_fma_f32 v[40:41], s[46:47], v[52:53], v[40:41] op_sel_hi:[0,1,1]
	v_cvt_scalef32_pk_f32_fp4 v[52:53], v184, 1.0 op_sel:[1,1,0]
	v_pk_fma_f32 v[42:43], s[46:47], v[52:53], v[42:43] op_sel_hi:[0,1,1]
	v_cvt_scalef32_pk_f32_fp4 v[52:53], v185, 1.0
	v_pk_fma_f32 v[44:45], s[46:47], v[52:53], v[44:45] op_sel_hi:[0,1,1]
	v_cvt_scalef32_pk_f32_fp4 v[52:53], v185, 1.0 op_sel:[1,0,0]
	v_pk_fma_f32 v[46:47], s[46:47], v[52:53], v[46:47] op_sel_hi:[0,1,1]
	v_cvt_scalef32_pk_f32_fp4 v[52:53], v185, 1.0 op_sel:[0,1,0]
	v_pk_fma_f32 v[48:49], s[46:47], v[52:53], v[48:49] op_sel_hi:[0,1,1]
	v_cvt_scalef32_pk_f32_fp4 v[52:53], v185, 1.0 op_sel:[1,1,0]
	v_pk_fma_f32 v[50:51], s[46:47], v[52:53], v[50:51] op_sel_hi:[0,1,1]
	v_cvt_scalef32_pk_f32_fp4 v[52:53], v182, 1.0
	v_pk_fma_f32 v[36:37], s[44:45], v[52:53], v[36:37] op_sel_hi:[0,1,1]
	v_cvt_scalef32_pk_f32_fp4 v[52:53], v182, 1.0 op_sel:[1,0,0]
	v_pk_fma_f32 v[38:39], s[44:45], v[52:53], v[38:39] op_sel_hi:[0,1,1]
	v_cvt_scalef32_pk_f32_fp4 v[52:53], v182, 1.0 op_sel:[0,1,0]
	v_pk_fma_f32 v[40:41], s[44:45], v[52:53], v[40:41] op_sel_hi:[0,1,1]
	v_cvt_scalef32_pk_f32_fp4 v[52:53], v182, 1.0 op_sel:[1,1,0]
	v_pk_fma_f32 v[42:43], s[44:45], v[52:53], v[42:43] op_sel_hi:[0,1,1]
	v_cvt_scalef32_pk_f32_fp4 v[52:53], v183, 1.0
	v_pk_fma_f32 v[44:45], s[44:45], v[52:53], v[44:45] op_sel_hi:[0,1,1]
	v_cvt_scalef32_pk_f32_fp4 v[52:53], v183, 1.0 op_sel:[1,0,0]
	v_pk_fma_f32 v[46:47], s[44:45], v[52:53], v[46:47] op_sel_hi:[0,1,1]
	v_cvt_scalef32_pk_f32_fp4 v[52:53], v183, 1.0 op_sel:[0,1,0]
	v_pk_fma_f32 v[48:49], s[44:45], v[52:53], v[48:49] op_sel_hi:[0,1,1]
	v_cvt_scalef32_pk_f32_fp4 v[52:53], v183, 1.0 op_sel:[1,1,0]
	v_pk_fma_f32 v[50:51], s[44:45], v[52:53], v[50:51] op_sel_hi:[0,1,1]
	v_cvt_scalef32_pk_f32_fp4 v[52:53], v180, 1.0
	v_pk_fma_f32 v[36:37], s[42:43], v[52:53], v[36:37] op_sel_hi:[0,1,1]
	v_cvt_scalef32_pk_f32_fp4 v[52:53], v180, 1.0 op_sel:[1,0,0]
	v_pk_fma_f32 v[38:39], s[42:43], v[52:53], v[38:39] op_sel_hi:[0,1,1]
	v_cvt_scalef32_pk_f32_fp4 v[52:53], v180, 1.0 op_sel:[0,1,0]
	v_pk_fma_f32 v[40:41], s[42:43], v[52:53], v[40:41] op_sel_hi:[0,1,1]
	v_cvt_scalef32_pk_f32_fp4 v[52:53], v180, 1.0 op_sel:[1,1,0]
	v_pk_fma_f32 v[42:43], s[42:43], v[52:53], v[42:43] op_sel_hi:[0,1,1]
	v_cvt_scalef32_pk_f32_fp4 v[52:53], v181, 1.0
	v_pk_fma_f32 v[44:45], s[42:43], v[52:53], v[44:45] op_sel_hi:[0,1,1]
	v_cvt_scalef32_pk_f32_fp4 v[52:53], v181, 1.0 op_sel:[1,0,0]
	v_pk_fma_f32 v[46:47], s[42:43], v[52:53], v[46:47] op_sel_hi:[0,1,1]
	v_cvt_scalef32_pk_f32_fp4 v[52:53], v181, 1.0 op_sel:[0,1,0]
	v_pk_fma_f32 v[48:49], s[42:43], v[52:53], v[48:49] op_sel_hi:[0,1,1]
	v_cvt_scalef32_pk_f32_fp4 v[52:53], v181, 1.0 op_sel:[1,1,0]
	v_pk_fma_f32 v[50:51], s[42:43], v[52:53], v[50:51] op_sel_hi:[0,1,1]
	v_mov_b32_e32 v35, s59
	v_mov_b32_e32 v52, s35
	v_cndmask_b32_e64 v35, v35, v52, s[8:9]
	v_mov_b32_e32 v52, s43
	v_bfi_b32 v33, s55, v34, v33
	v_cndmask_b32_e64 v35, v35, v52, s[6:7]
	v_mov_b32_e32 v52, s11
	v_mul_f32_e32 v32, 0.5, v32
	v_add_f32_e32 v33, 1.0, v33
	v_cndmask_b32_e64 v35, v35, v52, s[4:5]
	v_mul_f32_e32 v32, v32, v33
	v_mul_f32_e32 v32, v35, v32
	v_cvt_scalef32_pk_f32_fp4 v[34:35], v178, 1.0 op_sel:[1,0,0]
	v_readlane_b32 s10, v32, 0
	v_readlane_b32 s26, v32, 32
	v_readlane_b32 s28, v32, 16
	v_readlane_b32 s30, v32, 48
	v_cvt_scalef32_pk_f32_fp4 v[32:33], v178, 1.0
	v_pk_fma_f32 v[32:33], s[10:11], v[32:33], v[36:37] op_sel_hi:[0,1,1]
	v_cvt_scalef32_pk_f32_fp4 v[36:37], v178, 1.0 op_sel:[0,1,0]
	v_pk_fma_f32 v[36:37], s[10:11], v[36:37], v[40:41] op_sel_hi:[0,1,1]
	v_cvt_scalef32_pk_f32_fp4 v[40:41], v179, 1.0
	v_pk_fma_f32 v[40:41], s[10:11], v[40:41], v[44:45] op_sel_hi:[0,1,1]
	v_cvt_scalef32_pk_f32_fp4 v[44:45], v179, 1.0 op_sel:[0,1,0]
	v_pk_fma_f32 v[44:45], s[10:11], v[44:45], v[48:49] op_sel_hi:[0,1,1]
	v_cvt_scalef32_pk_f32_fp4 v[48:49], v176, 1.0
	v_pk_fma_f32 v[34:35], s[10:11], v[34:35], v[38:39] op_sel_hi:[0,1,1]
	v_pk_fma_f32 v[32:33], s[26:27], v[48:49], v[32:33] op_sel_hi:[0,1,1]
	v_cvt_scalef32_pk_f32_fp4 v[48:49], v176, 1.0 op_sel:[1,0,0]
	v_cvt_scalef32_pk_f32_fp4 v[38:39], v178, 1.0 op_sel:[1,1,0]
	v_pk_fma_f32 v[34:35], s[26:27], v[48:49], v[34:35] op_sel_hi:[0,1,1]
	v_cvt_scalef32_pk_f32_fp4 v[48:49], v176, 1.0 op_sel:[0,1,0]
	v_pk_fma_f32 v[38:39], s[10:11], v[38:39], v[42:43] op_sel_hi:[0,1,1]
	v_pk_fma_f32 v[36:37], s[26:27], v[48:49], v[36:37] op_sel_hi:[0,1,1]
	v_cvt_scalef32_pk_f32_fp4 v[48:49], v176, 1.0 op_sel:[1,1,0]
	v_cvt_scalef32_pk_f32_fp4 v[42:43], v179, 1.0 op_sel:[1,0,0]
	v_pk_fma_f32 v[38:39], s[26:27], v[48:49], v[38:39] op_sel_hi:[0,1,1]
	v_cvt_scalef32_pk_f32_fp4 v[48:49], v177, 1.0
	v_pk_fma_f32 v[42:43], s[10:11], v[42:43], v[46:47] op_sel_hi:[0,1,1]
	v_pk_fma_f32 v[40:41], s[26:27], v[48:49], v[40:41] op_sel_hi:[0,1,1]
	v_cvt_scalef32_pk_f32_fp4 v[48:49], v177, 1.0 op_sel:[1,0,0]
	v_cvt_scalef32_pk_f32_fp4 v[46:47], v179, 1.0 op_sel:[1,1,0]
	v_pk_fma_f32 v[42:43], s[26:27], v[48:49], v[42:43] op_sel_hi:[0,1,1]
	v_cvt_scalef32_pk_f32_fp4 v[48:49], v177, 1.0 op_sel:[0,1,0]
	v_pk_fma_f32 v[46:47], s[10:11], v[46:47], v[50:51] op_sel_hi:[0,1,1]
	v_pk_fma_f32 v[44:45], s[26:27], v[48:49], v[44:45] op_sel_hi:[0,1,1]
	v_cvt_scalef32_pk_f32_fp4 v[48:49], v177, 1.0 op_sel:[1,1,0]
	v_pk_fma_f32 v[46:47], s[26:27], v[48:49], v[46:47] op_sel_hi:[0,1,1]
	v_cvt_scalef32_pk_f32_fp4 v[48:49], v174, 1.0
	v_pk_fma_f32 v[32:33], s[28:29], v[48:49], v[32:33] op_sel_hi:[0,1,1]
	v_cvt_scalef32_pk_f32_fp4 v[48:49], v174, 1.0 op_sel:[1,0,0]
	v_pk_fma_f32 v[34:35], s[28:29], v[48:49], v[34:35] op_sel_hi:[0,1,1]
	v_cvt_scalef32_pk_f32_fp4 v[48:49], v174, 1.0 op_sel:[0,1,0]
	v_pk_fma_f32 v[36:37], s[28:29], v[48:49], v[36:37] op_sel_hi:[0,1,1]
	v_cvt_scalef32_pk_f32_fp4 v[48:49], v174, 1.0 op_sel:[1,1,0]
	v_pk_fma_f32 v[38:39], s[28:29], v[48:49], v[38:39] op_sel_hi:[0,1,1]
	v_cvt_scalef32_pk_f32_fp4 v[48:49], v175, 1.0
	v_pk_fma_f32 v[40:41], s[28:29], v[48:49], v[40:41] op_sel_hi:[0,1,1]
	v_cvt_scalef32_pk_f32_fp4 v[48:49], v175, 1.0 op_sel:[1,0,0]
	v_pk_fma_f32 v[42:43], s[28:29], v[48:49], v[42:43] op_sel_hi:[0,1,1]
	v_cvt_scalef32_pk_f32_fp4 v[48:49], v175, 1.0 op_sel:[0,1,0]
	v_pk_fma_f32 v[44:45], s[28:29], v[48:49], v[44:45] op_sel_hi:[0,1,1]
	v_cvt_scalef32_pk_f32_fp4 v[48:49], v175, 1.0 op_sel:[1,1,0]
	v_pk_fma_f32 v[46:47], s[28:29], v[48:49], v[46:47] op_sel_hi:[0,1,1]
	v_cvt_scalef32_pk_f32_fp4 v[48:49], v172, 1.0
	v_pk_fma_f32 v[200:201], s[30:31], v[48:49], v[32:33] op_sel_hi:[0,1,1]
	v_cvt_scalef32_pk_f32_fp4 v[32:33], v172, 1.0 op_sel:[1,0,0]
	v_pk_fma_f32 v[218:219], s[30:31], v[32:33], v[34:35] op_sel_hi:[0,1,1]
	v_cvt_scalef32_pk_f32_fp4 v[32:33], v172, 1.0 op_sel:[0,1,0]
	v_pk_fma_f32 v[216:217], s[30:31], v[32:33], v[36:37] op_sel_hi:[0,1,1]
	v_cvt_scalef32_pk_f32_fp4 v[32:33], v172, 1.0 op_sel:[1,1,0]
	v_pk_fma_f32 v[214:215], s[30:31], v[32:33], v[38:39] op_sel_hi:[0,1,1]
	v_cvt_scalef32_pk_f32_fp4 v[32:33], v173, 1.0
	v_pk_fma_f32 v[212:213], s[30:31], v[32:33], v[40:41] op_sel_hi:[0,1,1]
	v_cvt_scalef32_pk_f32_fp4 v[32:33], v173, 1.0 op_sel:[1,0,0]
	v_pk_fma_f32 v[210:211], s[30:31], v[32:33], v[42:43] op_sel_hi:[0,1,1]
	v_cvt_scalef32_pk_f32_fp4 v[32:33], v173, 1.0 op_sel:[0,1,0]
	v_pk_fma_f32 v[208:209], s[30:31], v[32:33], v[44:45] op_sel_hi:[0,1,1]
	v_cvt_scalef32_pk_f32_fp4 v[32:33], v173, 1.0 op_sel:[1,1,0]
	v_pk_fma_f32 v[206:207], s[30:31], v[32:33], v[46:47] op_sel_hi:[0,1,1]
	s_and_b64 vcc, exec, s[24:25]
	s_cbranch_vccnz .LBB0_900
	s_mov_b32 s26, s58
	s_add_i32 s58, s26, 16
	s_cmpk_gt_u32 s26, 0x6f
	s_cselect_b64 s[24:25], -1, 0
	s_cmpk_lt_u32 s26, 0x70
	s_cselect_b64 vcc, -1, 0
	s_bitcmp0_b32 s58, 6
	s_cselect_b64 s[10:11], -1, 0
	v_cndmask_b32_e64 v100, v116, v102, s[10:11]
	v_cndmask_b32_e32 v100, v118, v100, vcc
	s_nop 0
	s_waitcnt vmcnt(24)
	v_accvgpr_read_b32 v205, a43
	v_accvgpr_read_b32 v203, a45
	v_accvgpr_read_b32 v199, a47
	v_accvgpr_read_b32 v197, a49
	v_accvgpr_read_b32 v95, a23
	v_accvgpr_read_b32 v91, a27
	v_accvgpr_read_b32 v87, a31
	v_mov_b64_e32 v[80:81], v[232:233]
	v_accvgpr_read_b32 v204, a42
	v_accvgpr_read_b32 v202, a44
	v_accvgpr_read_b32 v198, a46
	v_accvgpr_read_b32 v196, a48
	v_accvgpr_read_b32 v94, a22
	v_accvgpr_read_b32 v93, a21
	v_accvgpr_read_b32 v92, a20
	v_accvgpr_read_b32 v90, a26
	v_accvgpr_read_b32 v89, a25
	v_accvgpr_read_b32 v88, a24
	v_accvgpr_read_b32 v86, a30
	v_accvgpr_read_b32 v85, a29
	v_accvgpr_read_b32 v84, a28
	v_mov_b64_e32 v[82:83], v[234:235]
	s_add_i32 s30, s26, 16
	v_readlane_b32 s28, v100, s30
	s_nop 1
	v_mad_i64_i32 v[136:137], s[10:11], s28, v130, v[96:97]
	global_load_dwordx4 a[20:23], v[136:137], off
	v_mad_i64_i32 v[136:137], s[10:11], s28, v130, v[98:99]
	global_load_dwordx2 a[42:43], v[136:137], off
	s_add_i32 s30, s26, 17
	v_readlane_b32 s28, v100, s30
	s_nop 1
	v_mad_i64_i32 v[136:137], s[10:11], s28, v130, v[96:97]
	global_load_dwordx4 a[24:27], v[136:137], off
	v_mad_i64_i32 v[136:137], s[10:11], s28, v130, v[98:99]
	global_load_dwordx2 a[44:45], v[136:137], off
	s_add_i32 s30, s26, 18
	v_readlane_b32 s28, v100, s30
	s_nop 1
	v_mad_i64_i32 v[136:137], s[10:11], s28, v130, v[96:97]
	global_load_dwordx4 a[28:31], v[136:137], off
	v_mad_i64_i32 v[136:137], s[10:11], s28, v130, v[98:99]
	global_load_dwordx2 a[46:47], v[136:137], off
	s_add_i32 s30, s26, 19
	v_readlane_b32 s28, v100, s30
	s_nop 1
	v_mad_i64_i32 v[136:137], s[10:11], s28, v130, v[96:97]
	global_load_dwordx4 v[232:235], v[136:137], off
	v_mad_i64_i32 v[136:137], s[10:11], s28, v130, v[98:99]
	global_load_dwordx2 a[48:49], v[136:137], off
	s_waitcnt vmcnt(24)
	v_accvgpr_read_b32 v195, a51
	v_accvgpr_read_b32 v193, a53
	v_accvgpr_read_b32 v191, a55
	v_accvgpr_read_b32 v189, a57
	v_mov_b64_e32 v[76:77], v[236:237]
	v_mov_b64_e32 v[72:73], v[240:241]
	v_mov_b64_e32 v[68:69], v[244:245]
	v_mov_b64_e32 v[64:65], v[248:249]
	v_accvgpr_read_b32 v194, a50
	v_accvgpr_read_b32 v192, a52
	v_accvgpr_read_b32 v190, a54
	v_accvgpr_read_b32 v188, a56
	v_mov_b64_e32 v[78:79], v[238:239]
	v_mov_b64_e32 v[74:75], v[242:243]
	v_mov_b64_e32 v[70:71], v[246:247]
	v_mov_b64_e32 v[66:67], v[250:251]
	s_add_i32 s30, s26, 20
	v_readlane_b32 s28, v100, s30
	s_nop 1
	v_mad_i64_i32 v[136:137], s[10:11], s28, v130, v[96:97]
	global_load_dwordx4 v[236:239], v[136:137], off
	v_mad_i64_i32 v[136:137], s[10:11], s28, v130, v[98:99]
	global_load_dwordx2 a[50:51], v[136:137], off
	s_add_i32 s30, s26, 21
	v_readlane_b32 s28, v100, s30
	s_nop 1
	v_mad_i64_i32 v[136:137], s[10:11], s28, v130, v[96:97]
	global_load_dwordx4 v[240:243], v[136:137], off
	v_mad_i64_i32 v[136:137], s[10:11], s28, v130, v[98:99]
	global_load_dwordx2 a[52:53], v[136:137], off
	s_add_i32 s30, s26, 22
	v_readlane_b32 s28, v100, s30
	s_nop 1
	v_mad_i64_i32 v[136:137], s[10:11], s28, v130, v[96:97]
	global_load_dwordx4 v[244:247], v[136:137], off
	v_mad_i64_i32 v[136:137], s[10:11], s28, v130, v[98:99]
	global_load_dwordx2 a[54:55], v[136:137], off
	s_add_i32 s30, s26, 23
	v_readlane_b32 s28, v100, s30
	s_nop 1
	v_mad_i64_i32 v[136:137], s[10:11], s28, v130, v[96:97]
	global_load_dwordx4 v[248:251], v[136:137], off
	v_mad_i64_i32 v[136:137], s[10:11], s28, v130, v[98:99]
	global_load_dwordx2 a[56:57], v[136:137], off
	s_waitcnt vmcnt(24)
	v_accvgpr_read_b32 v187, a59
	v_accvgpr_read_b32 v185, a61
	v_accvgpr_read_b32 v183, a63
	v_accvgpr_read_b32 v181, a65
	v_accvgpr_read_b32 v63, a3
	v_accvgpr_read_b32 v59, a7
	v_accvgpr_read_b32 v55, a11
	v_accvgpr_read_b32 v51, a15
	v_accvgpr_read_b32 v186, a58
	v_accvgpr_read_b32 v184, a60
	v_accvgpr_read_b32 v182, a62
	v_accvgpr_read_b32 v180, a64
	v_accvgpr_read_b32 v62, a2
	v_accvgpr_read_b32 v61, a1
	v_accvgpr_read_b32 v60, a0
	v_accvgpr_read_b32 v58, a6
	v_accvgpr_read_b32 v57, a5
	v_accvgpr_read_b32 v56, a4
	v_accvgpr_read_b32 v54, a10
	v_accvgpr_read_b32 v53, a9
	v_accvgpr_read_b32 v52, a8
	v_accvgpr_read_b32 v50, a14
	v_accvgpr_read_b32 v49, a13
	v_accvgpr_read_b32 v48, a12
	s_add_i32 s30, s26, 24
	v_readlane_b32 s28, v100, s30
	s_nop 1
	v_mad_i64_i32 v[136:137], s[10:11], s28, v130, v[96:97]
	global_load_dwordx4 a[0:3], v[136:137], off
	v_mad_i64_i32 v[136:137], s[10:11], s28, v130, v[98:99]
	global_load_dwordx2 a[58:59], v[136:137], off
	s_add_i32 s30, s26, 25
	v_readlane_b32 s28, v100, s30
	s_nop 1
	v_mad_i64_i32 v[136:137], s[10:11], s28, v130, v[96:97]
	global_load_dwordx4 a[4:7], v[136:137], off
	v_mad_i64_i32 v[136:137], s[10:11], s28, v130, v[98:99]
	global_load_dwordx2 a[60:61], v[136:137], off
	s_add_i32 s30, s26, 26
	v_readlane_b32 s28, v100, s30
	s_nop 1
	v_mad_i64_i32 v[136:137], s[10:11], s28, v130, v[96:97]
	global_load_dwordx4 a[8:11], v[136:137], off
	v_mad_i64_i32 v[136:137], s[10:11], s28, v130, v[98:99]
	global_load_dwordx2 a[62:63], v[136:137], off
	s_add_i32 s30, s26, 27
	v_readlane_b32 s28, v100, s30
	s_nop 1
	v_mad_i64_i32 v[136:137], s[10:11], s28, v130, v[96:97]
	global_load_dwordx4 a[12:15], v[136:137], off
	v_mad_i64_i32 v[136:137], s[10:11], s28, v130, v[98:99]
	global_load_dwordx2 a[64:65], v[136:137], off
	s_waitcnt vmcnt(24)
	v_accvgpr_read_b32 v179, a67
	v_accvgpr_read_b32 v173, a41
	v_accvgpr_read_b32 v47, a19
	v_mov_b64_e32 v[40:41], v[220:221]
	v_mov_b64_e32 v[36:37], v[224:225]
	v_mov_b64_e32 v[32:33], v[228:229]
	v_accvgpr_read_b32 v178, a66
	v_mov_b64_e32 v[176:177], v[148:149]
	v_mov_b64_e32 v[174:175], v[252:253]
	v_accvgpr_read_b32 v172, a40
	v_accvgpr_read_b32 v46, a18
	v_accvgpr_read_b32 v45, a17
	v_accvgpr_read_b32 v44, a16
	v_mov_b64_e32 v[42:43], v[222:223]
	v_mov_b64_e32 v[38:39], v[226:227]
	v_mov_b64_e32 v[34:35], v[230:231]
	s_add_i32 s30, s26, 28
	v_readlane_b32 s28, v100, s30
	s_nop 1
	v_mad_i64_i32 v[136:137], s[10:11], s28, v130, v[96:97]
	global_load_dwordx4 a[16:19], v[136:137], off
	v_mad_i64_i32 v[136:137], s[10:11], s28, v130, v[98:99]
	global_load_dwordx2 a[66:67], v[136:137], off
	s_add_i32 s30, s26, 29
	v_readlane_b32 s28, v100, s30
	s_nop 1
	v_mad_i64_i32 v[136:137], s[10:11], s28, v130, v[96:97]
	global_load_dwordx4 v[220:223], v[136:137], off
	v_mad_i64_i32 v[136:137], s[10:11], s28, v130, v[98:99]
	global_load_dwordx2 v[148:149], v[136:137], off
	s_add_i32 s30, s26, 30
	v_readlane_b32 s28, v100, s30
	s_nop 1
	v_mad_i64_i32 v[136:137], s[10:11], s28, v130, v[96:97]
	global_load_dwordx4 v[224:227], v[136:137], off
	v_mad_i64_i32 v[136:137], s[10:11], s28, v130, v[98:99]
	global_load_dwordx2 v[252:253], v[136:137], off
	s_add_i32 s30, s26, 31
	v_readlane_b32 s28, v100, s30
	s_nop 1
	v_mad_i64_i32 v[136:137], s[10:11], s28, v130, v[96:97]
	global_load_dwordx4 v[228:231], v[136:137], off
	v_mad_i64_i32 v[136:137], s[10:11], s28, v130, v[98:99]
	global_load_dwordx2 a[40:41], v[136:137], off
	s_cmp_lg_u32 s26, 64
	s_cbranch_scc1 .LBB0_904
	v_ashrrev_i32_e32 v119, 31, v118
	v_ashrrev_i32_e32 v121, 31, v120
	v_lshlrev_b64 v[164:165], 2, v[120:121]
	v_lshl_add_u64 v[168:169], s[14:15], 0, v[164:165]
	v_lshl_add_u64 v[164:165], s[12:13], 0, v[164:165]
	v_lshlrev_b64 v[166:167], 2, v[118:119]
	v_lshl_add_u64 v[170:171], s[14:15], 0, v[166:167]
	v_lshl_add_u64 v[166:167], s[12:13], 0, v[166:167]
	global_load_dword a68, v[170:171], off
	global_load_dword a69, v[168:169], off
	global_load_dword v117, v[166:167], off
	global_load_dword v103, v[164:165], off
	s_branch .LBB0_904

.LBB0_1386:
	v_mov_b32_e32 v8, v128
	v_add_u32_e32 v9, 0xffffe000, v8
	v_lshrrev_b32_e32 v9, 12, v9
	v_add_u32_e32 v9, 1, v9
	v_cmp_lt_i32_e32 vcc, s29, v8
	v_lshlrev_b32_e32 v158, 16, v2
	v_and_b32_e32 v159, 0xffff0000, v2
	v_cndmask_b32_e32 v144, 0, v9, vcc
	v_accvgpr_read_b32 v9, a70
	v_add_u32_e32 v128, v8, v9
	v_min_i32_e32 v10, 0x5fff, v128
	v_lshlrev_b32_e32 v160, 16, v3
	v_and_b32_e32 v161, 0xffff0000, v3
	v_ashrrev_i32_e32 v9, 31, v8
	v_accvgpr_read_b32 v2, a72
	v_ashrrev_i32_e32 v11, 31, v10
	v_lshlrev_b32_e32 v154, 16, v0
	v_and_b32_e32 v155, 0xffff0000, v0
	v_lshlrev_b32_e32 v156, 16, v1
	v_and_b32_e32 v157, 0xffff0000, v1
	v_lshlrev_b64 v[0:1], 12, v[8:9]
	v_accvgpr_read_b32 v3, a73
	v_lshlrev_b64 v[12:13], 11, v[10:11]
	v_lshl_add_u64 v[162:163], v[2:3], 0, v[0:1]
	v_add_u32_e32 v0, 5, v144
	v_accvgpr_read_b32 v2, a230
	v_lshl_add_u64 v[12:13], v[102:103], 0, v[12:13]
	v_lshlrev_b64 v[10:11], 9, v[10:11]
	v_mad_u64_u32 v[0:1], s[12:13], v0, s27, v[114:115]
	v_accvgpr_read_b32 v3, a231
	global_load_dwordx4 a[32:35], v[12:13], off offset:16
	global_load_dwordx4 a[36:39], v[12:13], off
	v_lshl_add_u64 v[12:13], v[110:111], 0, v[10:11]
	v_lshl_add_u64 v[16:17], v[0:1], 0, v[2:3]
	global_load_dword v118, v[12:13], off
	global_load_dword v120, v[12:13], off offset:256
	v_lshl_add_u64 v[24:25], v[16:17], 0, s[14:15]
	v_add_co_u32_e32 v16, vcc, s33, v16
	v_lshl_add_u64 v[10:11], v[112:113], 0, v[10:11]
	s_nop 0
	v_addc_co_u32_e32 v17, vcc, 0, v17, vcc
	s_waitcnt vmcnt(6)
	v_mov_b32_e32 v32, v254
	s_waitcnt vmcnt(4)
	v_mov_b32_e32 v33, v147
	global_load_dword v147, v[10:11], off
	global_load_dword v254, v[10:11], off offset:256
	v_lshlrev_b32_e32 v124, 16, v4
	v_and_b32_e32 v125, 0xffff0000, v4
	v_lshlrev_b32_e32 v126, 16, v5
	v_and_b32_e32 v127, 0xffff0000, v5
	v_lshlrev_b32_e32 v150, 16, v6
	v_and_b32_e32 v151, 0xffff0000, v6
	v_lshlrev_b32_e32 v152, 16, v7
	v_and_b32_e32 v153, 0xffff0000, v7
	v_lshlrev_b64 v[122:123], 10, v[8:9]
	global_load_dwordx4 v[0:3], v[162:163], off offset:48
	global_load_dwordx4 v[4:7], v[162:163], off offset:32
	global_load_dwordx4 v[8:11], v[162:163], off offset:16
	global_load_dwordx4 v[12:15], v[162:163], off
	global_load_dwordx4 v[28:31], v[16:17], off
	s_nop 0
	global_load_dwordx4 v[16:19], v[24:25], off offset:48
	global_load_dwordx4 v[20:23], v[24:25], off offset:32
	s_nop 0
	global_load_dwordx4 v[24:27], v[24:25], off offset:16
	v_mul_f32_e32 v145, v33, v117
	v_mul_f32_e32 v146, v32, v105
	v_mov_b32_e32 v200, 0
	v_accvgpr_read_b32 v205, a43
	v_accvgpr_read_b32 v203, a45
	v_accvgpr_read_b32 v199, a47
	v_accvgpr_read_b32 v197, a49
	v_accvgpr_read_b32 v195, a51
	v_accvgpr_read_b32 v193, a53
	v_accvgpr_read_b32 v191, a55
	v_accvgpr_read_b32 v189, a57
	v_accvgpr_read_b32 v187, a59
	v_accvgpr_read_b32 v185, a61
	v_accvgpr_read_b32 v183, a63
	v_accvgpr_read_b32 v181, a65
	v_accvgpr_read_b32 v179, a67
	v_accvgpr_read_b32 v173, a41
	v_accvgpr_read_b32 v95, a23
	v_accvgpr_read_b32 v91, a31
	v_mov_b64_e32 v[84:85], v[232:233]
	v_mov_b64_e32 v[80:81], v[236:237]
	v_mov_b64_e32 v[76:77], v[240:241]
	v_mov_b64_e32 v[72:73], v[244:245]
	v_mov_b64_e32 v[68:69], v[248:249]
	v_accvgpr_read_b32 v67, a3
	v_accvgpr_read_b32 v63, a7
	v_accvgpr_read_b32 v59, a11
	v_accvgpr_read_b32 v55, a15
	v_accvgpr_read_b32 v51, a19
	v_accvgpr_read_b32 v47, a27
	v_mov_b64_e32 v[40:41], v[220:221]
	v_mov_b64_e32 v[36:37], v[224:225]
	s_mov_b32 s26, 0
	v_accvgpr_read_b32 v204, a42
	v_accvgpr_read_b32 v202, a44
	v_accvgpr_read_b32 v198, a46
	v_accvgpr_read_b32 v196, a48
	v_accvgpr_read_b32 v194, a50
	v_accvgpr_read_b32 v192, a52
	v_accvgpr_read_b32 v190, a54
	v_accvgpr_read_b32 v188, a56
	v_accvgpr_read_b32 v186, a58
	v_accvgpr_read_b32 v184, a60
	v_accvgpr_read_b32 v182, a62
	v_accvgpr_read_b32 v180, a64
	v_accvgpr_read_b32 v178, a66
	v_mov_b64_e32 v[176:177], v[148:149]
	v_mov_b64_e32 v[174:175], v[252:253]
	v_accvgpr_read_b32 v172, a40
	v_accvgpr_read_b32 v94, a22
	v_accvgpr_read_b32 v93, a21
	v_accvgpr_read_b32 v92, a20
	v_accvgpr_read_b32 v90, a30
	v_accvgpr_read_b32 v89, a29
	v_accvgpr_read_b32 v88, a28
	v_mov_b64_e32 v[86:87], v[234:235]
	v_mov_b64_e32 v[82:83], v[238:239]
	v_mov_b64_e32 v[78:79], v[242:243]
	v_mov_b64_e32 v[32:33], v[228:229]
	v_mov_b64_e32 v[74:75], v[246:247]
	v_mov_b64_e32 v[70:71], v[250:251]
	v_accvgpr_read_b32 v66, a2
	v_accvgpr_read_b32 v65, a1
	v_accvgpr_read_b32 v64, a0
	v_accvgpr_read_b32 v62, a6
	v_accvgpr_read_b32 v61, a5
	v_accvgpr_read_b32 v60, a4
	v_accvgpr_read_b32 v58, a10
	v_accvgpr_read_b32 v57, a9
	v_accvgpr_read_b32 v56, a8
	v_accvgpr_read_b32 v54, a14
	v_accvgpr_read_b32 v53, a13
	v_accvgpr_read_b32 v52, a12
	v_accvgpr_read_b32 v50, a18
	v_accvgpr_read_b32 v49, a17
	v_accvgpr_read_b32 v48, a16
	v_accvgpr_read_b32 v46, a26
	v_accvgpr_read_b32 v45, a25
	v_accvgpr_read_b32 v44, a24
	v_mov_b64_e32 v[42:43], v[222:223]
	v_mov_b64_e32 v[38:39], v[226:227]
	v_mov_b64_e32 v[34:35], v[230:231]
	v_mov_b32_e32 v201, v200
	v_mov_b32_e32 v218, v200
	v_mov_b32_e32 v219, v200
	v_mov_b32_e32 v216, v200
	v_mov_b32_e32 v217, v200
	v_mov_b32_e32 v214, v200
	v_mov_b32_e32 v215, v200
	v_mov_b32_e32 v212, v200
	v_mov_b32_e32 v213, v200
	v_mov_b32_e32 v210, v200
	v_mov_b32_e32 v211, v200
	v_mov_b32_e32 v208, v200
	v_mov_b32_e32 v209, v200
	v_mov_b32_e32 v206, v200
	v_mov_b32_e32 v207, v200
.LBB0_1387:
	s_add_i32 s58, s26, 16
	s_cmpk_gt_u32 s26, 0x6f
	s_cselect_b64 s[24:25], -1, 0
	s_cmpk_lt_u32 s26, 0x70
	s_cselect_b64 vcc, -1, 0
	s_bitcmp0_b32 s58, 6
	s_cselect_b64 s[12:13], -1, 0
	v_cndmask_b32_e64 v100, v116, v104, s[12:13]
	v_cndmask_b32_e32 v100, v118, v100, vcc
	s_nop 0
	v_readlane_b32 s28, v100, s58
	s_nop 1
	v_mad_i64_i32 v[148:149], s[12:13], s28, v130, v[96:97]
	global_load_dwordx4 a[20:23], v[148:149], off
	v_mad_i64_i32 v[148:149], s[12:13], s28, v130, v[98:99]
	s_add_i32 s12, s26, 17
	global_load_dwordx2 a[42:43], v[148:149], off
	s_nop 1
	v_readlane_b32 s28, v100, s12
	s_nop 1
	v_mad_i64_i32 v[148:149], s[12:13], s28, v130, v[96:97]
	global_load_dwordx4 a[28:31], v[148:149], off
	v_mad_i64_i32 v[148:149], s[12:13], s28, v130, v[98:99]
	s_add_i32 s12, s26, 18
	global_load_dwordx2 a[44:45], v[148:149], off
	s_nop 1
	v_readlane_b32 s28, v100, s12
	s_nop 1
	v_mad_i64_i32 v[148:149], s[12:13], s28, v130, v[96:97]
	global_load_dwordx4 v[232:235], v[148:149], off
	v_mad_i64_i32 v[148:149], s[12:13], s28, v130, v[98:99]
	s_add_i32 s12, s26, 19
	global_load_dwordx2 a[46:47], v[148:149], off
	s_nop 1
	v_readlane_b32 s28, v100, s12
	s_nop 1
	v_mad_i64_i32 v[148:149], s[12:13], s28, v130, v[96:97]
	global_load_dwordx4 v[236:239], v[148:149], off
	v_mad_i64_i32 v[148:149], s[12:13], s28, v130, v[98:99]
	s_add_i32 s12, s26, 20
	global_load_dwordx2 a[48:49], v[148:149], off
	s_nop 1
	v_readlane_b32 s28, v100, s12
	s_nop 1
	v_mad_i64_i32 v[148:149], s[12:13], s28, v130, v[96:97]
	global_load_dwordx4 v[240:243], v[148:149], off
	v_mad_i64_i32 v[148:149], s[12:13], s28, v130, v[98:99]
	s_add_i32 s12, s26, 21
	global_load_dwordx2 a[50:51], v[148:149], off
	s_nop 1
	v_readlane_b32 s28, v100, s12
	s_nop 1
	v_mad_i64_i32 v[148:149], s[12:13], s28, v130, v[96:97]
	global_load_dwordx4 v[244:247], v[148:149], off
	v_mad_i64_i32 v[148:149], s[12:13], s28, v130, v[98:99]
	s_add_i32 s12, s26, 22
	global_load_dwordx2 a[52:53], v[148:149], off
	s_nop 1
	v_readlane_b32 s28, v100, s12
	s_nop 1
	v_mad_i64_i32 v[148:149], s[12:13], s28, v130, v[96:97]
	global_load_dwordx4 v[248:251], v[148:149], off
	v_mad_i64_i32 v[148:149], s[12:13], s28, v130, v[98:99]
	s_add_i32 s12, s26, 23
	global_load_dwordx2 a[54:55], v[148:149], off
	s_nop 1
	v_readlane_b32 s28, v100, s12
	s_nop 1
	v_mad_i64_i32 v[148:149], s[12:13], s28, v130, v[96:97]
	global_load_dwordx4 a[0:3], v[148:149], off
	v_mad_i64_i32 v[148:149], s[12:13], s28, v130, v[98:99]
	s_add_i32 s12, s26, 24
	global_load_dwordx2 a[56:57], v[148:149], off
	s_nop 1
	v_readlane_b32 s28, v100, s12
	s_nop 1
	v_mad_i64_i32 v[148:149], s[12:13], s28, v130, v[96:97]
	global_load_dwordx4 a[4:7], v[148:149], off
	v_mad_i64_i32 v[148:149], s[12:13], s28, v130, v[98:99]
	s_add_i32 s12, s26, 25
	global_load_dwordx2 a[58:59], v[148:149], off
	s_nop 1
	v_readlane_b32 s28, v100, s12
	s_nop 1
	v_mad_i64_i32 v[148:149], s[12:13], s28, v130, v[96:97]
	global_load_dwordx4 a[8:11], v[148:149], off
	v_mad_i64_i32 v[148:149], s[12:13], s28, v130, v[98:99]
	s_add_i32 s12, s26, 26
	global_load_dwordx2 a[60:61], v[148:149], off
	s_nop 1
	v_readlane_b32 s28, v100, s12
	s_nop 1
	v_mad_i64_i32 v[148:149], s[12:13], s28, v130, v[96:97]
	global_load_dwordx4 a[12:15], v[148:149], off
	v_mad_i64_i32 v[148:149], s[12:13], s28, v130, v[98:99]
	s_add_i32 s12, s26, 27
	global_load_dwordx2 a[62:63], v[148:149], off
	s_nop 1
	v_readlane_b32 s28, v100, s12
	s_nop 1
	v_mad_i64_i32 v[148:149], s[12:13], s28, v130, v[96:97]
	global_load_dwordx4 a[16:19], v[148:149], off
	v_mad_i64_i32 v[148:149], s[12:13], s28, v130, v[98:99]
	s_add_i32 s12, s26, 28
	global_load_dwordx2 a[64:65], v[148:149], off
	s_nop 1
	v_readlane_b32 s28, v100, s12
	s_nop 1
	v_mad_i64_i32 v[148:149], s[12:13], s28, v130, v[96:97]
	global_load_dwordx4 a[24:27], v[148:149], off
	v_mad_i64_i32 v[148:149], s[12:13], s28, v130, v[98:99]
	s_add_i32 s12, s26, 29
	global_load_dwordx2 a[66:67], v[148:149], off
	s_nop 1
	v_readlane_b32 s28, v100, s12
	s_nop 1
	v_mad_i64_i32 v[148:149], s[12:13], s28, v130, v[96:97]
	global_load_dwordx4 v[220:223], v[148:149], off
	v_mad_i64_i32 v[148:149], s[12:13], s28, v130, v[98:99]
	s_add_i32 s12, s26, 30
	global_load_dwordx2 v[148:149], v[148:149], off
	s_nop 1
	v_readlane_b32 s28, v100, s12
	s_nop 1
	v_mad_i64_i32 v[224:225], s[12:13], s28, v130, v[96:97]
	v_mad_i64_i32 v[228:229], s[12:13], s28, v130, v[98:99]
	s_add_i32 s12, s26, 31
	global_load_dwordx4 v[224:227], v[224:225], off
	s_cmp_lg_u32 s26, 64
	s_nop 0
	v_readlane_b32 s28, v100, s12
	global_load_dwordx2 v[252:253], v[228:229], off
	s_nop 0
	v_mad_i64_i32 v[228:229], s[12:13], s28, v130, v[96:97]
	v_mad_i64_i32 v[100:101], s[12:13], s28, v130, v[98:99]
	global_load_dwordx4 v[228:231], v[228:229], off
	s_nop 0
	global_load_dwordx2 a[40:41], v[100:101], off
	s_cbranch_scc1 .LBB0_1389
	v_ashrrev_i32_e32 v119, 31, v118
	v_ashrrev_i32_e32 v121, 31, v120
	v_lshlrev_b64 v[164:165], 2, v[120:121]
	v_lshl_add_u64 v[168:169], s[4:5], 0, v[164:165]
	v_lshl_add_u64 v[164:165], s[16:17], 0, v[164:165]
	v_lshlrev_b64 v[166:167], 2, v[118:119]
	v_lshl_add_u64 v[170:171], s[4:5], 0, v[166:167]
	v_lshl_add_u64 v[166:167], s[16:17], 0, v[166:167]
	global_load_dword a68, v[170:171], off
	global_load_dword a69, v[168:169], off
	global_load_dword v117, v[166:167], off
	global_load_dword v105, v[164:165], off

.LBB0_1403:
	s_andn2_saveexec_b64 s[50:51], s[50:51]
	v_mul_f32_e32 v34, v33, v33
	v_fmamk_f32 v35, v34, 0xba1345e1, v139
	v_fmaak_f32 v35, v34, v35, 0xbcdac9b8
	v_fmaak_f32 v35, v34, v35, 0x3de703be
	v_fmaak_f32 v35, v34, v35, 0xbec09330
	v_fmaak_f32 v34, v34, v35, 0x3e0375d0
	v_fma_f32 v34, |v33|, v34, |v33|
	s_or_b64 exec, exec, s[50:51]
	v_cvt_scalef32_pk_f32_fp4 v[36:37], v204, 1.0
	v_pk_fma_f32 v[36:37], s[30:31], v[36:37], v[200:201] op_sel_hi:[0,1,1]
	v_cvt_scalef32_pk_f32_fp4 v[38:39], v204, 1.0 op_sel:[1,0,0]
	v_cvt_scalef32_pk_f32_fp4 v[52:53], v202, 1.0
	v_pk_fma_f32 v[38:39], s[30:31], v[38:39], v[218:219] op_sel_hi:[0,1,1]
	v_cvt_scalef32_pk_f32_fp4 v[40:41], v204, 1.0 op_sel:[0,1,0]
	v_pk_fma_f32 v[36:37], s[28:29], v[52:53], v[36:37] op_sel_hi:[0,1,1]
	v_cvt_scalef32_pk_f32_fp4 v[52:53], v202, 1.0 op_sel:[1,0,0]
	v_pk_fma_f32 v[40:41], s[30:31], v[40:41], v[216:217] op_sel_hi:[0,1,1]
	v_cvt_scalef32_pk_f32_fp4 v[42:43], v204, 1.0 op_sel:[1,1,0]
	v_pk_fma_f32 v[38:39], s[28:29], v[52:53], v[38:39] op_sel_hi:[0,1,1]
	v_cvt_scalef32_pk_f32_fp4 v[52:53], v202, 1.0 op_sel:[0,1,0]
	v_pk_fma_f32 v[42:43], s[30:31], v[42:43], v[214:215] op_sel_hi:[0,1,1]
	v_cvt_scalef32_pk_f32_fp4 v[44:45], v205, 1.0
	v_pk_fma_f32 v[40:41], s[28:29], v[52:53], v[40:41] op_sel_hi:[0,1,1]
	v_cvt_scalef32_pk_f32_fp4 v[52:53], v202, 1.0 op_sel:[1,1,0]
	v_pk_fma_f32 v[44:45], s[30:31], v[44:45], v[212:213] op_sel_hi:[0,1,1]
	v_cvt_scalef32_pk_f32_fp4 v[46:47], v205, 1.0 op_sel:[1,0,0]
	v_pk_fma_f32 v[42:43], s[28:29], v[52:53], v[42:43] op_sel_hi:[0,1,1]
	v_cvt_scalef32_pk_f32_fp4 v[52:53], v203, 1.0
	v_pk_fma_f32 v[46:47], s[30:31], v[46:47], v[210:211] op_sel_hi:[0,1,1]
	v_cvt_scalef32_pk_f32_fp4 v[48:49], v205, 1.0 op_sel:[0,1,0]
	v_pk_fma_f32 v[44:45], s[28:29], v[52:53], v[44:45] op_sel_hi:[0,1,1]
	v_cvt_scalef32_pk_f32_fp4 v[52:53], v203, 1.0 op_sel:[1,0,0]
	v_pk_fma_f32 v[48:49], s[30:31], v[48:49], v[208:209] op_sel_hi:[0,1,1]
	v_cvt_scalef32_pk_f32_fp4 v[50:51], v205, 1.0 op_sel:[1,1,0]
	v_pk_fma_f32 v[46:47], s[28:29], v[52:53], v[46:47] op_sel_hi:[0,1,1]
	v_cvt_scalef32_pk_f32_fp4 v[52:53], v203, 1.0 op_sel:[0,1,0]
	v_pk_fma_f32 v[50:51], s[30:31], v[50:51], v[206:207] op_sel_hi:[0,1,1]
	v_pk_fma_f32 v[48:49], s[28:29], v[52:53], v[48:49] op_sel_hi:[0,1,1]
	v_cvt_scalef32_pk_f32_fp4 v[52:53], v203, 1.0 op_sel:[1,1,0]
	v_pk_fma_f32 v[50:51], s[28:29], v[52:53], v[50:51] op_sel_hi:[0,1,1]
	v_cvt_scalef32_pk_f32_fp4 v[52:53], v198, 1.0
	v_pk_fma_f32 v[36:37], s[26:27], v[52:53], v[36:37] op_sel_hi:[0,1,1]
	v_cvt_scalef32_pk_f32_fp4 v[52:53], v198, 1.0 op_sel:[1,0,0]
	v_pk_fma_f32 v[38:39], s[26:27], v[52:53], v[38:39] op_sel_hi:[0,1,1]
	v_cvt_scalef32_pk_f32_fp4 v[52:53], v198, 1.0 op_sel:[0,1,0]
	v_pk_fma_f32 v[40:41], s[26:27], v[52:53], v[40:41] op_sel_hi:[0,1,1]
	v_cvt_scalef32_pk_f32_fp4 v[52:53], v198, 1.0 op_sel:[1,1,0]
	v_pk_fma_f32 v[42:43], s[26:27], v[52:53], v[42:43] op_sel_hi:[0,1,1]
	v_cvt_scalef32_pk_f32_fp4 v[52:53], v199, 1.0
	v_pk_fma_f32 v[44:45], s[26:27], v[52:53], v[44:45] op_sel_hi:[0,1,1]
	v_cvt_scalef32_pk_f32_fp4 v[52:53], v199, 1.0 op_sel:[1,0,0]
	v_pk_fma_f32 v[46:47], s[26:27], v[52:53], v[46:47] op_sel_hi:[0,1,1]
	v_cvt_scalef32_pk_f32_fp4 v[52:53], v199, 1.0 op_sel:[0,1,0]
	v_pk_fma_f32 v[48:49], s[26:27], v[52:53], v[48:49] op_sel_hi:[0,1,1]
	v_cvt_scalef32_pk_f32_fp4 v[52:53], v199, 1.0 op_sel:[1,1,0]
	v_pk_fma_f32 v[50:51], s[26:27], v[52:53], v[50:51] op_sel_hi:[0,1,1]
	v_cvt_scalef32_pk_f32_fp4 v[52:53], v196, 1.0
	v_pk_fma_f32 v[36:37], s[12:13], v[52:53], v[36:37] op_sel_hi:[0,1,1]
	v_cvt_scalef32_pk_f32_fp4 v[52:53], v196, 1.0 op_sel:[1,0,0]
	v_pk_fma_f32 v[38:39], s[12:13], v[52:53], v[38:39] op_sel_hi:[0,1,1]
	v_cvt_scalef32_pk_f32_fp4 v[52:53], v196, 1.0 op_sel:[0,1,0]
	v_pk_fma_f32 v[40:41], s[12:13], v[52:53], v[40:41] op_sel_hi:[0,1,1]
	v_cvt_scalef32_pk_f32_fp4 v[52:53], v196, 1.0 op_sel:[1,1,0]
	v_pk_fma_f32 v[42:43], s[12:13], v[52:53], v[42:43] op_sel_hi:[0,1,1]
	v_cvt_scalef32_pk_f32_fp4 v[52:53], v197, 1.0
	v_pk_fma_f32 v[44:45], s[12:13], v[52:53], v[44:45] op_sel_hi:[0,1,1]
	v_cvt_scalef32_pk_f32_fp4 v[52:53], v197, 1.0 op_sel:[1,0,0]
	v_pk_fma_f32 v[46:47], s[12:13], v[52:53], v[46:47] op_sel_hi:[0,1,1]
	v_cvt_scalef32_pk_f32_fp4 v[52:53], v197, 1.0 op_sel:[0,1,0]
	v_pk_fma_f32 v[48:49], s[12:13], v[52:53], v[48:49] op_sel_hi:[0,1,1]
	v_cvt_scalef32_pk_f32_fp4 v[52:53], v197, 1.0 op_sel:[1,1,0]
	v_pk_fma_f32 v[50:51], s[12:13], v[52:53], v[50:51] op_sel_hi:[0,1,1]
	v_cvt_scalef32_pk_f32_fp4 v[52:53], v194, 1.0
	v_pk_fma_f32 v[36:37], s[40:41], v[52:53], v[36:37] op_sel_hi:[0,1,1]
	v_cvt_scalef32_pk_f32_fp4 v[52:53], v194, 1.0 op_sel:[1,0,0]
	v_pk_fma_f32 v[38:39], s[40:41], v[52:53], v[38:39] op_sel_hi:[0,1,1]
	v_cvt_scalef32_pk_f32_fp4 v[52:53], v194, 1.0 op_sel:[0,1,0]
	v_pk_fma_f32 v[40:41], s[40:41], v[52:53], v[40:41] op_sel_hi:[0,1,1]
	v_cvt_scalef32_pk_f32_fp4 v[52:53], v194, 1.0 op_sel:[1,1,0]
	v_pk_fma_f32 v[42:43], s[40:41], v[52:53], v[42:43] op_sel_hi:[0,1,1]
	v_cvt_scalef32_pk_f32_fp4 v[52:53], v195, 1.0
	v_pk_fma_f32 v[44:45], s[40:41], v[52:53], v[44:45] op_sel_hi:[0,1,1]
	v_cvt_scalef32_pk_f32_fp4 v[52:53], v195, 1.0 op_sel:[1,0,0]
	v_pk_fma_f32 v[46:47], s[40:41], v[52:53], v[46:47] op_sel_hi:[0,1,1]
	v_cvt_scalef32_pk_f32_fp4 v[52:53], v195, 1.0 op_sel:[0,1,0]
	v_pk_fma_f32 v[48:49], s[40:41], v[52:53], v[48:49] op_sel_hi:[0,1,1]
	v_cvt_scalef32_pk_f32_fp4 v[52:53], v195, 1.0 op_sel:[1,1,0]
	v_pk_fma_f32 v[50:51], s[40:41], v[52:53], v[50:51] op_sel_hi:[0,1,1]
	v_cvt_scalef32_pk_f32_fp4 v[52:53], v192, 1.0
	v_pk_fma_f32 v[36:37], s[38:39], v[52:53], v[36:37] op_sel_hi:[0,1,1]
	v_cvt_scalef32_pk_f32_fp4 v[52:53], v192, 1.0 op_sel:[1,0,0]
	v_pk_fma_f32 v[38:39], s[38:39], v[52:53], v[38:39] op_sel_hi:[0,1,1]
	v_cvt_scalef32_pk_f32_fp4 v[52:53], v192, 1.0 op_sel:[0,1,0]
	v_pk_fma_f32 v[40:41], s[38:39], v[52:53], v[40:41] op_sel_hi:[0,1,1]
	v_cvt_scalef32_pk_f32_fp4 v[52:53], v192, 1.0 op_sel:[1,1,0]
	v_pk_fma_f32 v[42:43], s[38:39], v[52:53], v[42:43] op_sel_hi:[0,1,1]
	v_cvt_scalef32_pk_f32_fp4 v[52:53], v193, 1.0
	v_pk_fma_f32 v[44:45], s[38:39], v[52:53], v[44:45] op_sel_hi:[0,1,1]
	v_cvt_scalef32_pk_f32_fp4 v[52:53], v193, 1.0 op_sel:[1,0,0]
	v_pk_fma_f32 v[46:47], s[38:39], v[52:53], v[46:47] op_sel_hi:[0,1,1]
	v_cvt_scalef32_pk_f32_fp4 v[52:53], v193, 1.0 op_sel:[0,1,0]
	v_pk_fma_f32 v[48:49], s[38:39], v[52:53], v[48:49] op_sel_hi:[0,1,1]
	v_cvt_scalef32_pk_f32_fp4 v[52:53], v193, 1.0 op_sel:[1,1,0]
	v_pk_fma_f32 v[50:51], s[38:39], v[52:53], v[50:51] op_sel_hi:[0,1,1]
	v_cvt_scalef32_pk_f32_fp4 v[52:53], v190, 1.0
	v_pk_fma_f32 v[36:37], s[36:37], v[52:53], v[36:37] op_sel_hi:[0,1,1]
	v_cvt_scalef32_pk_f32_fp4 v[52:53], v190, 1.0 op_sel:[1,0,0]
	v_pk_fma_f32 v[38:39], s[36:37], v[52:53], v[38:39] op_sel_hi:[0,1,1]
	v_cvt_scalef32_pk_f32_fp4 v[52:53], v190, 1.0 op_sel:[0,1,0]
	v_pk_fma_f32 v[40:41], s[36:37], v[52:53], v[40:41] op_sel_hi:[0,1,1]
	v_cvt_scalef32_pk_f32_fp4 v[52:53], v190, 1.0 op_sel:[1,1,0]
	v_pk_fma_f32 v[42:43], s[36:37], v[52:53], v[42:43] op_sel_hi:[0,1,1]
	v_cvt_scalef32_pk_f32_fp4 v[52:53], v191, 1.0
	v_pk_fma_f32 v[44:45], s[36:37], v[52:53], v[44:45] op_sel_hi:[0,1,1]
	v_cvt_scalef32_pk_f32_fp4 v[52:53], v191, 1.0 op_sel:[1,0,0]
	v_pk_fma_f32 v[46:47], s[36:37], v[52:53], v[46:47] op_sel_hi:[0,1,1]
	v_cvt_scalef32_pk_f32_fp4 v[52:53], v191, 1.0 op_sel:[0,1,0]
	v_pk_fma_f32 v[48:49], s[36:37], v[52:53], v[48:49] op_sel_hi:[0,1,1]
	v_cvt_scalef32_pk_f32_fp4 v[52:53], v191, 1.0 op_sel:[1,1,0]
	v_pk_fma_f32 v[50:51], s[36:37], v[52:53], v[50:51] op_sel_hi:[0,1,1]
	v_cvt_scalef32_pk_f32_fp4 v[52:53], v188, 1.0
	v_pk_fma_f32 v[36:37], s[34:35], v[52:53], v[36:37] op_sel_hi:[0,1,1]
	v_cvt_scalef32_pk_f32_fp4 v[52:53], v188, 1.0 op_sel:[1,0,0]
	v_pk_fma_f32 v[38:39], s[34:35], v[52:53], v[38:39] op_sel_hi:[0,1,1]
	v_cvt_scalef32_pk_f32_fp4 v[52:53], v188, 1.0 op_sel:[0,1,0]
	v_pk_fma_f32 v[40:41], s[34:35], v[52:53], v[40:41] op_sel_hi:[0,1,1]
	v_cvt_scalef32_pk_f32_fp4 v[52:53], v188, 1.0 op_sel:[1,1,0]
	v_pk_fma_f32 v[42:43], s[34:35], v[52:53], v[42:43] op_sel_hi:[0,1,1]
	v_cvt_scalef32_pk_f32_fp4 v[52:53], v189, 1.0
	v_pk_fma_f32 v[44:45], s[34:35], v[52:53], v[44:45] op_sel_hi:[0,1,1]
	v_cvt_scalef32_pk_f32_fp4 v[52:53], v189, 1.0 op_sel:[1,0,0]
	v_pk_fma_f32 v[46:47], s[34:35], v[52:53], v[46:47] op_sel_hi:[0,1,1]
	v_cvt_scalef32_pk_f32_fp4 v[52:53], v189, 1.0 op_sel:[0,1,0]
	v_pk_fma_f32 v[48:49], s[34:35], v[52:53], v[48:49] op_sel_hi:[0,1,1]
	v_cvt_scalef32_pk_f32_fp4 v[52:53], v189, 1.0 op_sel:[1,1,0]
	v_pk_fma_f32 v[50:51], s[34:35], v[52:53], v[50:51] op_sel_hi:[0,1,1]
	v_cvt_scalef32_pk_f32_fp4 v[52:53], v186, 1.0
	v_pk_fma_f32 v[36:37], s[48:49], v[52:53], v[36:37] op_sel_hi:[0,1,1]
	v_cvt_scalef32_pk_f32_fp4 v[52:53], v186, 1.0 op_sel:[1,0,0]
	v_pk_fma_f32 v[38:39], s[48:49], v[52:53], v[38:39] op_sel_hi:[0,1,1]
	v_cvt_scalef32_pk_f32_fp4 v[52:53], v186, 1.0 op_sel:[0,1,0]
	v_pk_fma_f32 v[40:41], s[48:49], v[52:53], v[40:41] op_sel_hi:[0,1,1]
	v_cvt_scalef32_pk_f32_fp4 v[52:53], v186, 1.0 op_sel:[1,1,0]
	v_pk_fma_f32 v[42:43], s[48:49], v[52:53], v[42:43] op_sel_hi:[0,1,1]
	v_cvt_scalef32_pk_f32_fp4 v[52:53], v187, 1.0
	v_pk_fma_f32 v[44:45], s[48:49], v[52:53], v[44:45] op_sel_hi:[0,1,1]
	v_cvt_scalef32_pk_f32_fp4 v[52:53], v187, 1.0 op_sel:[1,0,0]
	v_pk_fma_f32 v[46:47], s[48:49], v[52:53], v[46:47] op_sel_hi:[0,1,1]
	v_cvt_scalef32_pk_f32_fp4 v[52:53], v187, 1.0 op_sel:[0,1,0]
	v_pk_fma_f32 v[48:49], s[48:49], v[52:53], v[48:49] op_sel_hi:[0,1,1]
	v_cvt_scalef32_pk_f32_fp4 v[52:53], v187, 1.0 op_sel:[1,1,0]
	v_pk_fma_f32 v[50:51], s[48:49], v[52:53], v[50:51] op_sel_hi:[0,1,1]
	v_cvt_scalef32_pk_f32_fp4 v[52:53], v184, 1.0
	v_pk_fma_f32 v[36:37], s[46:47], v[52:53], v[36:37] op_sel_hi:[0,1,1]
	v_cvt_scalef32_pk_f32_fp4 v[52:53], v184, 1.0 op_sel:[1,0,0]
	v_pk_fma_f32 v[38:39], s[46:47], v[52:53], v[38:39] op_sel_hi:[0,1,1]
	v_cvt_scalef32_pk_f32_fp4 v[52:53], v184, 1.0 op_sel:[0,1,0]
	v_pk_fma_f32 v[40:41], s[46:47], v[52:53], v[40:41] op_sel_hi:[0,1,1]
	v_cvt_scalef32_pk_f32_fp4 v[52:53], v184, 1.0 op_sel:[1,1,0]
	v_pk_fma_f32 v[42:43], s[46:47], v[52:53], v[42:43] op_sel_hi:[0,1,1]
	v_cvt_scalef32_pk_f32_fp4 v[52:53], v185, 1.0
	v_pk_fma_f32 v[44:45], s[46:47], v[52:53], v[44:45] op_sel_hi:[0,1,1]
	v_cvt_scalef32_pk_f32_fp4 v[52:53], v185, 1.0 op_sel:[1,0,0]
	v_pk_fma_f32 v[46:47], s[46:47], v[52:53], v[46:47] op_sel_hi:[0,1,1]
	v_cvt_scalef32_pk_f32_fp4 v[52:53], v185, 1.0 op_sel:[0,1,0]
	v_pk_fma_f32 v[48:49], s[46:47], v[52:53], v[48:49] op_sel_hi:[0,1,1]
	v_cvt_scalef32_pk_f32_fp4 v[52:53], v185, 1.0 op_sel:[1,1,0]
	v_pk_fma_f32 v[50:51], s[46:47], v[52:53], v[50:51] op_sel_hi:[0,1,1]
	v_cvt_scalef32_pk_f32_fp4 v[52:53], v182, 1.0
	v_pk_fma_f32 v[36:37], s[44:45], v[52:53], v[36:37] op_sel_hi:[0,1,1]
	v_cvt_scalef32_pk_f32_fp4 v[52:53], v182, 1.0 op_sel:[1,0,0]
	v_pk_fma_f32 v[38:39], s[44:45], v[52:53], v[38:39] op_sel_hi:[0,1,1]
	v_cvt_scalef32_pk_f32_fp4 v[52:53], v182, 1.0 op_sel:[0,1,0]
	v_pk_fma_f32 v[40:41], s[44:45], v[52:53], v[40:41] op_sel_hi:[0,1,1]
	v_cvt_scalef32_pk_f32_fp4 v[52:53], v182, 1.0 op_sel:[1,1,0]
	v_pk_fma_f32 v[42:43], s[44:45], v[52:53], v[42:43] op_sel_hi:[0,1,1]
	v_cvt_scalef32_pk_f32_fp4 v[52:53], v183, 1.0
	v_pk_fma_f32 v[44:45], s[44:45], v[52:53], v[44:45] op_sel_hi:[0,1,1]
	v_cvt_scalef32_pk_f32_fp4 v[52:53], v183, 1.0 op_sel:[1,0,0]
	v_pk_fma_f32 v[46:47], s[44:45], v[52:53], v[46:47] op_sel_hi:[0,1,1]
	v_cvt_scalef32_pk_f32_fp4 v[52:53], v183, 1.0 op_sel:[0,1,0]
	v_pk_fma_f32 v[48:49], s[44:45], v[52:53], v[48:49] op_sel_hi:[0,1,1]
	v_cvt_scalef32_pk_f32_fp4 v[52:53], v183, 1.0 op_sel:[1,1,0]
	v_pk_fma_f32 v[50:51], s[44:45], v[52:53], v[50:51] op_sel_hi:[0,1,1]
	v_cvt_scalef32_pk_f32_fp4 v[52:53], v180, 1.0
	v_pk_fma_f32 v[36:37], s[42:43], v[52:53], v[36:37] op_sel_hi:[0,1,1]
	v_cvt_scalef32_pk_f32_fp4 v[52:53], v180, 1.0 op_sel:[1,0,0]
	v_pk_fma_f32 v[38:39], s[42:43], v[52:53], v[38:39] op_sel_hi:[0,1,1]
	v_cvt_scalef32_pk_f32_fp4 v[52:53], v180, 1.0 op_sel:[0,1,0]
	v_pk_fma_f32 v[40:41], s[42:43], v[52:53], v[40:41] op_sel_hi:[0,1,1]
	v_cvt_scalef32_pk_f32_fp4 v[52:53], v180, 1.0 op_sel:[1,1,0]
	v_pk_fma_f32 v[42:43], s[42:43], v[52:53], v[42:43] op_sel_hi:[0,1,1]
	v_cvt_scalef32_pk_f32_fp4 v[52:53], v181, 1.0
	v_pk_fma_f32 v[44:45], s[42:43], v[52:53], v[44:45] op_sel_hi:[0,1,1]
	v_cvt_scalef32_pk_f32_fp4 v[52:53], v181, 1.0 op_sel:[1,0,0]
	v_pk_fma_f32 v[46:47], s[42:43], v[52:53], v[46:47] op_sel_hi:[0,1,1]
	v_cvt_scalef32_pk_f32_fp4 v[52:53], v181, 1.0 op_sel:[0,1,0]
	v_pk_fma_f32 v[48:49], s[42:43], v[52:53], v[48:49] op_sel_hi:[0,1,1]
	v_cvt_scalef32_pk_f32_fp4 v[52:53], v181, 1.0 op_sel:[1,1,0]
	v_pk_fma_f32 v[50:51], s[42:43], v[52:53], v[50:51] op_sel_hi:[0,1,1]
	v_mov_b32_e32 v35, s59
	v_mov_b32_e32 v52, s35
	v_cndmask_b32_e64 v35, v35, v52, s[10:11]
	v_mov_b32_e32 v52, s43
	v_bfi_b32 v33, s55, v34, v33
	v_cndmask_b32_e64 v35, v35, v52, s[8:9]
	v_mov_b32_e32 v52, s13
	v_mul_f32_e32 v32, 0.5, v32
	v_add_f32_e32 v33, 1.0, v33
	v_cndmask_b32_e64 v35, v35, v52, s[6:7]
	v_mul_f32_e32 v32, v32, v33
	v_mul_f32_e32 v32, v35, v32
	v_cvt_scalef32_pk_f32_fp4 v[34:35], v178, 1.0 op_sel:[1,0,0]
	v_readlane_b32 s12, v32, 0
	v_readlane_b32 s26, v32, 32
	v_readlane_b32 s28, v32, 16
	v_readlane_b32 s30, v32, 48
	v_cvt_scalef32_pk_f32_fp4 v[32:33], v178, 1.0
	v_pk_fma_f32 v[32:33], s[12:13], v[32:33], v[36:37] op_sel_hi:[0,1,1]
	v_cvt_scalef32_pk_f32_fp4 v[36:37], v178, 1.0 op_sel:[0,1,0]
	v_pk_fma_f32 v[36:37], s[12:13], v[36:37], v[40:41] op_sel_hi:[0,1,1]
	v_cvt_scalef32_pk_f32_fp4 v[40:41], v179, 1.0
	v_pk_fma_f32 v[40:41], s[12:13], v[40:41], v[44:45] op_sel_hi:[0,1,1]
	v_cvt_scalef32_pk_f32_fp4 v[44:45], v179, 1.0 op_sel:[0,1,0]
	v_pk_fma_f32 v[44:45], s[12:13], v[44:45], v[48:49] op_sel_hi:[0,1,1]
	v_cvt_scalef32_pk_f32_fp4 v[48:49], v176, 1.0
	v_pk_fma_f32 v[34:35], s[12:13], v[34:35], v[38:39] op_sel_hi:[0,1,1]
	v_pk_fma_f32 v[32:33], s[26:27], v[48:49], v[32:33] op_sel_hi:[0,1,1]
	v_cvt_scalef32_pk_f32_fp4 v[48:49], v176, 1.0 op_sel:[1,0,0]
	v_cvt_scalef32_pk_f32_fp4 v[38:39], v178, 1.0 op_sel:[1,1,0]
	v_pk_fma_f32 v[34:35], s[26:27], v[48:49], v[34:35] op_sel_hi:[0,1,1]
	v_cvt_scalef32_pk_f32_fp4 v[48:49], v176, 1.0 op_sel:[0,1,0]
	v_pk_fma_f32 v[38:39], s[12:13], v[38:39], v[42:43] op_sel_hi:[0,1,1]
	v_pk_fma_f32 v[36:37], s[26:27], v[48:49], v[36:37] op_sel_hi:[0,1,1]
	v_cvt_scalef32_pk_f32_fp4 v[48:49], v176, 1.0 op_sel:[1,1,0]
	v_cvt_scalef32_pk_f32_fp4 v[42:43], v179, 1.0 op_sel:[1,0,0]
	v_pk_fma_f32 v[38:39], s[26:27], v[48:49], v[38:39] op_sel_hi:[0,1,1]
	v_cvt_scalef32_pk_f32_fp4 v[48:49], v177, 1.0
	v_pk_fma_f32 v[42:43], s[12:13], v[42:43], v[46:47] op_sel_hi:[0,1,1]
	v_pk_fma_f32 v[40:41], s[26:27], v[48:49], v[40:41] op_sel_hi:[0,1,1]
	v_cvt_scalef32_pk_f32_fp4 v[48:49], v177, 1.0 op_sel:[1,0,0]
	v_cvt_scalef32_pk_f32_fp4 v[46:47], v179, 1.0 op_sel:[1,1,0]
	v_pk_fma_f32 v[42:43], s[26:27], v[48:49], v[42:43] op_sel_hi:[0,1,1]
	v_cvt_scalef32_pk_f32_fp4 v[48:49], v177, 1.0 op_sel:[0,1,0]
	v_pk_fma_f32 v[46:47], s[12:13], v[46:47], v[50:51] op_sel_hi:[0,1,1]
	v_pk_fma_f32 v[44:45], s[26:27], v[48:49], v[44:45] op_sel_hi:[0,1,1]
	v_cvt_scalef32_pk_f32_fp4 v[48:49], v177, 1.0 op_sel:[1,1,0]
	v_pk_fma_f32 v[46:47], s[26:27], v[48:49], v[46:47] op_sel_hi:[0,1,1]
	v_cvt_scalef32_pk_f32_fp4 v[48:49], v174, 1.0
	v_pk_fma_f32 v[32:33], s[28:29], v[48:49], v[32:33] op_sel_hi:[0,1,1]
	v_cvt_scalef32_pk_f32_fp4 v[48:49], v174, 1.0 op_sel:[1,0,0]
	v_pk_fma_f32 v[34:35], s[28:29], v[48:49], v[34:35] op_sel_hi:[0,1,1]
	v_cvt_scalef32_pk_f32_fp4 v[48:49], v174, 1.0 op_sel:[0,1,0]
	v_pk_fma_f32 v[36:37], s[28:29], v[48:49], v[36:37] op_sel_hi:[0,1,1]
	v_cvt_scalef32_pk_f32_fp4 v[48:49], v174, 1.0 op_sel:[1,1,0]
	v_pk_fma_f32 v[38:39], s[28:29], v[48:49], v[38:39] op_sel_hi:[0,1,1]
	v_cvt_scalef32_pk_f32_fp4 v[48:49], v175, 1.0
	v_pk_fma_f32 v[40:41], s[28:29], v[48:49], v[40:41] op_sel_hi:[0,1,1]
	v_cvt_scalef32_pk_f32_fp4 v[48:49], v175, 1.0 op_sel:[1,0,0]
	v_pk_fma_f32 v[42:43], s[28:29], v[48:49], v[42:43] op_sel_hi:[0,1,1]
	v_cvt_scalef32_pk_f32_fp4 v[48:49], v175, 1.0 op_sel:[0,1,0]
	v_pk_fma_f32 v[44:45], s[28:29], v[48:49], v[44:45] op_sel_hi:[0,1,1]
	v_cvt_scalef32_pk_f32_fp4 v[48:49], v175, 1.0 op_sel:[1,1,0]
	v_pk_fma_f32 v[46:47], s[28:29], v[48:49], v[46:47] op_sel_hi:[0,1,1]
	v_cvt_scalef32_pk_f32_fp4 v[48:49], v172, 1.0
	v_pk_fma_f32 v[200:201], s[30:31], v[48:49], v[32:33] op_sel_hi:[0,1,1]
	v_cvt_scalef32_pk_f32_fp4 v[32:33], v172, 1.0 op_sel:[1,0,0]
	v_pk_fma_f32 v[218:219], s[30:31], v[32:33], v[34:35] op_sel_hi:[0,1,1]
	v_cvt_scalef32_pk_f32_fp4 v[32:33], v172, 1.0 op_sel:[0,1,0]
	v_pk_fma_f32 v[216:217], s[30:31], v[32:33], v[36:37] op_sel_hi:[0,1,1]
	v_cvt_scalef32_pk_f32_fp4 v[32:33], v172, 1.0 op_sel:[1,1,0]
	v_pk_fma_f32 v[214:215], s[30:31], v[32:33], v[38:39] op_sel_hi:[0,1,1]
	v_cvt_scalef32_pk_f32_fp4 v[32:33], v173, 1.0
	v_pk_fma_f32 v[212:213], s[30:31], v[32:33], v[40:41] op_sel_hi:[0,1,1]
	v_cvt_scalef32_pk_f32_fp4 v[32:33], v173, 1.0 op_sel:[1,0,0]
	v_pk_fma_f32 v[210:211], s[30:31], v[32:33], v[42:43] op_sel_hi:[0,1,1]
	v_cvt_scalef32_pk_f32_fp4 v[32:33], v173, 1.0 op_sel:[0,1,0]
	v_pk_fma_f32 v[208:209], s[30:31], v[32:33], v[44:45] op_sel_hi:[0,1,1]
	v_cvt_scalef32_pk_f32_fp4 v[32:33], v173, 1.0 op_sel:[1,1,0]
	v_pk_fma_f32 v[206:207], s[30:31], v[32:33], v[46:47] op_sel_hi:[0,1,1]
	s_and_b64 vcc, exec, s[24:25]
	s_cbranch_vccnz .LBB0_1385
	s_mov_b32 s26, s58
	s_add_i32 s58, s26, 16
	s_cmpk_gt_u32 s26, 0x6f
	s_cselect_b64 s[24:25], -1, 0
	s_cmpk_lt_u32 s26, 0x70
	s_cselect_b64 vcc, -1, 0
	s_bitcmp0_b32 s58, 6
	s_cselect_b64 s[12:13], -1, 0
	v_cndmask_b32_e64 v100, v116, v104, s[12:13]
	v_cndmask_b32_e32 v100, v118, v100, vcc
	s_nop 0
	s_waitcnt vmcnt(24)
	v_accvgpr_read_b32 v205, a43
	v_accvgpr_read_b32 v203, a45
	v_accvgpr_read_b32 v199, a47
	v_accvgpr_read_b32 v197, a49
	v_accvgpr_read_b32 v95, a23
	v_accvgpr_read_b32 v91, a31
	v_mov_b64_e32 v[84:85], v[232:233]
	v_mov_b64_e32 v[80:81], v[236:237]
	v_accvgpr_read_b32 v204, a42
	v_accvgpr_read_b32 v202, a44
	v_accvgpr_read_b32 v198, a46
	v_accvgpr_read_b32 v196, a48
	v_accvgpr_read_b32 v94, a22
	v_accvgpr_read_b32 v93, a21
	v_accvgpr_read_b32 v92, a20
	v_accvgpr_read_b32 v90, a30
	v_accvgpr_read_b32 v89, a29
	v_accvgpr_read_b32 v88, a28
	v_mov_b64_e32 v[86:87], v[234:235]
	v_mov_b64_e32 v[82:83], v[238:239]
	s_add_i32 s30, s26, 16
	v_readlane_b32 s28, v100, s30
	s_nop 1
	v_mad_i64_i32 v[136:137], s[12:13], s28, v130, v[96:97]
	global_load_dwordx4 a[20:23], v[136:137], off
	v_mad_i64_i32 v[136:137], s[12:13], s28, v130, v[98:99]
	global_load_dwordx2 a[42:43], v[136:137], off
	s_add_i32 s30, s26, 17
	v_readlane_b32 s28, v100, s30
	s_nop 1
	v_mad_i64_i32 v[136:137], s[12:13], s28, v130, v[96:97]
	global_load_dwordx4 a[28:31], v[136:137], off
	v_mad_i64_i32 v[136:137], s[12:13], s28, v130, v[98:99]
	global_load_dwordx2 a[44:45], v[136:137], off
	s_add_i32 s30, s26, 18
	v_readlane_b32 s28, v100, s30
	s_nop 1
	v_mad_i64_i32 v[136:137], s[12:13], s28, v130, v[96:97]
	global_load_dwordx4 v[232:235], v[136:137], off
	v_mad_i64_i32 v[136:137], s[12:13], s28, v130, v[98:99]
	global_load_dwordx2 a[46:47], v[136:137], off
	s_add_i32 s30, s26, 19
	v_readlane_b32 s28, v100, s30
	s_nop 1
	v_mad_i64_i32 v[136:137], s[12:13], s28, v130, v[96:97]
	global_load_dwordx4 v[236:239], v[136:137], off
	v_mad_i64_i32 v[136:137], s[12:13], s28, v130, v[98:99]
	global_load_dwordx2 a[48:49], v[136:137], off
	s_waitcnt vmcnt(24)
	v_accvgpr_read_b32 v195, a51
	v_accvgpr_read_b32 v193, a53
	v_accvgpr_read_b32 v191, a55
	v_accvgpr_read_b32 v189, a57
	v_mov_b64_e32 v[76:77], v[240:241]
	v_mov_b64_e32 v[72:73], v[244:245]
	v_mov_b64_e32 v[68:69], v[248:249]
	v_accvgpr_read_b32 v67, a3
	v_accvgpr_read_b32 v194, a50
	v_accvgpr_read_b32 v192, a52
	v_accvgpr_read_b32 v190, a54
	v_accvgpr_read_b32 v188, a56
	v_mov_b64_e32 v[78:79], v[242:243]
	v_mov_b64_e32 v[74:75], v[246:247]
	v_mov_b64_e32 v[70:71], v[250:251]
	v_accvgpr_read_b32 v66, a2
	v_accvgpr_read_b32 v65, a1
	v_accvgpr_read_b32 v64, a0
	s_add_i32 s30, s26, 20
	v_readlane_b32 s28, v100, s30
	s_nop 1
	v_mad_i64_i32 v[136:137], s[12:13], s28, v130, v[96:97]
	global_load_dwordx4 v[240:243], v[136:137], off
	v_mad_i64_i32 v[136:137], s[12:13], s28, v130, v[98:99]
	global_load_dwordx2 a[50:51], v[136:137], off
	s_add_i32 s30, s26, 21
	v_readlane_b32 s28, v100, s30
	s_nop 1
	v_mad_i64_i32 v[136:137], s[12:13], s28, v130, v[96:97]
	global_load_dwordx4 v[244:247], v[136:137], off
	v_mad_i64_i32 v[136:137], s[12:13], s28, v130, v[98:99]
	global_load_dwordx2 a[52:53], v[136:137], off
	s_add_i32 s30, s26, 22
	v_readlane_b32 s28, v100, s30
	s_nop 1
	v_mad_i64_i32 v[136:137], s[12:13], s28, v130, v[96:97]
	global_load_dwordx4 v[248:251], v[136:137], off
	v_mad_i64_i32 v[136:137], s[12:13], s28, v130, v[98:99]
	global_load_dwordx2 a[54:55], v[136:137], off
	s_add_i32 s30, s26, 23
	v_readlane_b32 s28, v100, s30
	s_nop 1
	v_mad_i64_i32 v[136:137], s[12:13], s28, v130, v[96:97]
	global_load_dwordx4 a[0:3], v[136:137], off
	v_mad_i64_i32 v[136:137], s[12:13], s28, v130, v[98:99]
	global_load_dwordx2 a[56:57], v[136:137], off
	s_waitcnt vmcnt(24)
	v_accvgpr_read_b32 v187, a59
	v_accvgpr_read_b32 v185, a61
	v_accvgpr_read_b32 v183, a63
	v_accvgpr_read_b32 v181, a65
	v_accvgpr_read_b32 v63, a7
	v_accvgpr_read_b32 v59, a11
	v_accvgpr_read_b32 v55, a15
	v_accvgpr_read_b32 v51, a19
	v_accvgpr_read_b32 v186, a58
	v_accvgpr_read_b32 v184, a60
	v_accvgpr_read_b32 v182, a62
	v_accvgpr_read_b32 v180, a64
	v_accvgpr_read_b32 v62, a6
	v_accvgpr_read_b32 v61, a5
	v_accvgpr_read_b32 v60, a4
	v_accvgpr_read_b32 v58, a10
	v_accvgpr_read_b32 v57, a9
	v_accvgpr_read_b32 v56, a8
	v_accvgpr_read_b32 v54, a14
	v_accvgpr_read_b32 v53, a13
	v_accvgpr_read_b32 v52, a12
	v_accvgpr_read_b32 v50, a18
	v_accvgpr_read_b32 v49, a17
	v_accvgpr_read_b32 v48, a16
	s_add_i32 s30, s26, 24
	v_readlane_b32 s28, v100, s30
	s_nop 1
	v_mad_i64_i32 v[136:137], s[12:13], s28, v130, v[96:97]
	global_load_dwordx4 a[4:7], v[136:137], off
	v_mad_i64_i32 v[136:137], s[12:13], s28, v130, v[98:99]
	global_load_dwordx2 a[58:59], v[136:137], off
	s_add_i32 s30, s26, 25
	v_readlane_b32 s28, v100, s30
	s_nop 1
	v_mad_i64_i32 v[136:137], s[12:13], s28, v130, v[96:97]
	global_load_dwordx4 a[8:11], v[136:137], off
	v_mad_i64_i32 v[136:137], s[12:13], s28, v130, v[98:99]
	global_load_dwordx2 a[60:61], v[136:137], off
	s_add_i32 s30, s26, 26
	v_readlane_b32 s28, v100, s30
	s_nop 1
	v_mad_i64_i32 v[136:137], s[12:13], s28, v130, v[96:97]
	global_load_dwordx4 a[12:15], v[136:137], off
	v_mad_i64_i32 v[136:137], s[12:13], s28, v130, v[98:99]
	global_load_dwordx2 a[62:63], v[136:137], off
	s_add_i32 s30, s26, 27
	v_readlane_b32 s28, v100, s30
	s_nop 1
	v_mad_i64_i32 v[136:137], s[12:13], s28, v130, v[96:97]
	global_load_dwordx4 a[16:19], v[136:137], off
	v_mad_i64_i32 v[136:137], s[12:13], s28, v130, v[98:99]
	global_load_dwordx2 a[64:65], v[136:137], off
	s_waitcnt vmcnt(24)
	v_accvgpr_read_b32 v179, a67
	v_accvgpr_read_b32 v173, a41
	v_accvgpr_read_b32 v47, a27
	v_mov_b64_e32 v[40:41], v[220:221]
	v_mov_b64_e32 v[36:37], v[224:225]
	v_mov_b64_e32 v[32:33], v[228:229]
	v_accvgpr_read_b32 v178, a66
	v_mov_b64_e32 v[176:177], v[148:149]
	v_mov_b64_e32 v[174:175], v[252:253]
	v_accvgpr_read_b32 v172, a40
	v_accvgpr_read_b32 v46, a26
	v_accvgpr_read_b32 v45, a25
	v_accvgpr_read_b32 v44, a24
	v_mov_b64_e32 v[42:43], v[222:223]
	v_mov_b64_e32 v[38:39], v[226:227]
	v_mov_b64_e32 v[34:35], v[230:231]
	s_add_i32 s30, s26, 28
	v_readlane_b32 s28, v100, s30
	s_nop 1
	v_mad_i64_i32 v[136:137], s[12:13], s28, v130, v[96:97]
	global_load_dwordx4 a[24:27], v[136:137], off
	v_mad_i64_i32 v[136:137], s[12:13], s28, v130, v[98:99]
	global_load_dwordx2 a[66:67], v[136:137], off
	s_add_i32 s30, s26, 29
	v_readlane_b32 s28, v100, s30
	s_nop 1
	v_mad_i64_i32 v[136:137], s[12:13], s28, v130, v[96:97]
	global_load_dwordx4 v[220:223], v[136:137], off
	v_mad_i64_i32 v[136:137], s[12:13], s28, v130, v[98:99]
	global_load_dwordx2 v[148:149], v[136:137], off
	s_add_i32 s30, s26, 30
	v_readlane_b32 s28, v100, s30
	s_nop 1
	v_mad_i64_i32 v[136:137], s[12:13], s28, v130, v[96:97]
	global_load_dwordx4 v[224:227], v[136:137], off
	v_mad_i64_i32 v[136:137], s[12:13], s28, v130, v[98:99]
	global_load_dwordx2 v[252:253], v[136:137], off
	s_add_i32 s30, s26, 31
	v_readlane_b32 s28, v100, s30
	s_nop 1
	v_mad_i64_i32 v[136:137], s[12:13], s28, v130, v[96:97]
	global_load_dwordx4 v[228:231], v[136:137], off
	v_mad_i64_i32 v[136:137], s[12:13], s28, v130, v[98:99]
	global_load_dwordx2 a[40:41], v[136:137], off
	s_cmp_lg_u32 s26, 64
	s_cbranch_scc1 .LBB0_1389
	v_ashrrev_i32_e32 v119, 31, v118
	v_ashrrev_i32_e32 v121, 31, v120
	v_lshlrev_b64 v[164:165], 2, v[120:121]
	v_lshl_add_u64 v[168:169], s[4:5], 0, v[164:165]
	v_lshl_add_u64 v[164:165], s[16:17], 0, v[164:165]
	v_lshlrev_b64 v[166:167], 2, v[118:119]
	v_lshl_add_u64 v[170:171], s[4:5], 0, v[166:167]
	v_lshl_add_u64 v[166:167], s[16:17], 0, v[166:167]
	global_load_dword a68, v[170:171], off
	global_load_dword a69, v[168:169], off
	global_load_dword v117, v[166:167], off
	global_load_dword v105, v[164:165], off
	s_branch .LBB0_1389

.LBB0_2085:
	v_mov_b32_e32 v8, v128
	v_add_u32_e32 v9, 0xffffe000, v8
	v_lshrrev_b32_e32 v9, 12, v9
	v_add_u32_e32 v9, 1, v9
	v_cmp_lt_i32_e32 vcc, s29, v8
	v_lshlrev_b32_e32 v156, 16, v2
	v_and_b32_e32 v157, 0xffff0000, v2
	v_cndmask_b32_e32 v144, 0, v9, vcc
	v_accvgpr_read_b32 v9, a70
	v_add_u32_e32 v128, v8, v9
	v_min_i32_e32 v10, 0x5fff, v128
	v_lshlrev_b32_e32 v158, 16, v3
	v_and_b32_e32 v159, 0xffff0000, v3
	v_ashrrev_i32_e32 v9, 31, v8
	v_accvgpr_read_b32 v2, a72
	v_ashrrev_i32_e32 v11, 31, v10
	v_lshlrev_b32_e32 v152, 16, v0
	v_and_b32_e32 v153, 0xffff0000, v0
	v_lshlrev_b32_e32 v154, 16, v1
	v_and_b32_e32 v155, 0xffff0000, v1
	v_lshlrev_b64 v[0:1], 12, v[8:9]
	v_accvgpr_read_b32 v3, a73
	v_lshlrev_b64 v[12:13], 11, v[10:11]
	v_lshl_add_u64 v[160:161], v[2:3], 0, v[0:1]
	v_add_u32_e32 v0, 10, v144
	v_accvgpr_read_b32 v2, a230
	v_lshl_add_u64 v[12:13], v[104:105], 0, v[12:13]
	v_lshlrev_b64 v[10:11], 9, v[10:11]
	v_mad_u64_u32 v[0:1], s[12:13], v0, s27, v[114:115]
	v_accvgpr_read_b32 v3, a231
	global_load_dwordx4 a[28:31], v[12:13], off offset:16
	global_load_dwordx4 a[32:35], v[12:13], off
	v_lshl_add_u64 v[12:13], v[110:111], 0, v[10:11]
	v_lshl_add_u64 v[16:17], v[0:1], 0, v[2:3]
	global_load_dword v118, v[12:13], off
	global_load_dword v120, v[12:13], off offset:256
	v_lshl_add_u64 v[24:25], v[16:17], 0, s[14:15]
	v_add_co_u32_e32 v16, vcc, s33, v16
	v_lshl_add_u64 v[10:11], v[112:113], 0, v[10:11]
	s_nop 0
	v_addc_co_u32_e32 v17, vcc, 0, v17, vcc
	s_waitcnt vmcnt(6)
	v_mov_b32_e32 v32, v254
	s_waitcnt vmcnt(4)
	v_mov_b32_e32 v33, v147
	global_load_dword v147, v[10:11], off
	global_load_dword v254, v[10:11], off offset:256
	v_lshlrev_b32_e32 v124, 16, v4
	v_and_b32_e32 v125, 0xffff0000, v4
	v_lshlrev_b32_e32 v126, 16, v5
	v_and_b32_e32 v127, 0xffff0000, v5
	v_lshlrev_b32_e32 v148, 16, v6
	v_and_b32_e32 v149, 0xffff0000, v6
	v_lshlrev_b32_e32 v150, 16, v7
	v_and_b32_e32 v151, 0xffff0000, v7
	v_lshlrev_b64 v[122:123], 10, v[8:9]
	global_load_dwordx4 v[0:3], v[160:161], off offset:48
	global_load_dwordx4 v[4:7], v[160:161], off offset:32
	global_load_dwordx4 v[8:11], v[160:161], off offset:16
	global_load_dwordx4 v[12:15], v[160:161], off
	global_load_dwordx4 v[28:31], v[16:17], off
	s_nop 0
	global_load_dwordx4 v[16:19], v[24:25], off offset:48
	global_load_dwordx4 v[20:23], v[24:25], off offset:32
	s_nop 0
	global_load_dwordx4 v[24:27], v[24:25], off offset:16
	v_mul_f32_e32 v145, v33, v117
	v_mul_f32_e32 v146, v32, v103
	v_mov_b32_e32 v198, 0
	v_accvgpr_read_b32 v203, a43
	v_accvgpr_read_b32 v201, a45
	v_accvgpr_read_b32 v197, a47
	v_accvgpr_read_b32 v195, a49
	v_accvgpr_read_b32 v193, a51
	v_accvgpr_read_b32 v191, a53
	v_accvgpr_read_b32 v189, a55
	v_accvgpr_read_b32 v187, a57
	v_accvgpr_read_b32 v185, a59
	v_accvgpr_read_b32 v183, a61
	v_accvgpr_read_b32 v181, a63
	v_accvgpr_read_b32 v179, a65
	v_accvgpr_read_b32 v177, a67
	v_accvgpr_read_b32 v175, a37
	v_accvgpr_read_b32 v173, a39
	v_accvgpr_read_b32 v171, a41
	v_accvgpr_read_b32 v95, a23
	v_accvgpr_read_b32 v91, a27
	v_mov_b64_e32 v[84:85], v[230:231]
	v_mov_b64_e32 v[80:81], v[234:235]
	v_mov_b64_e32 v[76:77], v[238:239]
	v_mov_b64_e32 v[72:73], v[242:243]
	v_mov_b64_e32 v[68:69], v[246:247]
	v_mov_b64_e32 v[64:65], v[250:251]
	v_accvgpr_read_b32 v63, a3
	v_accvgpr_read_b32 v59, a7
	v_accvgpr_read_b32 v55, a11
	v_accvgpr_read_b32 v51, a15
	v_accvgpr_read_b32 v47, a19
	v_mov_b64_e32 v[40:41], v[218:219]
	v_mov_b64_e32 v[36:37], v[222:223]
	s_mov_b32 s26, 0
	v_accvgpr_read_b32 v202, a42
	v_accvgpr_read_b32 v200, a44
	v_accvgpr_read_b32 v196, a46
	v_accvgpr_read_b32 v194, a48
	v_accvgpr_read_b32 v192, a50
	v_accvgpr_read_b32 v190, a52
	v_accvgpr_read_b32 v188, a54
	v_accvgpr_read_b32 v186, a56
	v_accvgpr_read_b32 v184, a58
	v_accvgpr_read_b32 v182, a60
	v_accvgpr_read_b32 v180, a62
	v_accvgpr_read_b32 v178, a64
	v_accvgpr_read_b32 v176, a66
	v_accvgpr_read_b32 v174, a36
	v_accvgpr_read_b32 v172, a38
	v_accvgpr_read_b32 v170, a40
	v_accvgpr_read_b32 v94, a22
	v_accvgpr_read_b32 v93, a21
	v_accvgpr_read_b32 v92, a20
	v_accvgpr_read_b32 v90, a26
	v_accvgpr_read_b32 v89, a25
	v_accvgpr_read_b32 v88, a24
	v_mov_b64_e32 v[86:87], v[232:233]
	v_mov_b64_e32 v[32:33], v[226:227]
	v_mov_b64_e32 v[82:83], v[236:237]
	v_mov_b64_e32 v[78:79], v[240:241]
	v_mov_b64_e32 v[74:75], v[244:245]
	v_mov_b64_e32 v[70:71], v[248:249]
	v_mov_b64_e32 v[66:67], v[252:253]
	v_accvgpr_read_b32 v62, a2
	v_accvgpr_read_b32 v61, a1
	v_accvgpr_read_b32 v60, a0
	v_accvgpr_read_b32 v58, a6
	v_accvgpr_read_b32 v57, a5
	v_accvgpr_read_b32 v56, a4
	v_accvgpr_read_b32 v54, a10
	v_accvgpr_read_b32 v53, a9
	v_accvgpr_read_b32 v52, a8
	v_accvgpr_read_b32 v50, a14
	v_accvgpr_read_b32 v49, a13
	v_accvgpr_read_b32 v48, a12
	v_accvgpr_read_b32 v46, a18
	v_accvgpr_read_b32 v45, a17
	v_accvgpr_read_b32 v44, a16
	v_mov_b64_e32 v[42:43], v[220:221]
	v_mov_b64_e32 v[38:39], v[224:225]
	v_mov_b64_e32 v[34:35], v[228:229]
	v_mov_b32_e32 v199, v198
	v_mov_b32_e32 v216, v198
	v_mov_b32_e32 v217, v198
	v_mov_b32_e32 v214, v198
	v_mov_b32_e32 v215, v198
	v_mov_b32_e32 v212, v198
	v_mov_b32_e32 v213, v198
	v_mov_b32_e32 v210, v198
	v_mov_b32_e32 v211, v198
	v_mov_b32_e32 v208, v198
	v_mov_b32_e32 v209, v198
	v_mov_b32_e32 v206, v198
	v_mov_b32_e32 v207, v198
	v_mov_b32_e32 v204, v198
	v_mov_b32_e32 v205, v198
.LBB0_2086:
	s_add_i32 s58, s26, 16
	s_cmpk_gt_u32 s26, 0x6f
	s_cselect_b64 s[24:25], -1, 0
	s_cmpk_lt_u32 s26, 0x70
	s_cselect_b64 vcc, -1, 0
	s_bitcmp0_b32 s58, 6
	s_cselect_b64 s[12:13], -1, 0
	v_cndmask_b32_e64 v100, v116, v102, s[12:13]
	v_cndmask_b32_e32 v100, v118, v100, vcc
	s_nop 0
	v_readlane_b32 s28, v100, s58
	s_nop 1
	v_mad_i64_i32 v[218:219], s[12:13], s28, v130, v[96:97]
	global_load_dwordx4 a[20:23], v[218:219], off
	v_mad_i64_i32 v[218:219], s[12:13], s28, v130, v[98:99]
	s_add_i32 s12, s26, 17
	global_load_dwordx2 a[42:43], v[218:219], off
	s_nop 1
	v_readlane_b32 s28, v100, s12
	s_nop 1
	v_mad_i64_i32 v[218:219], s[12:13], s28, v130, v[96:97]
	global_load_dwordx4 a[24:27], v[218:219], off
	v_mad_i64_i32 v[218:219], s[12:13], s28, v130, v[98:99]
	s_add_i32 s12, s26, 18
	global_load_dwordx2 a[44:45], v[218:219], off
	s_nop 1
	v_readlane_b32 s28, v100, s12
	s_nop 1
	v_mad_i64_i32 v[218:219], s[12:13], s28, v130, v[96:97]
	global_load_dwordx4 v[230:233], v[218:219], off
	v_mad_i64_i32 v[218:219], s[12:13], s28, v130, v[98:99]
	s_add_i32 s12, s26, 19
	global_load_dwordx2 a[46:47], v[218:219], off
	s_nop 1
	v_readlane_b32 s28, v100, s12
	s_nop 1
	v_mad_i64_i32 v[218:219], s[12:13], s28, v130, v[96:97]
	global_load_dwordx4 v[234:237], v[218:219], off
	v_mad_i64_i32 v[218:219], s[12:13], s28, v130, v[98:99]
	s_add_i32 s12, s26, 20
	global_load_dwordx2 a[48:49], v[218:219], off
	s_nop 1
	v_readlane_b32 s28, v100, s12
	s_nop 1
	v_mad_i64_i32 v[218:219], s[12:13], s28, v130, v[96:97]
	global_load_dwordx4 v[238:241], v[218:219], off
	v_mad_i64_i32 v[218:219], s[12:13], s28, v130, v[98:99]
	s_add_i32 s12, s26, 21
	global_load_dwordx2 a[50:51], v[218:219], off
	s_nop 1
	v_readlane_b32 s28, v100, s12
	s_nop 1
	v_mad_i64_i32 v[218:219], s[12:13], s28, v130, v[96:97]
	global_load_dwordx4 v[242:245], v[218:219], off
	v_mad_i64_i32 v[218:219], s[12:13], s28, v130, v[98:99]
	s_add_i32 s12, s26, 22
	global_load_dwordx2 a[52:53], v[218:219], off
	s_nop 1
	v_readlane_b32 s28, v100, s12
	s_nop 1
	v_mad_i64_i32 v[218:219], s[12:13], s28, v130, v[96:97]
	global_load_dwordx4 v[246:249], v[218:219], off
	v_mad_i64_i32 v[218:219], s[12:13], s28, v130, v[98:99]
	s_add_i32 s12, s26, 23
	global_load_dwordx2 a[54:55], v[218:219], off
	s_nop 1
	v_readlane_b32 s28, v100, s12
	s_nop 1
	v_mad_i64_i32 v[218:219], s[12:13], s28, v130, v[96:97]
	global_load_dwordx4 v[250:253], v[218:219], off
	v_mad_i64_i32 v[218:219], s[12:13], s28, v130, v[98:99]
	s_add_i32 s12, s26, 24
	global_load_dwordx2 a[56:57], v[218:219], off
	s_nop 1
	v_readlane_b32 s28, v100, s12
	s_nop 1
	v_mad_i64_i32 v[218:219], s[12:13], s28, v130, v[96:97]
	global_load_dwordx4 a[0:3], v[218:219], off
	v_mad_i64_i32 v[218:219], s[12:13], s28, v130, v[98:99]
	s_add_i32 s12, s26, 25
	global_load_dwordx2 a[58:59], v[218:219], off
	s_nop 1
	v_readlane_b32 s28, v100, s12
	s_nop 1
	v_mad_i64_i32 v[218:219], s[12:13], s28, v130, v[96:97]
	global_load_dwordx4 a[4:7], v[218:219], off
	v_mad_i64_i32 v[218:219], s[12:13], s28, v130, v[98:99]
	s_add_i32 s12, s26, 26
	global_load_dwordx2 a[60:61], v[218:219], off
	s_nop 1
	v_readlane_b32 s28, v100, s12
	s_nop 1
	v_mad_i64_i32 v[218:219], s[12:13], s28, v130, v[96:97]
	global_load_dwordx4 a[8:11], v[218:219], off
	v_mad_i64_i32 v[218:219], s[12:13], s28, v130, v[98:99]
	s_add_i32 s12, s26, 27
	global_load_dwordx2 a[62:63], v[218:219], off
	s_nop 1
	v_readlane_b32 s28, v100, s12
	s_nop 1
	v_mad_i64_i32 v[218:219], s[12:13], s28, v130, v[96:97]
	global_load_dwordx4 a[12:15], v[218:219], off
	v_mad_i64_i32 v[218:219], s[12:13], s28, v130, v[98:99]
	s_add_i32 s12, s26, 28
	global_load_dwordx2 a[64:65], v[218:219], off
	s_nop 1
	v_readlane_b32 s28, v100, s12
	s_nop 1
	v_mad_i64_i32 v[218:219], s[12:13], s28, v130, v[96:97]
	global_load_dwordx4 a[16:19], v[218:219], off
	v_mad_i64_i32 v[218:219], s[12:13], s28, v130, v[98:99]
	s_add_i32 s12, s26, 29
	global_load_dwordx2 a[66:67], v[218:219], off
	s_nop 1
	v_readlane_b32 s28, v100, s12
	s_nop 1
	v_mad_i64_i32 v[222:223], s[12:13], s28, v130, v[98:99]
	global_load_dwordx2 a[36:37], v[222:223], off
	v_mad_i64_i32 v[218:219], s[12:13], s28, v130, v[96:97]
	s_add_i32 s12, s26, 30
	global_load_dwordx4 v[218:221], v[218:219], off
	s_nop 1
	v_readlane_b32 s28, v100, s12
	s_nop 1
	v_mad_i64_i32 v[222:223], s[12:13], s28, v130, v[96:97]
	v_mad_i64_i32 v[226:227], s[12:13], s28, v130, v[98:99]
	s_add_i32 s12, s26, 31
	global_load_dwordx4 v[222:225], v[222:223], off
	s_cmp_lg_u32 s26, 64
	s_nop 0
	v_readlane_b32 s28, v100, s12
	global_load_dwordx2 a[38:39], v[226:227], off
	s_nop 0
	v_mad_i64_i32 v[226:227], s[12:13], s28, v130, v[96:97]
	v_mad_i64_i32 v[100:101], s[12:13], s28, v130, v[98:99]
	global_load_dwordx4 v[226:229], v[226:227], off
	s_nop 0
	global_load_dwordx2 a[40:41], v[100:101], off
	s_cbranch_scc1 .LBB0_2088
	v_ashrrev_i32_e32 v119, 31, v118
	v_ashrrev_i32_e32 v121, 31, v120
	v_lshlrev_b64 v[162:163], 2, v[120:121]
	v_lshl_add_u64 v[166:167], s[4:5], 0, v[162:163]
	v_lshl_add_u64 v[162:163], s[16:17], 0, v[162:163]
	v_lshlrev_b64 v[164:165], 2, v[118:119]
	v_lshl_add_u64 v[168:169], s[4:5], 0, v[164:165]
	v_lshl_add_u64 v[164:165], s[16:17], 0, v[164:165]
	global_load_dword a68, v[168:169], off
	global_load_dword a69, v[166:167], off
	global_load_dword v117, v[164:165], off
	global_load_dword v103, v[162:163], off

.LBB0_2102:
	s_andn2_saveexec_b64 s[50:51], s[50:51]
	v_mul_f32_e32 v34, v33, v33
	v_fmamk_f32 v35, v34, 0xba1345e1, v139
	v_fmaak_f32 v35, v34, v35, 0xbcdac9b8
	v_fmaak_f32 v35, v34, v35, 0x3de703be
	v_fmaak_f32 v35, v34, v35, 0xbec09330
	v_fmaak_f32 v34, v34, v35, 0x3e0375d0
	v_fma_f32 v34, |v33|, v34, |v33|
	s_or_b64 exec, exec, s[50:51]
	v_cvt_scalef32_pk_f32_fp4 v[36:37], v202, 1.0
	v_pk_fma_f32 v[36:37], s[30:31], v[36:37], v[198:199] op_sel_hi:[0,1,1]
	v_cvt_scalef32_pk_f32_fp4 v[38:39], v202, 1.0 op_sel:[1,0,0]
	v_cvt_scalef32_pk_f32_fp4 v[52:53], v200, 1.0
	v_pk_fma_f32 v[38:39], s[30:31], v[38:39], v[216:217] op_sel_hi:[0,1,1]
	v_cvt_scalef32_pk_f32_fp4 v[40:41], v202, 1.0 op_sel:[0,1,0]
	v_pk_fma_f32 v[36:37], s[28:29], v[52:53], v[36:37] op_sel_hi:[0,1,1]
	v_cvt_scalef32_pk_f32_fp4 v[52:53], v200, 1.0 op_sel:[1,0,0]
	v_pk_fma_f32 v[40:41], s[30:31], v[40:41], v[214:215] op_sel_hi:[0,1,1]
	v_cvt_scalef32_pk_f32_fp4 v[42:43], v202, 1.0 op_sel:[1,1,0]
	v_pk_fma_f32 v[38:39], s[28:29], v[52:53], v[38:39] op_sel_hi:[0,1,1]
	v_cvt_scalef32_pk_f32_fp4 v[52:53], v200, 1.0 op_sel:[0,1,0]
	v_pk_fma_f32 v[42:43], s[30:31], v[42:43], v[212:213] op_sel_hi:[0,1,1]
	v_cvt_scalef32_pk_f32_fp4 v[44:45], v203, 1.0
	v_pk_fma_f32 v[40:41], s[28:29], v[52:53], v[40:41] op_sel_hi:[0,1,1]
	v_cvt_scalef32_pk_f32_fp4 v[52:53], v200, 1.0 op_sel:[1,1,0]
	v_pk_fma_f32 v[44:45], s[30:31], v[44:45], v[210:211] op_sel_hi:[0,1,1]
	v_cvt_scalef32_pk_f32_fp4 v[46:47], v203, 1.0 op_sel:[1,0,0]
	v_pk_fma_f32 v[42:43], s[28:29], v[52:53], v[42:43] op_sel_hi:[0,1,1]
	v_cvt_scalef32_pk_f32_fp4 v[52:53], v201, 1.0
	v_pk_fma_f32 v[46:47], s[30:31], v[46:47], v[208:209] op_sel_hi:[0,1,1]
	v_cvt_scalef32_pk_f32_fp4 v[48:49], v203, 1.0 op_sel:[0,1,0]
	v_pk_fma_f32 v[44:45], s[28:29], v[52:53], v[44:45] op_sel_hi:[0,1,1]
	v_cvt_scalef32_pk_f32_fp4 v[52:53], v201, 1.0 op_sel:[1,0,0]
	v_pk_fma_f32 v[48:49], s[30:31], v[48:49], v[206:207] op_sel_hi:[0,1,1]
	v_cvt_scalef32_pk_f32_fp4 v[50:51], v203, 1.0 op_sel:[1,1,0]
	v_pk_fma_f32 v[46:47], s[28:29], v[52:53], v[46:47] op_sel_hi:[0,1,1]
	v_cvt_scalef32_pk_f32_fp4 v[52:53], v201, 1.0 op_sel:[0,1,0]
	v_pk_fma_f32 v[50:51], s[30:31], v[50:51], v[204:205] op_sel_hi:[0,1,1]
	v_pk_fma_f32 v[48:49], s[28:29], v[52:53], v[48:49] op_sel_hi:[0,1,1]
	v_cvt_scalef32_pk_f32_fp4 v[52:53], v201, 1.0 op_sel:[1,1,0]
	v_pk_fma_f32 v[50:51], s[28:29], v[52:53], v[50:51] op_sel_hi:[0,1,1]
	v_cvt_scalef32_pk_f32_fp4 v[52:53], v196, 1.0
	v_pk_fma_f32 v[36:37], s[26:27], v[52:53], v[36:37] op_sel_hi:[0,1,1]
	v_cvt_scalef32_pk_f32_fp4 v[52:53], v196, 1.0 op_sel:[1,0,0]
	v_pk_fma_f32 v[38:39], s[26:27], v[52:53], v[38:39] op_sel_hi:[0,1,1]
	v_cvt_scalef32_pk_f32_fp4 v[52:53], v196, 1.0 op_sel:[0,1,0]
	v_pk_fma_f32 v[40:41], s[26:27], v[52:53], v[40:41] op_sel_hi:[0,1,1]
	v_cvt_scalef32_pk_f32_fp4 v[52:53], v196, 1.0 op_sel:[1,1,0]
	v_pk_fma_f32 v[42:43], s[26:27], v[52:53], v[42:43] op_sel_hi:[0,1,1]
	v_cvt_scalef32_pk_f32_fp4 v[52:53], v197, 1.0
	v_pk_fma_f32 v[44:45], s[26:27], v[52:53], v[44:45] op_sel_hi:[0,1,1]
	v_cvt_scalef32_pk_f32_fp4 v[52:53], v197, 1.0 op_sel:[1,0,0]
	v_pk_fma_f32 v[46:47], s[26:27], v[52:53], v[46:47] op_sel_hi:[0,1,1]
	v_cvt_scalef32_pk_f32_fp4 v[52:53], v197, 1.0 op_sel:[0,1,0]
	v_pk_fma_f32 v[48:49], s[26:27], v[52:53], v[48:49] op_sel_hi:[0,1,1]
	v_cvt_scalef32_pk_f32_fp4 v[52:53], v197, 1.0 op_sel:[1,1,0]
	v_pk_fma_f32 v[50:51], s[26:27], v[52:53], v[50:51] op_sel_hi:[0,1,1]
	v_cvt_scalef32_pk_f32_fp4 v[52:53], v194, 1.0
	v_pk_fma_f32 v[36:37], s[12:13], v[52:53], v[36:37] op_sel_hi:[0,1,1]
	v_cvt_scalef32_pk_f32_fp4 v[52:53], v194, 1.0 op_sel:[1,0,0]
	v_pk_fma_f32 v[38:39], s[12:13], v[52:53], v[38:39] op_sel_hi:[0,1,1]
	v_cvt_scalef32_pk_f32_fp4 v[52:53], v194, 1.0 op_sel:[0,1,0]
	v_pk_fma_f32 v[40:41], s[12:13], v[52:53], v[40:41] op_sel_hi:[0,1,1]
	v_cvt_scalef32_pk_f32_fp4 v[52:53], v194, 1.0 op_sel:[1,1,0]
	v_pk_fma_f32 v[42:43], s[12:13], v[52:53], v[42:43] op_sel_hi:[0,1,1]
	v_cvt_scalef32_pk_f32_fp4 v[52:53], v195, 1.0
	v_pk_fma_f32 v[44:45], s[12:13], v[52:53], v[44:45] op_sel_hi:[0,1,1]
	v_cvt_scalef32_pk_f32_fp4 v[52:53], v195, 1.0 op_sel:[1,0,0]
	v_pk_fma_f32 v[46:47], s[12:13], v[52:53], v[46:47] op_sel_hi:[0,1,1]
	v_cvt_scalef32_pk_f32_fp4 v[52:53], v195, 1.0 op_sel:[0,1,0]
	v_pk_fma_f32 v[48:49], s[12:13], v[52:53], v[48:49] op_sel_hi:[0,1,1]
	v_cvt_scalef32_pk_f32_fp4 v[52:53], v195, 1.0 op_sel:[1,1,0]
	v_pk_fma_f32 v[50:51], s[12:13], v[52:53], v[50:51] op_sel_hi:[0,1,1]
	v_cvt_scalef32_pk_f32_fp4 v[52:53], v192, 1.0
	v_pk_fma_f32 v[36:37], s[40:41], v[52:53], v[36:37] op_sel_hi:[0,1,1]
	v_cvt_scalef32_pk_f32_fp4 v[52:53], v192, 1.0 op_sel:[1,0,0]
	v_pk_fma_f32 v[38:39], s[40:41], v[52:53], v[38:39] op_sel_hi:[0,1,1]
	v_cvt_scalef32_pk_f32_fp4 v[52:53], v192, 1.0 op_sel:[0,1,0]
	v_pk_fma_f32 v[40:41], s[40:41], v[52:53], v[40:41] op_sel_hi:[0,1,1]
	v_cvt_scalef32_pk_f32_fp4 v[52:53], v192, 1.0 op_sel:[1,1,0]
	v_pk_fma_f32 v[42:43], s[40:41], v[52:53], v[42:43] op_sel_hi:[0,1,1]
	v_cvt_scalef32_pk_f32_fp4 v[52:53], v193, 1.0
	v_pk_fma_f32 v[44:45], s[40:41], v[52:53], v[44:45] op_sel_hi:[0,1,1]
	v_cvt_scalef32_pk_f32_fp4 v[52:53], v193, 1.0 op_sel:[1,0,0]
	v_pk_fma_f32 v[46:47], s[40:41], v[52:53], v[46:47] op_sel_hi:[0,1,1]
	v_cvt_scalef32_pk_f32_fp4 v[52:53], v193, 1.0 op_sel:[0,1,0]
	v_pk_fma_f32 v[48:49], s[40:41], v[52:53], v[48:49] op_sel_hi:[0,1,1]
	v_cvt_scalef32_pk_f32_fp4 v[52:53], v193, 1.0 op_sel:[1,1,0]
	v_pk_fma_f32 v[50:51], s[40:41], v[52:53], v[50:51] op_sel_hi:[0,1,1]
	v_cvt_scalef32_pk_f32_fp4 v[52:53], v190, 1.0
	v_pk_fma_f32 v[36:37], s[38:39], v[52:53], v[36:37] op_sel_hi:[0,1,1]
	v_cvt_scalef32_pk_f32_fp4 v[52:53], v190, 1.0 op_sel:[1,0,0]
	v_pk_fma_f32 v[38:39], s[38:39], v[52:53], v[38:39] op_sel_hi:[0,1,1]
	v_cvt_scalef32_pk_f32_fp4 v[52:53], v190, 1.0 op_sel:[0,1,0]
	v_pk_fma_f32 v[40:41], s[38:39], v[52:53], v[40:41] op_sel_hi:[0,1,1]
	v_cvt_scalef32_pk_f32_fp4 v[52:53], v190, 1.0 op_sel:[1,1,0]
	v_pk_fma_f32 v[42:43], s[38:39], v[52:53], v[42:43] op_sel_hi:[0,1,1]
	v_cvt_scalef32_pk_f32_fp4 v[52:53], v191, 1.0
	v_pk_fma_f32 v[44:45], s[38:39], v[52:53], v[44:45] op_sel_hi:[0,1,1]
	v_cvt_scalef32_pk_f32_fp4 v[52:53], v191, 1.0 op_sel:[1,0,0]
	v_pk_fma_f32 v[46:47], s[38:39], v[52:53], v[46:47] op_sel_hi:[0,1,1]
	v_cvt_scalef32_pk_f32_fp4 v[52:53], v191, 1.0 op_sel:[0,1,0]
	v_pk_fma_f32 v[48:49], s[38:39], v[52:53], v[48:49] op_sel_hi:[0,1,1]
	v_cvt_scalef32_pk_f32_fp4 v[52:53], v191, 1.0 op_sel:[1,1,0]
	v_pk_fma_f32 v[50:51], s[38:39], v[52:53], v[50:51] op_sel_hi:[0,1,1]
	v_cvt_scalef32_pk_f32_fp4 v[52:53], v188, 1.0
	v_pk_fma_f32 v[36:37], s[36:37], v[52:53], v[36:37] op_sel_hi:[0,1,1]
	v_cvt_scalef32_pk_f32_fp4 v[52:53], v188, 1.0 op_sel:[1,0,0]
	v_pk_fma_f32 v[38:39], s[36:37], v[52:53], v[38:39] op_sel_hi:[0,1,1]
	v_cvt_scalef32_pk_f32_fp4 v[52:53], v188, 1.0 op_sel:[0,1,0]
	v_pk_fma_f32 v[40:41], s[36:37], v[52:53], v[40:41] op_sel_hi:[0,1,1]
	v_cvt_scalef32_pk_f32_fp4 v[52:53], v188, 1.0 op_sel:[1,1,0]
	v_pk_fma_f32 v[42:43], s[36:37], v[52:53], v[42:43] op_sel_hi:[0,1,1]
	v_cvt_scalef32_pk_f32_fp4 v[52:53], v189, 1.0
	v_pk_fma_f32 v[44:45], s[36:37], v[52:53], v[44:45] op_sel_hi:[0,1,1]
	v_cvt_scalef32_pk_f32_fp4 v[52:53], v189, 1.0 op_sel:[1,0,0]
	v_pk_fma_f32 v[46:47], s[36:37], v[52:53], v[46:47] op_sel_hi:[0,1,1]
	v_cvt_scalef32_pk_f32_fp4 v[52:53], v189, 1.0 op_sel:[0,1,0]
	v_pk_fma_f32 v[48:49], s[36:37], v[52:53], v[48:49] op_sel_hi:[0,1,1]
	v_cvt_scalef32_pk_f32_fp4 v[52:53], v189, 1.0 op_sel:[1,1,0]
	v_pk_fma_f32 v[50:51], s[36:37], v[52:53], v[50:51] op_sel_hi:[0,1,1]
	v_cvt_scalef32_pk_f32_fp4 v[52:53], v186, 1.0
	v_pk_fma_f32 v[36:37], s[34:35], v[52:53], v[36:37] op_sel_hi:[0,1,1]
	v_cvt_scalef32_pk_f32_fp4 v[52:53], v186, 1.0 op_sel:[1,0,0]
	v_pk_fma_f32 v[38:39], s[34:35], v[52:53], v[38:39] op_sel_hi:[0,1,1]
	v_cvt_scalef32_pk_f32_fp4 v[52:53], v186, 1.0 op_sel:[0,1,0]
	v_pk_fma_f32 v[40:41], s[34:35], v[52:53], v[40:41] op_sel_hi:[0,1,1]
	v_cvt_scalef32_pk_f32_fp4 v[52:53], v186, 1.0 op_sel:[1,1,0]
	v_pk_fma_f32 v[42:43], s[34:35], v[52:53], v[42:43] op_sel_hi:[0,1,1]
	v_cvt_scalef32_pk_f32_fp4 v[52:53], v187, 1.0
	v_pk_fma_f32 v[44:45], s[34:35], v[52:53], v[44:45] op_sel_hi:[0,1,1]
	v_cvt_scalef32_pk_f32_fp4 v[52:53], v187, 1.0 op_sel:[1,0,0]
	v_pk_fma_f32 v[46:47], s[34:35], v[52:53], v[46:47] op_sel_hi:[0,1,1]
	v_cvt_scalef32_pk_f32_fp4 v[52:53], v187, 1.0 op_sel:[0,1,0]
	v_pk_fma_f32 v[48:49], s[34:35], v[52:53], v[48:49] op_sel_hi:[0,1,1]
	v_cvt_scalef32_pk_f32_fp4 v[52:53], v187, 1.0 op_sel:[1,1,0]
	v_pk_fma_f32 v[50:51], s[34:35], v[52:53], v[50:51] op_sel_hi:[0,1,1]
	v_cvt_scalef32_pk_f32_fp4 v[52:53], v184, 1.0
	v_pk_fma_f32 v[36:37], s[48:49], v[52:53], v[36:37] op_sel_hi:[0,1,1]
	v_cvt_scalef32_pk_f32_fp4 v[52:53], v184, 1.0 op_sel:[1,0,0]
	v_pk_fma_f32 v[38:39], s[48:49], v[52:53], v[38:39] op_sel_hi:[0,1,1]
	v_cvt_scalef32_pk_f32_fp4 v[52:53], v184, 1.0 op_sel:[0,1,0]
	v_pk_fma_f32 v[40:41], s[48:49], v[52:53], v[40:41] op_sel_hi:[0,1,1]
	v_cvt_scalef32_pk_f32_fp4 v[52:53], v184, 1.0 op_sel:[1,1,0]
	v_pk_fma_f32 v[42:43], s[48:49], v[52:53], v[42:43] op_sel_hi:[0,1,1]
	v_cvt_scalef32_pk_f32_fp4 v[52:53], v185, 1.0
	v_pk_fma_f32 v[44:45], s[48:49], v[52:53], v[44:45] op_sel_hi:[0,1,1]
	v_cvt_scalef32_pk_f32_fp4 v[52:53], v185, 1.0 op_sel:[1,0,0]
	v_pk_fma_f32 v[46:47], s[48:49], v[52:53], v[46:47] op_sel_hi:[0,1,1]
	v_cvt_scalef32_pk_f32_fp4 v[52:53], v185, 1.0 op_sel:[0,1,0]
	v_pk_fma_f32 v[48:49], s[48:49], v[52:53], v[48:49] op_sel_hi:[0,1,1]
	v_cvt_scalef32_pk_f32_fp4 v[52:53], v185, 1.0 op_sel:[1,1,0]
	v_pk_fma_f32 v[50:51], s[48:49], v[52:53], v[50:51] op_sel_hi:[0,1,1]
	v_cvt_scalef32_pk_f32_fp4 v[52:53], v182, 1.0
	v_pk_fma_f32 v[36:37], s[46:47], v[52:53], v[36:37] op_sel_hi:[0,1,1]
	v_cvt_scalef32_pk_f32_fp4 v[52:53], v182, 1.0 op_sel:[1,0,0]
	v_pk_fma_f32 v[38:39], s[46:47], v[52:53], v[38:39] op_sel_hi:[0,1,1]
	v_cvt_scalef32_pk_f32_fp4 v[52:53], v182, 1.0 op_sel:[0,1,0]
	v_pk_fma_f32 v[40:41], s[46:47], v[52:53], v[40:41] op_sel_hi:[0,1,1]
	v_cvt_scalef32_pk_f32_fp4 v[52:53], v182, 1.0 op_sel:[1,1,0]
	v_pk_fma_f32 v[42:43], s[46:47], v[52:53], v[42:43] op_sel_hi:[0,1,1]
	v_cvt_scalef32_pk_f32_fp4 v[52:53], v183, 1.0
	v_pk_fma_f32 v[44:45], s[46:47], v[52:53], v[44:45] op_sel_hi:[0,1,1]
	v_cvt_scalef32_pk_f32_fp4 v[52:53], v183, 1.0 op_sel:[1,0,0]
	v_pk_fma_f32 v[46:47], s[46:47], v[52:53], v[46:47] op_sel_hi:[0,1,1]
	v_cvt_scalef32_pk_f32_fp4 v[52:53], v183, 1.0 op_sel:[0,1,0]
	v_pk_fma_f32 v[48:49], s[46:47], v[52:53], v[48:49] op_sel_hi:[0,1,1]
	v_cvt_scalef32_pk_f32_fp4 v[52:53], v183, 1.0 op_sel:[1,1,0]
	v_pk_fma_f32 v[50:51], s[46:47], v[52:53], v[50:51] op_sel_hi:[0,1,1]
	v_cvt_scalef32_pk_f32_fp4 v[52:53], v180, 1.0
	v_pk_fma_f32 v[36:37], s[44:45], v[52:53], v[36:37] op_sel_hi:[0,1,1]
	v_cvt_scalef32_pk_f32_fp4 v[52:53], v180, 1.0 op_sel:[1,0,0]
	v_pk_fma_f32 v[38:39], s[44:45], v[52:53], v[38:39] op_sel_hi:[0,1,1]
	v_cvt_scalef32_pk_f32_fp4 v[52:53], v180, 1.0 op_sel:[0,1,0]
	v_pk_fma_f32 v[40:41], s[44:45], v[52:53], v[40:41] op_sel_hi:[0,1,1]
	v_cvt_scalef32_pk_f32_fp4 v[52:53], v180, 1.0 op_sel:[1,1,0]
	v_pk_fma_f32 v[42:43], s[44:45], v[52:53], v[42:43] op_sel_hi:[0,1,1]
	v_cvt_scalef32_pk_f32_fp4 v[52:53], v181, 1.0
	v_pk_fma_f32 v[44:45], s[44:45], v[52:53], v[44:45] op_sel_hi:[0,1,1]
	v_cvt_scalef32_pk_f32_fp4 v[52:53], v181, 1.0 op_sel:[1,0,0]
	v_pk_fma_f32 v[46:47], s[44:45], v[52:53], v[46:47] op_sel_hi:[0,1,1]
	v_cvt_scalef32_pk_f32_fp4 v[52:53], v181, 1.0 op_sel:[0,1,0]
	v_pk_fma_f32 v[48:49], s[44:45], v[52:53], v[48:49] op_sel_hi:[0,1,1]
	v_cvt_scalef32_pk_f32_fp4 v[52:53], v181, 1.0 op_sel:[1,1,0]
	v_pk_fma_f32 v[50:51], s[44:45], v[52:53], v[50:51] op_sel_hi:[0,1,1]
	v_cvt_scalef32_pk_f32_fp4 v[52:53], v178, 1.0
	v_pk_fma_f32 v[36:37], s[42:43], v[52:53], v[36:37] op_sel_hi:[0,1,1]
	v_cvt_scalef32_pk_f32_fp4 v[52:53], v178, 1.0 op_sel:[1,0,0]
	v_pk_fma_f32 v[38:39], s[42:43], v[52:53], v[38:39] op_sel_hi:[0,1,1]
	v_cvt_scalef32_pk_f32_fp4 v[52:53], v178, 1.0 op_sel:[0,1,0]
	v_pk_fma_f32 v[40:41], s[42:43], v[52:53], v[40:41] op_sel_hi:[0,1,1]
	v_cvt_scalef32_pk_f32_fp4 v[52:53], v178, 1.0 op_sel:[1,1,0]
	v_pk_fma_f32 v[42:43], s[42:43], v[52:53], v[42:43] op_sel_hi:[0,1,1]
	v_cvt_scalef32_pk_f32_fp4 v[52:53], v179, 1.0
	v_pk_fma_f32 v[44:45], s[42:43], v[52:53], v[44:45] op_sel_hi:[0,1,1]
	v_cvt_scalef32_pk_f32_fp4 v[52:53], v179, 1.0 op_sel:[1,0,0]
	v_pk_fma_f32 v[46:47], s[42:43], v[52:53], v[46:47] op_sel_hi:[0,1,1]
	v_cvt_scalef32_pk_f32_fp4 v[52:53], v179, 1.0 op_sel:[0,1,0]
	v_pk_fma_f32 v[48:49], s[42:43], v[52:53], v[48:49] op_sel_hi:[0,1,1]
	v_cvt_scalef32_pk_f32_fp4 v[52:53], v179, 1.0 op_sel:[1,1,0]
	v_pk_fma_f32 v[50:51], s[42:43], v[52:53], v[50:51] op_sel_hi:[0,1,1]
	v_mov_b32_e32 v35, s59
	v_mov_b32_e32 v52, s35
	v_cndmask_b32_e64 v35, v35, v52, s[10:11]
	v_mov_b32_e32 v52, s43
	v_bfi_b32 v33, s55, v34, v33
	v_cndmask_b32_e64 v35, v35, v52, s[8:9]
	v_mov_b32_e32 v52, s13
	v_mul_f32_e32 v32, 0.5, v32
	v_add_f32_e32 v33, 1.0, v33
	v_cndmask_b32_e64 v35, v35, v52, s[6:7]
	v_mul_f32_e32 v32, v32, v33
	v_mul_f32_e32 v32, v35, v32
	v_cvt_scalef32_pk_f32_fp4 v[34:35], v176, 1.0 op_sel:[1,0,0]
	v_readlane_b32 s12, v32, 0
	v_readlane_b32 s26, v32, 32
	v_readlane_b32 s28, v32, 16
	v_readlane_b32 s30, v32, 48
	v_cvt_scalef32_pk_f32_fp4 v[32:33], v176, 1.0
	v_pk_fma_f32 v[32:33], s[12:13], v[32:33], v[36:37] op_sel_hi:[0,1,1]
	v_cvt_scalef32_pk_f32_fp4 v[36:37], v176, 1.0 op_sel:[0,1,0]
	v_pk_fma_f32 v[36:37], s[12:13], v[36:37], v[40:41] op_sel_hi:[0,1,1]
	v_cvt_scalef32_pk_f32_fp4 v[40:41], v177, 1.0
	v_pk_fma_f32 v[40:41], s[12:13], v[40:41], v[44:45] op_sel_hi:[0,1,1]
	v_cvt_scalef32_pk_f32_fp4 v[44:45], v177, 1.0 op_sel:[0,1,0]
	v_pk_fma_f32 v[44:45], s[12:13], v[44:45], v[48:49] op_sel_hi:[0,1,1]
	v_cvt_scalef32_pk_f32_fp4 v[48:49], v174, 1.0
	v_pk_fma_f32 v[34:35], s[12:13], v[34:35], v[38:39] op_sel_hi:[0,1,1]
	v_pk_fma_f32 v[32:33], s[26:27], v[48:49], v[32:33] op_sel_hi:[0,1,1]
	v_cvt_scalef32_pk_f32_fp4 v[48:49], v174, 1.0 op_sel:[1,0,0]
	v_cvt_scalef32_pk_f32_fp4 v[38:39], v176, 1.0 op_sel:[1,1,0]
	v_pk_fma_f32 v[34:35], s[26:27], v[48:49], v[34:35] op_sel_hi:[0,1,1]
	v_cvt_scalef32_pk_f32_fp4 v[48:49], v174, 1.0 op_sel:[0,1,0]
	v_pk_fma_f32 v[38:39], s[12:13], v[38:39], v[42:43] op_sel_hi:[0,1,1]
	v_pk_fma_f32 v[36:37], s[26:27], v[48:49], v[36:37] op_sel_hi:[0,1,1]
	v_cvt_scalef32_pk_f32_fp4 v[48:49], v174, 1.0 op_sel:[1,1,0]
	v_cvt_scalef32_pk_f32_fp4 v[42:43], v177, 1.0 op_sel:[1,0,0]
	v_pk_fma_f32 v[38:39], s[26:27], v[48:49], v[38:39] op_sel_hi:[0,1,1]
	v_cvt_scalef32_pk_f32_fp4 v[48:49], v175, 1.0
	v_pk_fma_f32 v[42:43], s[12:13], v[42:43], v[46:47] op_sel_hi:[0,1,1]
	v_pk_fma_f32 v[40:41], s[26:27], v[48:49], v[40:41] op_sel_hi:[0,1,1]
	v_cvt_scalef32_pk_f32_fp4 v[48:49], v175, 1.0 op_sel:[1,0,0]
	v_cvt_scalef32_pk_f32_fp4 v[46:47], v177, 1.0 op_sel:[1,1,0]
	v_pk_fma_f32 v[42:43], s[26:27], v[48:49], v[42:43] op_sel_hi:[0,1,1]
	v_cvt_scalef32_pk_f32_fp4 v[48:49], v175, 1.0 op_sel:[0,1,0]
	v_pk_fma_f32 v[46:47], s[12:13], v[46:47], v[50:51] op_sel_hi:[0,1,1]
	v_pk_fma_f32 v[44:45], s[26:27], v[48:49], v[44:45] op_sel_hi:[0,1,1]
	v_cvt_scalef32_pk_f32_fp4 v[48:49], v175, 1.0 op_sel:[1,1,0]
	v_pk_fma_f32 v[46:47], s[26:27], v[48:49], v[46:47] op_sel_hi:[0,1,1]
	v_cvt_scalef32_pk_f32_fp4 v[48:49], v172, 1.0
	v_pk_fma_f32 v[32:33], s[28:29], v[48:49], v[32:33] op_sel_hi:[0,1,1]
	v_cvt_scalef32_pk_f32_fp4 v[48:49], v172, 1.0 op_sel:[1,0,0]
	v_pk_fma_f32 v[34:35], s[28:29], v[48:49], v[34:35] op_sel_hi:[0,1,1]
	v_cvt_scalef32_pk_f32_fp4 v[48:49], v172, 1.0 op_sel:[0,1,0]
	v_pk_fma_f32 v[36:37], s[28:29], v[48:49], v[36:37] op_sel_hi:[0,1,1]
	v_cvt_scalef32_pk_f32_fp4 v[48:49], v172, 1.0 op_sel:[1,1,0]
	v_pk_fma_f32 v[38:39], s[28:29], v[48:49], v[38:39] op_sel_hi:[0,1,1]
	v_cvt_scalef32_pk_f32_fp4 v[48:49], v173, 1.0
	v_pk_fma_f32 v[40:41], s[28:29], v[48:49], v[40:41] op_sel_hi:[0,1,1]
	v_cvt_scalef32_pk_f32_fp4 v[48:49], v173, 1.0 op_sel:[1,0,0]
	v_pk_fma_f32 v[42:43], s[28:29], v[48:49], v[42:43] op_sel_hi:[0,1,1]
	v_cvt_scalef32_pk_f32_fp4 v[48:49], v173, 1.0 op_sel:[0,1,0]
	v_pk_fma_f32 v[44:45], s[28:29], v[48:49], v[44:45] op_sel_hi:[0,1,1]
	v_cvt_scalef32_pk_f32_fp4 v[48:49], v173, 1.0 op_sel:[1,1,0]
	v_pk_fma_f32 v[46:47], s[28:29], v[48:49], v[46:47] op_sel_hi:[0,1,1]
	v_cvt_scalef32_pk_f32_fp4 v[48:49], v170, 1.0
	v_pk_fma_f32 v[198:199], s[30:31], v[48:49], v[32:33] op_sel_hi:[0,1,1]
	v_cvt_scalef32_pk_f32_fp4 v[32:33], v170, 1.0 op_sel:[1,0,0]
	v_pk_fma_f32 v[216:217], s[30:31], v[32:33], v[34:35] op_sel_hi:[0,1,1]
	v_cvt_scalef32_pk_f32_fp4 v[32:33], v170, 1.0 op_sel:[0,1,0]
	v_pk_fma_f32 v[214:215], s[30:31], v[32:33], v[36:37] op_sel_hi:[0,1,1]
	v_cvt_scalef32_pk_f32_fp4 v[32:33], v170, 1.0 op_sel:[1,1,0]
	v_pk_fma_f32 v[212:213], s[30:31], v[32:33], v[38:39] op_sel_hi:[0,1,1]
	v_cvt_scalef32_pk_f32_fp4 v[32:33], v171, 1.0
	v_pk_fma_f32 v[210:211], s[30:31], v[32:33], v[40:41] op_sel_hi:[0,1,1]
	v_cvt_scalef32_pk_f32_fp4 v[32:33], v171, 1.0 op_sel:[1,0,0]
	v_pk_fma_f32 v[208:209], s[30:31], v[32:33], v[42:43] op_sel_hi:[0,1,1]
	v_cvt_scalef32_pk_f32_fp4 v[32:33], v171, 1.0 op_sel:[0,1,0]
	v_pk_fma_f32 v[206:207], s[30:31], v[32:33], v[44:45] op_sel_hi:[0,1,1]
	v_cvt_scalef32_pk_f32_fp4 v[32:33], v171, 1.0 op_sel:[1,1,0]
	v_pk_fma_f32 v[204:205], s[30:31], v[32:33], v[46:47] op_sel_hi:[0,1,1]
	s_and_b64 vcc, exec, s[24:25]
	s_cbranch_vccnz .LBB0_2084
	s_mov_b32 s26, s58
	s_add_i32 s58, s26, 16
	s_cmpk_gt_u32 s26, 0x6f
	s_cselect_b64 s[24:25], -1, 0
	s_cmpk_lt_u32 s26, 0x70
	s_cselect_b64 vcc, -1, 0
	s_bitcmp0_b32 s58, 6
	s_cselect_b64 s[12:13], -1, 0
	v_cndmask_b32_e64 v100, v116, v102, s[12:13]
	v_cndmask_b32_e32 v100, v118, v100, vcc
	s_nop 0
	s_waitcnt vmcnt(24)
	v_accvgpr_read_b32 v203, a43
	v_accvgpr_read_b32 v201, a45
	v_accvgpr_read_b32 v197, a47
	v_accvgpr_read_b32 v195, a49
	v_accvgpr_read_b32 v95, a23
	v_accvgpr_read_b32 v91, a27
	v_mov_b64_e32 v[84:85], v[230:231]
	v_mov_b64_e32 v[80:81], v[234:235]
	v_accvgpr_read_b32 v202, a42
	v_accvgpr_read_b32 v200, a44
	v_accvgpr_read_b32 v196, a46
	v_accvgpr_read_b32 v194, a48
	v_accvgpr_read_b32 v94, a22
	v_accvgpr_read_b32 v93, a21
	v_accvgpr_read_b32 v92, a20
	v_accvgpr_read_b32 v90, a26
	v_accvgpr_read_b32 v89, a25
	v_accvgpr_read_b32 v88, a24
	v_mov_b64_e32 v[86:87], v[232:233]
	v_mov_b64_e32 v[82:83], v[236:237]
	s_add_i32 s30, s26, 16
	v_readlane_b32 s28, v100, s30
	s_nop 1
	v_mad_i64_i32 v[136:137], s[12:13], s28, v130, v[96:97]
	global_load_dwordx4 a[20:23], v[136:137], off
	v_mad_i64_i32 v[136:137], s[12:13], s28, v130, v[98:99]
	global_load_dwordx2 a[42:43], v[136:137], off
	s_add_i32 s30, s26, 17
	v_readlane_b32 s28, v100, s30
	s_nop 1
	v_mad_i64_i32 v[136:137], s[12:13], s28, v130, v[96:97]
	global_load_dwordx4 a[24:27], v[136:137], off
	v_mad_i64_i32 v[136:137], s[12:13], s28, v130, v[98:99]
	global_load_dwordx2 a[44:45], v[136:137], off
	s_add_i32 s30, s26, 18
	v_readlane_b32 s28, v100, s30
	s_nop 1
	v_mad_i64_i32 v[136:137], s[12:13], s28, v130, v[96:97]
	global_load_dwordx4 v[230:233], v[136:137], off
	v_mad_i64_i32 v[136:137], s[12:13], s28, v130, v[98:99]
	global_load_dwordx2 a[46:47], v[136:137], off
	s_add_i32 s30, s26, 19
	v_readlane_b32 s28, v100, s30
	s_nop 1
	v_mad_i64_i32 v[136:137], s[12:13], s28, v130, v[96:97]
	global_load_dwordx4 v[234:237], v[136:137], off
	v_mad_i64_i32 v[136:137], s[12:13], s28, v130, v[98:99]
	global_load_dwordx2 a[48:49], v[136:137], off
	s_waitcnt vmcnt(24)
	v_accvgpr_read_b32 v193, a51
	v_accvgpr_read_b32 v191, a53
	v_accvgpr_read_b32 v189, a55
	v_accvgpr_read_b32 v187, a57
	v_mov_b64_e32 v[76:77], v[238:239]
	v_mov_b64_e32 v[72:73], v[242:243]
	v_mov_b64_e32 v[68:69], v[246:247]
	v_mov_b64_e32 v[64:65], v[250:251]
	v_accvgpr_read_b32 v192, a50
	v_accvgpr_read_b32 v190, a52
	v_accvgpr_read_b32 v188, a54
	v_accvgpr_read_b32 v186, a56
	v_mov_b64_e32 v[78:79], v[240:241]
	v_mov_b64_e32 v[74:75], v[244:245]
	v_mov_b64_e32 v[70:71], v[248:249]
	v_mov_b64_e32 v[66:67], v[252:253]
	s_add_i32 s30, s26, 20
	v_readlane_b32 s28, v100, s30
	s_nop 1
	v_mad_i64_i32 v[136:137], s[12:13], s28, v130, v[96:97]
	global_load_dwordx4 v[238:241], v[136:137], off
	v_mad_i64_i32 v[136:137], s[12:13], s28, v130, v[98:99]
	global_load_dwordx2 a[50:51], v[136:137], off
	s_add_i32 s30, s26, 21
	v_readlane_b32 s28, v100, s30
	s_nop 1
	v_mad_i64_i32 v[136:137], s[12:13], s28, v130, v[96:97]
	global_load_dwordx4 v[242:245], v[136:137], off
	v_mad_i64_i32 v[136:137], s[12:13], s28, v130, v[98:99]
	global_load_dwordx2 a[52:53], v[136:137], off
	s_add_i32 s30, s26, 22
	v_readlane_b32 s28, v100, s30
	s_nop 1
	v_mad_i64_i32 v[136:137], s[12:13], s28, v130, v[96:97]
	global_load_dwordx4 v[246:249], v[136:137], off
	v_mad_i64_i32 v[136:137], s[12:13], s28, v130, v[98:99]
	global_load_dwordx2 a[54:55], v[136:137], off
	s_add_i32 s30, s26, 23
	v_readlane_b32 s28, v100, s30
	s_nop 1
	v_mad_i64_i32 v[136:137], s[12:13], s28, v130, v[96:97]
	global_load_dwordx4 v[250:253], v[136:137], off
	v_mad_i64_i32 v[136:137], s[12:13], s28, v130, v[98:99]
	global_load_dwordx2 a[56:57], v[136:137], off
	s_waitcnt vmcnt(24)
	v_accvgpr_read_b32 v185, a59
	v_accvgpr_read_b32 v183, a61
	v_accvgpr_read_b32 v181, a63
	v_accvgpr_read_b32 v179, a65
	v_accvgpr_read_b32 v63, a3
	v_accvgpr_read_b32 v59, a7
	v_accvgpr_read_b32 v55, a11
	v_accvgpr_read_b32 v51, a15
	v_accvgpr_read_b32 v184, a58
	v_accvgpr_read_b32 v182, a60
	v_accvgpr_read_b32 v180, a62
	v_accvgpr_read_b32 v178, a64
	v_accvgpr_read_b32 v62, a2
	v_accvgpr_read_b32 v61, a1
	v_accvgpr_read_b32 v60, a0
	v_accvgpr_read_b32 v58, a6
	v_accvgpr_read_b32 v57, a5
	v_accvgpr_read_b32 v56, a4
	v_accvgpr_read_b32 v54, a10
	v_accvgpr_read_b32 v53, a9
	v_accvgpr_read_b32 v52, a8
	v_accvgpr_read_b32 v50, a14
	v_accvgpr_read_b32 v49, a13
	v_accvgpr_read_b32 v48, a12
	s_add_i32 s30, s26, 24
	v_readlane_b32 s28, v100, s30
	s_nop 1
	v_mad_i64_i32 v[136:137], s[12:13], s28, v130, v[96:97]
	global_load_dwordx4 a[0:3], v[136:137], off
	v_mad_i64_i32 v[136:137], s[12:13], s28, v130, v[98:99]
	global_load_dwordx2 a[58:59], v[136:137], off
	s_add_i32 s30, s26, 25
	v_readlane_b32 s28, v100, s30
	s_nop 1
	v_mad_i64_i32 v[136:137], s[12:13], s28, v130, v[96:97]
	global_load_dwordx4 a[4:7], v[136:137], off
	v_mad_i64_i32 v[136:137], s[12:13], s28, v130, v[98:99]
	global_load_dwordx2 a[60:61], v[136:137], off
	s_add_i32 s30, s26, 26
	v_readlane_b32 s28, v100, s30
	s_nop 1
	v_mad_i64_i32 v[136:137], s[12:13], s28, v130, v[96:97]
	global_load_dwordx4 a[8:11], v[136:137], off
	v_mad_i64_i32 v[136:137], s[12:13], s28, v130, v[98:99]
	global_load_dwordx2 a[62:63], v[136:137], off
	s_add_i32 s30, s26, 27
	v_readlane_b32 s28, v100, s30
	s_nop 1
	v_mad_i64_i32 v[136:137], s[12:13], s28, v130, v[96:97]
	global_load_dwordx4 a[12:15], v[136:137], off
	v_mad_i64_i32 v[136:137], s[12:13], s28, v130, v[98:99]
	global_load_dwordx2 a[64:65], v[136:137], off
	s_waitcnt vmcnt(24)
	v_accvgpr_read_b32 v177, a67
	v_accvgpr_read_b32 v175, a37
	v_accvgpr_read_b32 v173, a39
	v_accvgpr_read_b32 v171, a41
	v_accvgpr_read_b32 v47, a19
	v_mov_b64_e32 v[40:41], v[218:219]
	v_mov_b64_e32 v[36:37], v[222:223]
	v_mov_b64_e32 v[32:33], v[226:227]
	v_accvgpr_read_b32 v176, a66
	v_accvgpr_read_b32 v174, a36
	v_accvgpr_read_b32 v172, a38
	v_accvgpr_read_b32 v170, a40
	v_accvgpr_read_b32 v46, a18
	v_accvgpr_read_b32 v45, a17
	v_accvgpr_read_b32 v44, a16
	v_mov_b64_e32 v[42:43], v[220:221]
	v_mov_b64_e32 v[38:39], v[224:225]
	v_mov_b64_e32 v[34:35], v[228:229]
	s_add_i32 s30, s26, 28
	v_readlane_b32 s28, v100, s30
	s_nop 1
	v_mad_i64_i32 v[136:137], s[12:13], s28, v130, v[96:97]
	global_load_dwordx4 a[16:19], v[136:137], off
	v_mad_i64_i32 v[136:137], s[12:13], s28, v130, v[98:99]
	global_load_dwordx2 a[66:67], v[136:137], off
	s_add_i32 s30, s26, 29
	v_readlane_b32 s28, v100, s30
	s_nop 1
	v_mad_i64_i32 v[136:137], s[12:13], s28, v130, v[96:97]
	global_load_dwordx4 v[218:221], v[136:137], off
	v_mad_i64_i32 v[136:137], s[12:13], s28, v130, v[98:99]
	global_load_dwordx2 a[36:37], v[136:137], off
	s_add_i32 s30, s26, 30
	v_readlane_b32 s28, v100, s30
	s_nop 1
	v_mad_i64_i32 v[136:137], s[12:13], s28, v130, v[96:97]
	global_load_dwordx4 v[222:225], v[136:137], off
	v_mad_i64_i32 v[136:137], s[12:13], s28, v130, v[98:99]
	global_load_dwordx2 a[38:39], v[136:137], off
	s_add_i32 s30, s26, 31
	v_readlane_b32 s28, v100, s30
	s_nop 1
	v_mad_i64_i32 v[136:137], s[12:13], s28, v130, v[96:97]
	global_load_dwordx4 v[226:229], v[136:137], off
	v_mad_i64_i32 v[136:137], s[12:13], s28, v130, v[98:99]
	global_load_dwordx2 a[40:41], v[136:137], off
	s_cmp_lg_u32 s26, 64
	s_cbranch_scc1 .LBB0_2088
	v_ashrrev_i32_e32 v119, 31, v118
	v_ashrrev_i32_e32 v121, 31, v120
	v_lshlrev_b64 v[162:163], 2, v[120:121]
	v_lshl_add_u64 v[166:167], s[4:5], 0, v[162:163]
	v_lshl_add_u64 v[162:163], s[16:17], 0, v[162:163]
	v_lshlrev_b64 v[164:165], 2, v[118:119]
	v_lshl_add_u64 v[168:169], s[4:5], 0, v[164:165]
	v_lshl_add_u64 v[164:165], s[16:17], 0, v[164:165]
	global_load_dword a68, v[168:169], off
	global_load_dword a69, v[166:167], off
	global_load_dword v117, v[164:165], off
	global_load_dword v103, v[162:163], off
	s_branch .LBB0_2088

.LBB0_2570:
	v_mov_b32_e32 v8, v137
	v_add_u32_e32 v137, v8, v136
	v_add_u32_e32 v9, 0xffffe000, v8
	v_min_i32_e32 v10, 0x5fff, v137
	v_lshrrev_b32_e32 v14, 12, v9
	v_ashrrev_i32_e32 v11, 31, v10
	s_waitcnt vmcnt(1)
	v_lshlrev_b32_e32 v132, 16, v2
	v_and_b32_e32 v133, 0xffff0000, v2
	v_lshlrev_b32_e32 v134, 16, v3
	v_and_b32_e32 v135, 0xffff0000, v3
	v_ashrrev_i32_e32 v9, 31, v8
	v_accvgpr_read_b32 v2, a62
	v_lshlrev_b64 v[12:13], 11, v[10:11]
	v_lshlrev_b32_e32 v128, 16, v0
	v_and_b32_e32 v129, 0xffff0000, v0
	v_lshlrev_b32_e32 v130, 16, v1
	v_and_b32_e32 v131, 0xffff0000, v1
	v_lshlrev_b64 v[0:1], 12, v[8:9]
	v_accvgpr_read_b32 v3, a63
	v_lshl_add_u64 v[12:13], v[112:113], 0, v[12:13]
	v_lshl_add_u64 v[120:121], v[2:3], 0, v[0:1]
	v_add_u32_e32 v0, 16, v14
	v_cmp_lt_i32_e32 vcc, s23, v8
	v_accvgpr_read_b32 v2, a60
	global_load_dwordx4 a[12:15], v[12:13], off offset:16
	global_load_dwordx4 a[16:19], v[12:13], off
	v_accvgpr_read_b32 v12, a58
	v_cndmask_b32_e32 v0, 15, v0, vcc
	v_accvgpr_read_b32 v3, a61
	v_lshlrev_b64 v[10:11], 9, v[10:11]
	v_accvgpr_read_b32 v13, a59
	v_mad_u64_u32 v[0:1], s[6:7], v0, s19, v[2:3]
	v_accvgpr_read_b32 v2, a56
	v_lshl_add_u64 v[12:13], v[12:13], 0, v[10:11]
	v_accvgpr_read_b32 v3, a57
	global_load_dword v114, v[12:13], off
	global_load_dword v116, v[12:13], off offset:256
	v_lshl_add_u64 v[12:13], v[0:1], 0, v[2:3]
	v_lshl_add_u64 v[24:25], v[12:13], 0, s[10:11]
	v_add_co_u32_e32 v12, vcc, s27, v12
	v_lshl_add_u64 v[10:11], v[110:111], 0, v[10:11]
	s_nop 0
	v_addc_co_u32_e32 v13, vcc, 0, v13, vcc
	v_accvgpr_read_b32 v32, a52
	v_mov_b32_e32 v33, v254
	global_load_dword v254, v[10:11], off
	global_load_dword a52, v[10:11], off offset:256
	s_waitcnt vmcnt(6)
	v_lshlrev_b32_e32 v118, 16, v4
	v_and_b32_e32 v119, 0xffff0000, v4
	v_lshlrev_b32_e32 v122, 16, v5
	v_and_b32_e32 v123, 0xffff0000, v5
	v_lshlrev_b32_e32 v124, 16, v6
	v_and_b32_e32 v125, 0xffff0000, v6
	v_lshlrev_b32_e32 v126, 16, v7
	v_and_b32_e32 v127, 0xffff0000, v7
	global_load_dwordx4 v[0:3], v[120:121], off offset:48
	global_load_dwordx4 v[4:7], v[120:121], off offset:32
	global_load_dwordx4 v[8:11], v[120:121], off offset:16
	global_load_dwordx4 v[16:19], v[120:121], off
	global_load_dwordx4 v[28:31], v[12:13], off
	s_nop 0
	global_load_dwordx4 v[12:15], v[24:25], off offset:48
	global_load_dwordx4 v[20:23], v[24:25], off offset:32
	s_nop 0
	global_load_dwordx4 v[24:27], v[24:25], off offset:16
	v_mul_f32_e32 v200, v33, v103
	v_mul_f32_e32 v201, v32, v101
	v_mov_b32_e32 v174, 0
	v_accvgpr_read_b32 v183, a29
	v_accvgpr_read_b32 v177, a31
	v_accvgpr_read_b32 v173, a33
	v_accvgpr_read_b32 v171, a35
	v_accvgpr_read_b32 v169, a37
	v_accvgpr_read_b32 v167, a39
	v_accvgpr_read_b32 v165, a41
	v_accvgpr_read_b32 v163, a43
	v_accvgpr_read_b32 v161, a45
	v_accvgpr_read_b32 v159, a47
	v_accvgpr_read_b32 v157, a49
	v_accvgpr_read_b32 v155, a51
	v_accvgpr_read_b32 v153, a25
	v_accvgpr_read_b32 v151, a23
	v_accvgpr_read_b32 v149, a21
	v_accvgpr_read_b32 v147, a27
	v_accvgpr_read_b32 v95, a11
	v_mov_b64_e32 v[88:89], v[250:251]
	v_accvgpr_read_b32 v87, a3
	v_accvgpr_read_b32 v83, a7
	v_mov_b64_e32 v[76:77], v[214:215]
	v_mov_b64_e32 v[72:73], v[218:219]
	v_mov_b64_e32 v[68:69], v[222:223]
	v_mov_b64_e32 v[64:65], v[226:227]
	v_mov_b64_e32 v[60:61], v[230:231]
	v_mov_b64_e32 v[56:57], v[234:235]
	v_mov_b64_e32 v[52:53], v[238:239]
	v_mov_b64_e32 v[48:49], v[242:243]
	v_mov_b64_e32 v[44:45], v[246:247]
	v_mov_b64_e32 v[40:41], v[210:211]
	v_mov_b64_e32 v[36:37], v[206:207]
	s_mov_b32 s18, 0
	v_accvgpr_read_b32 v182, a28
	v_accvgpr_read_b32 v176, a30
	v_accvgpr_read_b32 v172, a32
	v_accvgpr_read_b32 v170, a34
	v_accvgpr_read_b32 v168, a36
	v_accvgpr_read_b32 v166, a38
	v_accvgpr_read_b32 v164, a40
	v_accvgpr_read_b32 v162, a42
	v_accvgpr_read_b32 v160, a44
	v_accvgpr_read_b32 v158, a46
	v_accvgpr_read_b32 v156, a48
	v_accvgpr_read_b32 v154, a50
	v_accvgpr_read_b32 v152, a24
	v_accvgpr_read_b32 v150, a22
	v_accvgpr_read_b32 v148, a20
	v_accvgpr_read_b32 v146, a26
	v_accvgpr_read_b32 v94, a10
	v_accvgpr_read_b32 v93, a9
	v_accvgpr_read_b32 v92, a8
	v_mov_b64_e32 v[90:91], v[252:253]
	v_accvgpr_read_b32 v86, a2
	v_accvgpr_read_b32 v85, a1
	v_accvgpr_read_b32 v84, a0
	v_mov_b64_e32 v[32:33], v[202:203]
	v_accvgpr_read_b32 v82, a6
	v_accvgpr_read_b32 v81, a5
	v_accvgpr_read_b32 v80, a4
	v_mov_b64_e32 v[78:79], v[216:217]
	v_mov_b64_e32 v[74:75], v[220:221]
	v_mov_b64_e32 v[70:71], v[224:225]
	v_mov_b64_e32 v[66:67], v[228:229]
	v_mov_b64_e32 v[62:63], v[232:233]
	v_mov_b64_e32 v[58:59], v[236:237]
	v_mov_b64_e32 v[54:55], v[240:241]
	v_mov_b64_e32 v[50:51], v[244:245]
	v_mov_b64_e32 v[46:47], v[248:249]
	v_mov_b64_e32 v[42:43], v[212:213]
	v_mov_b64_e32 v[38:39], v[208:209]
	v_mov_b64_e32 v[34:35], v[204:205]
	v_mov_b32_e32 v175, v174
	v_mov_b32_e32 v192, v174
	v_mov_b32_e32 v193, v174
	v_mov_b32_e32 v188, v174
	v_mov_b32_e32 v189, v174
	v_mov_b32_e32 v190, v174
	v_mov_b32_e32 v191, v174
	v_mov_b32_e32 v184, v174
	v_mov_b32_e32 v185, v174
	v_mov_b32_e32 v186, v174
	v_mov_b32_e32 v187, v174
	v_mov_b32_e32 v178, v174
	v_mov_b32_e32 v179, v174
	v_mov_b32_e32 v180, v174
	v_mov_b32_e32 v181, v174
.LBB0_2571:
	s_add_i32 s48, s18, 16
	s_cmpk_gt_u32 s18, 0x6f
	s_cselect_b64 s[8:9], -1, 0
	s_cmpk_lt_u32 s18, 0x70
	s_cselect_b64 vcc, -1, 0
	s_bitcmp0_b32 s48, 6
	s_cselect_b64 s[6:7], -1, 0
	v_cndmask_b32_e64 v104, v102, v100, s[6:7]
	v_cndmask_b32_e32 v104, v114, v104, vcc
	s_nop 0
	v_readlane_b32 s20, v104, s48
	s_nop 1
	v_mad_i64_i32 v[202:203], s[6:7], s20, v194, v[96:97]
	global_load_dwordx4 a[8:11], v[202:203], off
	v_mad_i64_i32 v[202:203], s[6:7], s20, v194, v[98:99]
	s_add_i32 s6, s18, 17
	global_load_dwordx2 a[28:29], v[202:203], off
	s_nop 1
	v_readlane_b32 s20, v104, s6
	s_nop 1
	v_mad_i64_i32 v[202:203], s[6:7], s20, v194, v[96:97]
	global_load_dwordx4 v[250:253], v[202:203], off
	v_mad_i64_i32 v[202:203], s[6:7], s20, v194, v[98:99]
	s_add_i32 s6, s18, 18
	global_load_dwordx2 a[30:31], v[202:203], off
	s_nop 1
	v_readlane_b32 s20, v104, s6
	s_nop 1
	v_mad_i64_i32 v[202:203], s[6:7], s20, v194, v[96:97]
	global_load_dwordx4 a[0:3], v[202:203], off
	v_mad_i64_i32 v[202:203], s[6:7], s20, v194, v[98:99]
	s_add_i32 s6, s18, 19
	global_load_dwordx2 a[32:33], v[202:203], off
	s_nop 1
	v_readlane_b32 s20, v104, s6
	s_nop 1
	v_mad_i64_i32 v[202:203], s[6:7], s20, v194, v[96:97]
	global_load_dwordx4 a[4:7], v[202:203], off
	v_mad_i64_i32 v[202:203], s[6:7], s20, v194, v[98:99]
	s_add_i32 s6, s18, 20
	global_load_dwordx2 a[34:35], v[202:203], off
	s_nop 1
	v_readlane_b32 s20, v104, s6
	s_nop 1
	v_mad_i64_i32 v[202:203], s[6:7], s20, v194, v[96:97]
	global_load_dwordx4 v[214:217], v[202:203], off
	v_mad_i64_i32 v[202:203], s[6:7], s20, v194, v[98:99]
	s_add_i32 s6, s18, 21
	global_load_dwordx2 a[36:37], v[202:203], off
	s_nop 1
	v_readlane_b32 s20, v104, s6
	s_nop 1
	v_mad_i64_i32 v[202:203], s[6:7], s20, v194, v[96:97]
	global_load_dwordx4 v[218:221], v[202:203], off
	v_mad_i64_i32 v[202:203], s[6:7], s20, v194, v[98:99]
	s_add_i32 s6, s18, 22
	global_load_dwordx2 a[38:39], v[202:203], off
	s_nop 1
	v_readlane_b32 s20, v104, s6
	s_nop 1
	v_mad_i64_i32 v[202:203], s[6:7], s20, v194, v[96:97]
	global_load_dwordx4 v[222:225], v[202:203], off
	v_mad_i64_i32 v[202:203], s[6:7], s20, v194, v[98:99]
	s_add_i32 s6, s18, 23
	global_load_dwordx2 a[40:41], v[202:203], off
	s_nop 1
	v_readlane_b32 s20, v104, s6
	s_nop 1
	v_mad_i64_i32 v[202:203], s[6:7], s20, v194, v[96:97]
	global_load_dwordx4 v[226:229], v[202:203], off
	v_mad_i64_i32 v[202:203], s[6:7], s20, v194, v[98:99]
	s_add_i32 s6, s18, 24
	global_load_dwordx2 a[42:43], v[202:203], off
	s_nop 1
	v_readlane_b32 s20, v104, s6
	s_nop 1
	v_mad_i64_i32 v[202:203], s[6:7], s20, v194, v[96:97]
	global_load_dwordx4 v[230:233], v[202:203], off
	v_mad_i64_i32 v[202:203], s[6:7], s20, v194, v[98:99]
	s_add_i32 s6, s18, 25
	global_load_dwordx2 a[44:45], v[202:203], off
	s_nop 1
	v_readlane_b32 s20, v104, s6
	s_nop 1
	v_mad_i64_i32 v[202:203], s[6:7], s20, v194, v[96:97]
	global_load_dwordx4 v[234:237], v[202:203], off
	v_mad_i64_i32 v[202:203], s[6:7], s20, v194, v[98:99]
	s_add_i32 s6, s18, 26
	global_load_dwordx2 a[46:47], v[202:203], off
	s_nop 1
	v_readlane_b32 s20, v104, s6
	s_nop 1
	v_mad_i64_i32 v[202:203], s[6:7], s20, v194, v[96:97]
	global_load_dwordx4 v[238:241], v[202:203], off
	v_mad_i64_i32 v[202:203], s[6:7], s20, v194, v[98:99]
	s_add_i32 s6, s18, 27
	global_load_dwordx2 a[48:49], v[202:203], off
	s_nop 1
	v_readlane_b32 s20, v104, s6
	s_nop 1
	v_mad_i64_i32 v[202:203], s[6:7], s20, v194, v[96:97]
	global_load_dwordx4 v[242:245], v[202:203], off
	v_mad_i64_i32 v[202:203], s[6:7], s20, v194, v[98:99]
	s_add_i32 s6, s18, 28
	global_load_dwordx2 a[50:51], v[202:203], off
	s_nop 1
	v_readlane_b32 s20, v104, s6
	s_nop 1
	v_mad_i64_i32 v[202:203], s[6:7], s20, v194, v[96:97]
	global_load_dwordx4 v[246:249], v[202:203], off
	v_mad_i64_i32 v[202:203], s[6:7], s20, v194, v[98:99]
	s_add_i32 s6, s18, 29
	global_load_dwordx2 a[24:25], v[202:203], off
	s_nop 1
	v_readlane_b32 s20, v104, s6
	s_nop 1
	v_mad_i64_i32 v[202:203], s[6:7], s20, v194, v[96:97]
	global_load_dwordx4 v[210:213], v[202:203], off
	v_mad_i64_i32 v[202:203], s[6:7], s20, v194, v[98:99]
	s_add_i32 s6, s18, 30
	global_load_dwordx2 a[22:23], v[202:203], off
	s_nop 1
	v_readlane_b32 s20, v104, s6
	s_nop 1
	v_mad_i64_i32 v[202:203], s[6:7], s20, v194, v[96:97]
	global_load_dwordx4 v[206:209], v[202:203], off
	v_mad_i64_i32 v[202:203], s[6:7], s20, v194, v[98:99]
	s_add_i32 s6, s18, 31
	global_load_dwordx2 a[20:21], v[202:203], off
	s_cmp_lg_u32 s18, 64
	s_nop 0
	v_readlane_b32 s20, v104, s6
	s_nop 1
	v_mad_i64_i32 v[104:105], s[6:7], s20, v194, v[98:99]
	global_load_dwordx2 a[26:27], v[104:105], off
	v_mad_i64_i32 v[202:203], s[6:7], s20, v194, v[96:97]
	global_load_dwordx4 v[202:205], v[202:203], off
	s_cbranch_scc1 .LBB0_2573
	v_ashrrev_i32_e32 v115, 31, v114
	v_ashrrev_i32_e32 v117, 31, v116
	v_lshlrev_b64 v[138:139], 2, v[116:117]
	v_lshl_add_u64 v[142:143], s[12:13], 0, v[138:139]
	v_lshl_add_u64 v[138:139], s[14:15], 0, v[138:139]
	v_lshlrev_b64 v[140:141], 2, v[114:115]
	v_lshl_add_u64 v[144:145], s[12:13], 0, v[140:141]
	v_lshl_add_u64 v[140:141], s[14:15], 0, v[140:141]
	global_load_dword a53, v[144:145], off
	global_load_dword a54, v[142:143], off
	global_load_dword v103, v[140:141], off
	global_load_dword v101, v[138:139], off

.LBB0_2587:
	s_andn2_saveexec_b64 s[42:43], s[42:43]
	v_mul_f32_e32 v34, v33, v33
	v_fmamk_f32 v35, v34, 0xba1345e1, v195
	v_fmaak_f32 v35, v34, v35, 0xbcdac9b8
	v_fmaak_f32 v35, v34, v35, 0x3de703be
	v_fmaak_f32 v35, v34, v35, 0xbec09330
	v_fmaak_f32 v34, v34, v35, 0x3e0375d0
	v_fma_f32 v34, |v33|, v34, |v33|
	s_or_b64 exec, exec, s[42:43]
	v_cvt_scalef32_pk_f32_fp4 v[36:37], v182, 1.0
	v_pk_fma_f32 v[36:37], s[22:23], v[36:37], v[174:175] op_sel_hi:[0,1,1]
	v_cvt_scalef32_pk_f32_fp4 v[38:39], v182, 1.0 op_sel:[1,0,0]
	v_cvt_scalef32_pk_f32_fp4 v[52:53], v176, 1.0
	v_pk_fma_f32 v[38:39], s[22:23], v[38:39], v[192:193] op_sel_hi:[0,1,1]
	v_cvt_scalef32_pk_f32_fp4 v[40:41], v182, 1.0 op_sel:[0,1,0]
	v_pk_fma_f32 v[36:37], s[20:21], v[52:53], v[36:37] op_sel_hi:[0,1,1]
	v_cvt_scalef32_pk_f32_fp4 v[52:53], v176, 1.0 op_sel:[1,0,0]
	v_pk_fma_f32 v[40:41], s[22:23], v[40:41], v[188:189] op_sel_hi:[0,1,1]
	v_cvt_scalef32_pk_f32_fp4 v[42:43], v182, 1.0 op_sel:[1,1,0]
	v_pk_fma_f32 v[38:39], s[20:21], v[52:53], v[38:39] op_sel_hi:[0,1,1]
	v_cvt_scalef32_pk_f32_fp4 v[52:53], v176, 1.0 op_sel:[0,1,0]
	v_pk_fma_f32 v[42:43], s[22:23], v[42:43], v[190:191] op_sel_hi:[0,1,1]
	v_cvt_scalef32_pk_f32_fp4 v[44:45], v183, 1.0
	v_pk_fma_f32 v[40:41], s[20:21], v[52:53], v[40:41] op_sel_hi:[0,1,1]
	v_cvt_scalef32_pk_f32_fp4 v[52:53], v176, 1.0 op_sel:[1,1,0]
	v_pk_fma_f32 v[44:45], s[22:23], v[44:45], v[184:185] op_sel_hi:[0,1,1]
	v_cvt_scalef32_pk_f32_fp4 v[46:47], v183, 1.0 op_sel:[1,0,0]
	v_pk_fma_f32 v[42:43], s[20:21], v[52:53], v[42:43] op_sel_hi:[0,1,1]
	v_cvt_scalef32_pk_f32_fp4 v[52:53], v177, 1.0
	v_pk_fma_f32 v[46:47], s[22:23], v[46:47], v[186:187] op_sel_hi:[0,1,1]
	v_cvt_scalef32_pk_f32_fp4 v[48:49], v183, 1.0 op_sel:[0,1,0]
	v_pk_fma_f32 v[44:45], s[20:21], v[52:53], v[44:45] op_sel_hi:[0,1,1]
	v_cvt_scalef32_pk_f32_fp4 v[52:53], v177, 1.0 op_sel:[1,0,0]
	v_pk_fma_f32 v[48:49], s[22:23], v[48:49], v[178:179] op_sel_hi:[0,1,1]
	v_cvt_scalef32_pk_f32_fp4 v[50:51], v183, 1.0 op_sel:[1,1,0]
	v_pk_fma_f32 v[46:47], s[20:21], v[52:53], v[46:47] op_sel_hi:[0,1,1]
	v_cvt_scalef32_pk_f32_fp4 v[52:53], v177, 1.0 op_sel:[0,1,0]
	v_pk_fma_f32 v[50:51], s[22:23], v[50:51], v[180:181] op_sel_hi:[0,1,1]
	v_pk_fma_f32 v[48:49], s[20:21], v[52:53], v[48:49] op_sel_hi:[0,1,1]
	v_cvt_scalef32_pk_f32_fp4 v[52:53], v177, 1.0 op_sel:[1,1,0]
	v_pk_fma_f32 v[50:51], s[20:21], v[52:53], v[50:51] op_sel_hi:[0,1,1]
	v_cvt_scalef32_pk_f32_fp4 v[52:53], v172, 1.0
	v_pk_fma_f32 v[36:37], s[18:19], v[52:53], v[36:37] op_sel_hi:[0,1,1]
	v_cvt_scalef32_pk_f32_fp4 v[52:53], v172, 1.0 op_sel:[1,0,0]
	v_pk_fma_f32 v[38:39], s[18:19], v[52:53], v[38:39] op_sel_hi:[0,1,1]
	v_cvt_scalef32_pk_f32_fp4 v[52:53], v172, 1.0 op_sel:[0,1,0]
	v_pk_fma_f32 v[40:41], s[18:19], v[52:53], v[40:41] op_sel_hi:[0,1,1]
	v_cvt_scalef32_pk_f32_fp4 v[52:53], v172, 1.0 op_sel:[1,1,0]
	v_pk_fma_f32 v[42:43], s[18:19], v[52:53], v[42:43] op_sel_hi:[0,1,1]
	v_cvt_scalef32_pk_f32_fp4 v[52:53], v173, 1.0
	v_pk_fma_f32 v[44:45], s[18:19], v[52:53], v[44:45] op_sel_hi:[0,1,1]
	v_cvt_scalef32_pk_f32_fp4 v[52:53], v173, 1.0 op_sel:[1,0,0]
	v_pk_fma_f32 v[46:47], s[18:19], v[52:53], v[46:47] op_sel_hi:[0,1,1]
	v_cvt_scalef32_pk_f32_fp4 v[52:53], v173, 1.0 op_sel:[0,1,0]
	v_pk_fma_f32 v[48:49], s[18:19], v[52:53], v[48:49] op_sel_hi:[0,1,1]
	v_cvt_scalef32_pk_f32_fp4 v[52:53], v173, 1.0 op_sel:[1,1,0]
	v_pk_fma_f32 v[50:51], s[18:19], v[52:53], v[50:51] op_sel_hi:[0,1,1]
	v_cvt_scalef32_pk_f32_fp4 v[52:53], v170, 1.0
	v_pk_fma_f32 v[36:37], s[6:7], v[52:53], v[36:37] op_sel_hi:[0,1,1]
	v_cvt_scalef32_pk_f32_fp4 v[52:53], v170, 1.0 op_sel:[1,0,0]
	v_pk_fma_f32 v[38:39], s[6:7], v[52:53], v[38:39] op_sel_hi:[0,1,1]
	v_cvt_scalef32_pk_f32_fp4 v[52:53], v170, 1.0 op_sel:[0,1,0]
	v_pk_fma_f32 v[40:41], s[6:7], v[52:53], v[40:41] op_sel_hi:[0,1,1]
	v_cvt_scalef32_pk_f32_fp4 v[52:53], v170, 1.0 op_sel:[1,1,0]
	v_pk_fma_f32 v[42:43], s[6:7], v[52:53], v[42:43] op_sel_hi:[0,1,1]
	v_cvt_scalef32_pk_f32_fp4 v[52:53], v171, 1.0
	v_pk_fma_f32 v[44:45], s[6:7], v[52:53], v[44:45] op_sel_hi:[0,1,1]
	v_cvt_scalef32_pk_f32_fp4 v[52:53], v171, 1.0 op_sel:[1,0,0]
	v_pk_fma_f32 v[46:47], s[6:7], v[52:53], v[46:47] op_sel_hi:[0,1,1]
	v_cvt_scalef32_pk_f32_fp4 v[52:53], v171, 1.0 op_sel:[0,1,0]
	v_pk_fma_f32 v[48:49], s[6:7], v[52:53], v[48:49] op_sel_hi:[0,1,1]
	v_cvt_scalef32_pk_f32_fp4 v[52:53], v171, 1.0 op_sel:[1,1,0]
	v_pk_fma_f32 v[50:51], s[6:7], v[52:53], v[50:51] op_sel_hi:[0,1,1]
	v_cvt_scalef32_pk_f32_fp4 v[52:53], v168, 1.0
	v_pk_fma_f32 v[36:37], s[30:31], v[52:53], v[36:37] op_sel_hi:[0,1,1]
	v_cvt_scalef32_pk_f32_fp4 v[52:53], v168, 1.0 op_sel:[1,0,0]
	v_pk_fma_f32 v[38:39], s[30:31], v[52:53], v[38:39] op_sel_hi:[0,1,1]
	v_cvt_scalef32_pk_f32_fp4 v[52:53], v168, 1.0 op_sel:[0,1,0]
	v_pk_fma_f32 v[40:41], s[30:31], v[52:53], v[40:41] op_sel_hi:[0,1,1]
	v_cvt_scalef32_pk_f32_fp4 v[52:53], v168, 1.0 op_sel:[1,1,0]
	v_pk_fma_f32 v[42:43], s[30:31], v[52:53], v[42:43] op_sel_hi:[0,1,1]
	v_cvt_scalef32_pk_f32_fp4 v[52:53], v169, 1.0
	v_pk_fma_f32 v[44:45], s[30:31], v[52:53], v[44:45] op_sel_hi:[0,1,1]
	v_cvt_scalef32_pk_f32_fp4 v[52:53], v169, 1.0 op_sel:[1,0,0]
	v_pk_fma_f32 v[46:47], s[30:31], v[52:53], v[46:47] op_sel_hi:[0,1,1]
	v_cvt_scalef32_pk_f32_fp4 v[52:53], v169, 1.0 op_sel:[0,1,0]
	v_pk_fma_f32 v[48:49], s[30:31], v[52:53], v[48:49] op_sel_hi:[0,1,1]
	v_cvt_scalef32_pk_f32_fp4 v[52:53], v169, 1.0 op_sel:[1,1,0]
	v_pk_fma_f32 v[50:51], s[30:31], v[52:53], v[50:51] op_sel_hi:[0,1,1]
	v_cvt_scalef32_pk_f32_fp4 v[52:53], v166, 1.0
	v_pk_fma_f32 v[36:37], s[28:29], v[52:53], v[36:37] op_sel_hi:[0,1,1]
	v_cvt_scalef32_pk_f32_fp4 v[52:53], v166, 1.0 op_sel:[1,0,0]
	v_pk_fma_f32 v[38:39], s[28:29], v[52:53], v[38:39] op_sel_hi:[0,1,1]
	v_cvt_scalef32_pk_f32_fp4 v[52:53], v166, 1.0 op_sel:[0,1,0]
	v_pk_fma_f32 v[40:41], s[28:29], v[52:53], v[40:41] op_sel_hi:[0,1,1]
	v_cvt_scalef32_pk_f32_fp4 v[52:53], v166, 1.0 op_sel:[1,1,0]
	v_pk_fma_f32 v[42:43], s[28:29], v[52:53], v[42:43] op_sel_hi:[0,1,1]
	v_cvt_scalef32_pk_f32_fp4 v[52:53], v167, 1.0
	v_pk_fma_f32 v[44:45], s[28:29], v[52:53], v[44:45] op_sel_hi:[0,1,1]
	v_cvt_scalef32_pk_f32_fp4 v[52:53], v167, 1.0 op_sel:[1,0,0]
	v_pk_fma_f32 v[46:47], s[28:29], v[52:53], v[46:47] op_sel_hi:[0,1,1]
	v_cvt_scalef32_pk_f32_fp4 v[52:53], v167, 1.0 op_sel:[0,1,0]
	v_pk_fma_f32 v[48:49], s[28:29], v[52:53], v[48:49] op_sel_hi:[0,1,1]
	v_cvt_scalef32_pk_f32_fp4 v[52:53], v167, 1.0 op_sel:[1,1,0]
	v_pk_fma_f32 v[50:51], s[28:29], v[52:53], v[50:51] op_sel_hi:[0,1,1]
	v_cvt_scalef32_pk_f32_fp4 v[52:53], v164, 1.0
	v_pk_fma_f32 v[36:37], s[26:27], v[52:53], v[36:37] op_sel_hi:[0,1,1]
	v_cvt_scalef32_pk_f32_fp4 v[52:53], v164, 1.0 op_sel:[1,0,0]
	v_pk_fma_f32 v[38:39], s[26:27], v[52:53], v[38:39] op_sel_hi:[0,1,1]
	v_cvt_scalef32_pk_f32_fp4 v[52:53], v164, 1.0 op_sel:[0,1,0]
	v_pk_fma_f32 v[40:41], s[26:27], v[52:53], v[40:41] op_sel_hi:[0,1,1]
	v_cvt_scalef32_pk_f32_fp4 v[52:53], v164, 1.0 op_sel:[1,1,0]
	v_pk_fma_f32 v[42:43], s[26:27], v[52:53], v[42:43] op_sel_hi:[0,1,1]
	v_cvt_scalef32_pk_f32_fp4 v[52:53], v165, 1.0
	v_pk_fma_f32 v[44:45], s[26:27], v[52:53], v[44:45] op_sel_hi:[0,1,1]
	v_cvt_scalef32_pk_f32_fp4 v[52:53], v165, 1.0 op_sel:[1,0,0]
	v_pk_fma_f32 v[46:47], s[26:27], v[52:53], v[46:47] op_sel_hi:[0,1,1]
	v_cvt_scalef32_pk_f32_fp4 v[52:53], v165, 1.0 op_sel:[0,1,0]
	v_pk_fma_f32 v[48:49], s[26:27], v[52:53], v[48:49] op_sel_hi:[0,1,1]
	v_cvt_scalef32_pk_f32_fp4 v[52:53], v165, 1.0 op_sel:[1,1,0]
	v_pk_fma_f32 v[50:51], s[26:27], v[52:53], v[50:51] op_sel_hi:[0,1,1]
	v_cvt_scalef32_pk_f32_fp4 v[52:53], v162, 1.0
	v_pk_fma_f32 v[36:37], s[24:25], v[52:53], v[36:37] op_sel_hi:[0,1,1]
	v_cvt_scalef32_pk_f32_fp4 v[52:53], v162, 1.0 op_sel:[1,0,0]
	v_pk_fma_f32 v[38:39], s[24:25], v[52:53], v[38:39] op_sel_hi:[0,1,1]
	v_cvt_scalef32_pk_f32_fp4 v[52:53], v162, 1.0 op_sel:[0,1,0]
	v_pk_fma_f32 v[40:41], s[24:25], v[52:53], v[40:41] op_sel_hi:[0,1,1]
	v_cvt_scalef32_pk_f32_fp4 v[52:53], v162, 1.0 op_sel:[1,1,0]
	v_pk_fma_f32 v[42:43], s[24:25], v[52:53], v[42:43] op_sel_hi:[0,1,1]
	v_cvt_scalef32_pk_f32_fp4 v[52:53], v163, 1.0
	v_pk_fma_f32 v[44:45], s[24:25], v[52:53], v[44:45] op_sel_hi:[0,1,1]
	v_cvt_scalef32_pk_f32_fp4 v[52:53], v163, 1.0 op_sel:[1,0,0]
	v_pk_fma_f32 v[46:47], s[24:25], v[52:53], v[46:47] op_sel_hi:[0,1,1]
	v_cvt_scalef32_pk_f32_fp4 v[52:53], v163, 1.0 op_sel:[0,1,0]
	v_pk_fma_f32 v[48:49], s[24:25], v[52:53], v[48:49] op_sel_hi:[0,1,1]
	v_cvt_scalef32_pk_f32_fp4 v[52:53], v163, 1.0 op_sel:[1,1,0]
	v_pk_fma_f32 v[50:51], s[24:25], v[52:53], v[50:51] op_sel_hi:[0,1,1]
	v_cvt_scalef32_pk_f32_fp4 v[52:53], v160, 1.0
	v_pk_fma_f32 v[36:37], s[40:41], v[52:53], v[36:37] op_sel_hi:[0,1,1]
	v_cvt_scalef32_pk_f32_fp4 v[52:53], v160, 1.0 op_sel:[1,0,0]
	v_pk_fma_f32 v[38:39], s[40:41], v[52:53], v[38:39] op_sel_hi:[0,1,1]
	v_cvt_scalef32_pk_f32_fp4 v[52:53], v160, 1.0 op_sel:[0,1,0]
	v_pk_fma_f32 v[40:41], s[40:41], v[52:53], v[40:41] op_sel_hi:[0,1,1]
	v_cvt_scalef32_pk_f32_fp4 v[52:53], v160, 1.0 op_sel:[1,1,0]
	v_pk_fma_f32 v[42:43], s[40:41], v[52:53], v[42:43] op_sel_hi:[0,1,1]
	v_cvt_scalef32_pk_f32_fp4 v[52:53], v161, 1.0
	v_pk_fma_f32 v[44:45], s[40:41], v[52:53], v[44:45] op_sel_hi:[0,1,1]
	v_cvt_scalef32_pk_f32_fp4 v[52:53], v161, 1.0 op_sel:[1,0,0]
	v_pk_fma_f32 v[46:47], s[40:41], v[52:53], v[46:47] op_sel_hi:[0,1,1]
	v_cvt_scalef32_pk_f32_fp4 v[52:53], v161, 1.0 op_sel:[0,1,0]
	v_pk_fma_f32 v[48:49], s[40:41], v[52:53], v[48:49] op_sel_hi:[0,1,1]
	v_cvt_scalef32_pk_f32_fp4 v[52:53], v161, 1.0 op_sel:[1,1,0]
	v_pk_fma_f32 v[50:51], s[40:41], v[52:53], v[50:51] op_sel_hi:[0,1,1]
	v_cvt_scalef32_pk_f32_fp4 v[52:53], v158, 1.0
	v_pk_fma_f32 v[36:37], s[38:39], v[52:53], v[36:37] op_sel_hi:[0,1,1]
	v_cvt_scalef32_pk_f32_fp4 v[52:53], v158, 1.0 op_sel:[1,0,0]
	v_pk_fma_f32 v[38:39], s[38:39], v[52:53], v[38:39] op_sel_hi:[0,1,1]
	v_cvt_scalef32_pk_f32_fp4 v[52:53], v158, 1.0 op_sel:[0,1,0]
	v_pk_fma_f32 v[40:41], s[38:39], v[52:53], v[40:41] op_sel_hi:[0,1,1]
	v_cvt_scalef32_pk_f32_fp4 v[52:53], v158, 1.0 op_sel:[1,1,0]
	v_pk_fma_f32 v[42:43], s[38:39], v[52:53], v[42:43] op_sel_hi:[0,1,1]
	v_cvt_scalef32_pk_f32_fp4 v[52:53], v159, 1.0
	v_pk_fma_f32 v[44:45], s[38:39], v[52:53], v[44:45] op_sel_hi:[0,1,1]
	v_cvt_scalef32_pk_f32_fp4 v[52:53], v159, 1.0 op_sel:[1,0,0]
	v_pk_fma_f32 v[46:47], s[38:39], v[52:53], v[46:47] op_sel_hi:[0,1,1]
	v_cvt_scalef32_pk_f32_fp4 v[52:53], v159, 1.0 op_sel:[0,1,0]
	v_pk_fma_f32 v[48:49], s[38:39], v[52:53], v[48:49] op_sel_hi:[0,1,1]
	v_cvt_scalef32_pk_f32_fp4 v[52:53], v159, 1.0 op_sel:[1,1,0]
	v_pk_fma_f32 v[50:51], s[38:39], v[52:53], v[50:51] op_sel_hi:[0,1,1]
	v_cvt_scalef32_pk_f32_fp4 v[52:53], v156, 1.0
	v_pk_fma_f32 v[36:37], s[36:37], v[52:53], v[36:37] op_sel_hi:[0,1,1]
	v_cvt_scalef32_pk_f32_fp4 v[52:53], v156, 1.0 op_sel:[1,0,0]
	v_pk_fma_f32 v[38:39], s[36:37], v[52:53], v[38:39] op_sel_hi:[0,1,1]
	v_cvt_scalef32_pk_f32_fp4 v[52:53], v156, 1.0 op_sel:[0,1,0]
	v_pk_fma_f32 v[40:41], s[36:37], v[52:53], v[40:41] op_sel_hi:[0,1,1]
	v_cvt_scalef32_pk_f32_fp4 v[52:53], v156, 1.0 op_sel:[1,1,0]
	v_pk_fma_f32 v[42:43], s[36:37], v[52:53], v[42:43] op_sel_hi:[0,1,1]
	v_cvt_scalef32_pk_f32_fp4 v[52:53], v157, 1.0
	v_pk_fma_f32 v[44:45], s[36:37], v[52:53], v[44:45] op_sel_hi:[0,1,1]
	v_cvt_scalef32_pk_f32_fp4 v[52:53], v157, 1.0 op_sel:[1,0,0]
	v_pk_fma_f32 v[46:47], s[36:37], v[52:53], v[46:47] op_sel_hi:[0,1,1]
	v_cvt_scalef32_pk_f32_fp4 v[52:53], v157, 1.0 op_sel:[0,1,0]
	v_pk_fma_f32 v[48:49], s[36:37], v[52:53], v[48:49] op_sel_hi:[0,1,1]
	v_cvt_scalef32_pk_f32_fp4 v[52:53], v157, 1.0 op_sel:[1,1,0]
	v_pk_fma_f32 v[50:51], s[36:37], v[52:53], v[50:51] op_sel_hi:[0,1,1]
	v_cvt_scalef32_pk_f32_fp4 v[52:53], v154, 1.0
	v_pk_fma_f32 v[36:37], s[34:35], v[52:53], v[36:37] op_sel_hi:[0,1,1]
	v_cvt_scalef32_pk_f32_fp4 v[52:53], v154, 1.0 op_sel:[1,0,0]
	v_pk_fma_f32 v[38:39], s[34:35], v[52:53], v[38:39] op_sel_hi:[0,1,1]
	v_cvt_scalef32_pk_f32_fp4 v[52:53], v154, 1.0 op_sel:[0,1,0]
	v_pk_fma_f32 v[40:41], s[34:35], v[52:53], v[40:41] op_sel_hi:[0,1,1]
	v_cvt_scalef32_pk_f32_fp4 v[52:53], v154, 1.0 op_sel:[1,1,0]
	v_pk_fma_f32 v[42:43], s[34:35], v[52:53], v[42:43] op_sel_hi:[0,1,1]
	v_cvt_scalef32_pk_f32_fp4 v[52:53], v155, 1.0
	v_pk_fma_f32 v[44:45], s[34:35], v[52:53], v[44:45] op_sel_hi:[0,1,1]
	v_cvt_scalef32_pk_f32_fp4 v[52:53], v155, 1.0 op_sel:[1,0,0]
	v_pk_fma_f32 v[46:47], s[34:35], v[52:53], v[46:47] op_sel_hi:[0,1,1]
	v_cvt_scalef32_pk_f32_fp4 v[52:53], v155, 1.0 op_sel:[0,1,0]
	v_pk_fma_f32 v[48:49], s[34:35], v[52:53], v[48:49] op_sel_hi:[0,1,1]
	v_cvt_scalef32_pk_f32_fp4 v[52:53], v155, 1.0 op_sel:[1,1,0]
	v_pk_fma_f32 v[50:51], s[34:35], v[52:53], v[50:51] op_sel_hi:[0,1,1]
	v_mov_b32_e32 v35, s49
	v_mov_b32_e32 v52, s25
	v_cndmask_b32_e64 v35, v35, v52, s[4:5]
	v_mov_b32_e32 v52, s35
	v_bfi_b32 v33, s47, v34, v33
	v_cndmask_b32_e64 v35, v35, v52, s[2:3]
	v_mov_b32_e32 v52, s7
	v_mul_f32_e32 v32, 0.5, v32
	v_add_f32_e32 v33, 1.0, v33
	v_cndmask_b32_e64 v35, v35, v52, s[0:1]
	v_mul_f32_e32 v32, v32, v33
	v_mul_f32_e32 v32, v35, v32
	v_cvt_scalef32_pk_f32_fp4 v[34:35], v152, 1.0 op_sel:[1,0,0]
	v_readlane_b32 s6, v32, 0
	v_readlane_b32 s18, v32, 32
	v_readlane_b32 s20, v32, 16
	v_readlane_b32 s22, v32, 48
	v_cvt_scalef32_pk_f32_fp4 v[32:33], v152, 1.0
	v_pk_fma_f32 v[32:33], s[6:7], v[32:33], v[36:37] op_sel_hi:[0,1,1]
	v_cvt_scalef32_pk_f32_fp4 v[36:37], v152, 1.0 op_sel:[0,1,0]
	v_pk_fma_f32 v[36:37], s[6:7], v[36:37], v[40:41] op_sel_hi:[0,1,1]
	v_cvt_scalef32_pk_f32_fp4 v[40:41], v153, 1.0
	v_pk_fma_f32 v[40:41], s[6:7], v[40:41], v[44:45] op_sel_hi:[0,1,1]
	v_cvt_scalef32_pk_f32_fp4 v[44:45], v153, 1.0 op_sel:[0,1,0]
	v_pk_fma_f32 v[44:45], s[6:7], v[44:45], v[48:49] op_sel_hi:[0,1,1]
	v_cvt_scalef32_pk_f32_fp4 v[48:49], v150, 1.0
	v_pk_fma_f32 v[34:35], s[6:7], v[34:35], v[38:39] op_sel_hi:[0,1,1]
	v_pk_fma_f32 v[32:33], s[18:19], v[48:49], v[32:33] op_sel_hi:[0,1,1]
	v_cvt_scalef32_pk_f32_fp4 v[48:49], v150, 1.0 op_sel:[1,0,0]
	v_cvt_scalef32_pk_f32_fp4 v[38:39], v152, 1.0 op_sel:[1,1,0]
	v_pk_fma_f32 v[34:35], s[18:19], v[48:49], v[34:35] op_sel_hi:[0,1,1]
	v_cvt_scalef32_pk_f32_fp4 v[48:49], v150, 1.0 op_sel:[0,1,0]
	v_pk_fma_f32 v[38:39], s[6:7], v[38:39], v[42:43] op_sel_hi:[0,1,1]
	v_pk_fma_f32 v[36:37], s[18:19], v[48:49], v[36:37] op_sel_hi:[0,1,1]
	v_cvt_scalef32_pk_f32_fp4 v[48:49], v150, 1.0 op_sel:[1,1,0]
	v_cvt_scalef32_pk_f32_fp4 v[42:43], v153, 1.0 op_sel:[1,0,0]
	v_pk_fma_f32 v[38:39], s[18:19], v[48:49], v[38:39] op_sel_hi:[0,1,1]
	v_cvt_scalef32_pk_f32_fp4 v[48:49], v151, 1.0
	v_pk_fma_f32 v[42:43], s[6:7], v[42:43], v[46:47] op_sel_hi:[0,1,1]
	v_pk_fma_f32 v[40:41], s[18:19], v[48:49], v[40:41] op_sel_hi:[0,1,1]
	v_cvt_scalef32_pk_f32_fp4 v[48:49], v151, 1.0 op_sel:[1,0,0]
	v_cvt_scalef32_pk_f32_fp4 v[46:47], v153, 1.0 op_sel:[1,1,0]
	v_pk_fma_f32 v[42:43], s[18:19], v[48:49], v[42:43] op_sel_hi:[0,1,1]
	v_cvt_scalef32_pk_f32_fp4 v[48:49], v151, 1.0 op_sel:[0,1,0]
	v_pk_fma_f32 v[46:47], s[6:7], v[46:47], v[50:51] op_sel_hi:[0,1,1]
	v_pk_fma_f32 v[44:45], s[18:19], v[48:49], v[44:45] op_sel_hi:[0,1,1]
	v_cvt_scalef32_pk_f32_fp4 v[48:49], v151, 1.0 op_sel:[1,1,0]
	v_pk_fma_f32 v[46:47], s[18:19], v[48:49], v[46:47] op_sel_hi:[0,1,1]
	v_cvt_scalef32_pk_f32_fp4 v[48:49], v148, 1.0
	v_pk_fma_f32 v[32:33], s[20:21], v[48:49], v[32:33] op_sel_hi:[0,1,1]
	v_cvt_scalef32_pk_f32_fp4 v[48:49], v148, 1.0 op_sel:[1,0,0]
	v_pk_fma_f32 v[34:35], s[20:21], v[48:49], v[34:35] op_sel_hi:[0,1,1]
	v_cvt_scalef32_pk_f32_fp4 v[48:49], v148, 1.0 op_sel:[0,1,0]
	v_pk_fma_f32 v[36:37], s[20:21], v[48:49], v[36:37] op_sel_hi:[0,1,1]
	v_cvt_scalef32_pk_f32_fp4 v[48:49], v148, 1.0 op_sel:[1,1,0]
	v_pk_fma_f32 v[38:39], s[20:21], v[48:49], v[38:39] op_sel_hi:[0,1,1]
	v_cvt_scalef32_pk_f32_fp4 v[48:49], v149, 1.0
	v_pk_fma_f32 v[40:41], s[20:21], v[48:49], v[40:41] op_sel_hi:[0,1,1]
	v_cvt_scalef32_pk_f32_fp4 v[48:49], v149, 1.0 op_sel:[1,0,0]
	v_pk_fma_f32 v[42:43], s[20:21], v[48:49], v[42:43] op_sel_hi:[0,1,1]
	v_cvt_scalef32_pk_f32_fp4 v[48:49], v149, 1.0 op_sel:[0,1,0]
	v_pk_fma_f32 v[44:45], s[20:21], v[48:49], v[44:45] op_sel_hi:[0,1,1]
	v_cvt_scalef32_pk_f32_fp4 v[48:49], v149, 1.0 op_sel:[1,1,0]
	v_pk_fma_f32 v[46:47], s[20:21], v[48:49], v[46:47] op_sel_hi:[0,1,1]
	v_cvt_scalef32_pk_f32_fp4 v[48:49], v146, 1.0
	v_pk_fma_f32 v[174:175], s[22:23], v[48:49], v[32:33] op_sel_hi:[0,1,1]
	v_cvt_scalef32_pk_f32_fp4 v[32:33], v146, 1.0 op_sel:[1,0,0]
	v_pk_fma_f32 v[192:193], s[22:23], v[32:33], v[34:35] op_sel_hi:[0,1,1]
	v_cvt_scalef32_pk_f32_fp4 v[32:33], v146, 1.0 op_sel:[0,1,0]
	v_pk_fma_f32 v[188:189], s[22:23], v[32:33], v[36:37] op_sel_hi:[0,1,1]
	v_cvt_scalef32_pk_f32_fp4 v[32:33], v146, 1.0 op_sel:[1,1,0]
	v_pk_fma_f32 v[190:191], s[22:23], v[32:33], v[38:39] op_sel_hi:[0,1,1]
	v_cvt_scalef32_pk_f32_fp4 v[32:33], v147, 1.0
	v_pk_fma_f32 v[184:185], s[22:23], v[32:33], v[40:41] op_sel_hi:[0,1,1]
	v_cvt_scalef32_pk_f32_fp4 v[32:33], v147, 1.0 op_sel:[1,0,0]
	v_pk_fma_f32 v[186:187], s[22:23], v[32:33], v[42:43] op_sel_hi:[0,1,1]
	v_cvt_scalef32_pk_f32_fp4 v[32:33], v147, 1.0 op_sel:[0,1,0]
	v_pk_fma_f32 v[178:179], s[22:23], v[32:33], v[44:45] op_sel_hi:[0,1,1]
	v_cvt_scalef32_pk_f32_fp4 v[32:33], v147, 1.0 op_sel:[1,1,0]
	v_pk_fma_f32 v[180:181], s[22:23], v[32:33], v[46:47] op_sel_hi:[0,1,1]
	s_and_b64 vcc, exec, s[8:9]
	s_cbranch_vccnz .LBB0_2569
	s_mov_b32 s18, s48
	s_add_i32 s48, s18, 16
	s_cmpk_gt_u32 s18, 0x6f
	s_cselect_b64 s[8:9], -1, 0
	s_cmpk_lt_u32 s18, 0x70
	s_cselect_b64 vcc, -1, 0
	s_bitcmp0_b32 s48, 6
	s_cselect_b64 s[6:7], -1, 0
	v_cndmask_b32_e64 v104, v102, v100, s[6:7]
	v_cndmask_b32_e32 v104, v114, v104, vcc
	s_nop 0
	s_waitcnt vmcnt(24)
	v_accvgpr_read_b32 v183, a29
	v_accvgpr_read_b32 v177, a31
	v_accvgpr_read_b32 v173, a33
	v_accvgpr_read_b32 v171, a35
	v_accvgpr_read_b32 v95, a11
	v_mov_b64_e32 v[88:89], v[250:251]
	v_accvgpr_read_b32 v87, a3
	v_accvgpr_read_b32 v83, a7
	v_accvgpr_read_b32 v182, a28
	v_accvgpr_read_b32 v176, a30
	v_accvgpr_read_b32 v172, a32
	v_accvgpr_read_b32 v170, a34
	v_accvgpr_read_b32 v94, a10
	v_accvgpr_read_b32 v93, a9
	v_accvgpr_read_b32 v92, a8
	v_mov_b64_e32 v[90:91], v[252:253]
	v_accvgpr_read_b32 v86, a2
	v_accvgpr_read_b32 v85, a1
	v_accvgpr_read_b32 v84, a0
	v_accvgpr_read_b32 v82, a6
	v_accvgpr_read_b32 v81, a5
	v_accvgpr_read_b32 v80, a4
	s_add_i32 s22, s18, 16
	v_readlane_b32 s20, v104, s22
	s_nop 1
	v_mad_i64_i32 v[108:109], s[6:7], s20, v194, v[96:97]
	global_load_dwordx4 a[8:11], v[108:109], off
	v_mad_i64_i32 v[108:109], s[6:7], s20, v194, v[98:99]
	global_load_dwordx2 a[28:29], v[108:109], off
	s_add_i32 s22, s18, 17
	v_readlane_b32 s20, v104, s22
	s_nop 1
	v_mad_i64_i32 v[108:109], s[6:7], s20, v194, v[96:97]
	global_load_dwordx4 v[250:253], v[108:109], off
	v_mad_i64_i32 v[108:109], s[6:7], s20, v194, v[98:99]
	global_load_dwordx2 a[30:31], v[108:109], off
	s_add_i32 s22, s18, 18
	v_readlane_b32 s20, v104, s22
	s_nop 1
	v_mad_i64_i32 v[108:109], s[6:7], s20, v194, v[96:97]
	global_load_dwordx4 a[0:3], v[108:109], off
	v_mad_i64_i32 v[108:109], s[6:7], s20, v194, v[98:99]
	global_load_dwordx2 a[32:33], v[108:109], off
	s_add_i32 s22, s18, 19
	v_readlane_b32 s20, v104, s22
	s_nop 1
	v_mad_i64_i32 v[108:109], s[6:7], s20, v194, v[96:97]
	global_load_dwordx4 a[4:7], v[108:109], off
	v_mad_i64_i32 v[108:109], s[6:7], s20, v194, v[98:99]
	global_load_dwordx2 a[34:35], v[108:109], off
	s_waitcnt vmcnt(24)
	v_accvgpr_read_b32 v169, a37
	v_accvgpr_read_b32 v167, a39
	v_accvgpr_read_b32 v165, a41
	v_accvgpr_read_b32 v163, a43
	v_mov_b64_e32 v[76:77], v[214:215]
	v_mov_b64_e32 v[72:73], v[218:219]
	v_mov_b64_e32 v[68:69], v[222:223]
	v_mov_b64_e32 v[64:65], v[226:227]
	v_accvgpr_read_b32 v168, a36
	v_accvgpr_read_b32 v166, a38
	v_accvgpr_read_b32 v164, a40
	v_accvgpr_read_b32 v162, a42
	v_mov_b64_e32 v[78:79], v[216:217]
	v_mov_b64_e32 v[74:75], v[220:221]
	v_mov_b64_e32 v[70:71], v[224:225]
	v_mov_b64_e32 v[66:67], v[228:229]
	s_add_i32 s22, s18, 20
	v_readlane_b32 s20, v104, s22
	s_nop 1
	v_mad_i64_i32 v[108:109], s[6:7], s20, v194, v[96:97]
	global_load_dwordx4 v[214:217], v[108:109], off
	v_mad_i64_i32 v[108:109], s[6:7], s20, v194, v[98:99]
	global_load_dwordx2 a[36:37], v[108:109], off
	s_add_i32 s22, s18, 21
	v_readlane_b32 s20, v104, s22
	s_nop 1
	v_mad_i64_i32 v[108:109], s[6:7], s20, v194, v[96:97]
	global_load_dwordx4 v[218:221], v[108:109], off
	v_mad_i64_i32 v[108:109], s[6:7], s20, v194, v[98:99]
	global_load_dwordx2 a[38:39], v[108:109], off
	s_add_i32 s22, s18, 22
	v_readlane_b32 s20, v104, s22
	s_nop 1
	v_mad_i64_i32 v[108:109], s[6:7], s20, v194, v[96:97]
	global_load_dwordx4 v[222:225], v[108:109], off
	v_mad_i64_i32 v[108:109], s[6:7], s20, v194, v[98:99]
	global_load_dwordx2 a[40:41], v[108:109], off
	s_add_i32 s22, s18, 23
	v_readlane_b32 s20, v104, s22
	s_nop 1
	v_mad_i64_i32 v[108:109], s[6:7], s20, v194, v[96:97]
	global_load_dwordx4 v[226:229], v[108:109], off
	v_mad_i64_i32 v[108:109], s[6:7], s20, v194, v[98:99]
	global_load_dwordx2 a[42:43], v[108:109], off
	s_waitcnt vmcnt(24)
	v_accvgpr_read_b32 v161, a45
	v_accvgpr_read_b32 v159, a47
	v_accvgpr_read_b32 v157, a49
	v_accvgpr_read_b32 v155, a51
	v_mov_b64_e32 v[60:61], v[230:231]
	v_mov_b64_e32 v[56:57], v[234:235]
	v_mov_b64_e32 v[52:53], v[238:239]
	v_mov_b64_e32 v[48:49], v[242:243]
	v_accvgpr_read_b32 v160, a44
	v_accvgpr_read_b32 v158, a46
	v_accvgpr_read_b32 v156, a48
	v_accvgpr_read_b32 v154, a50
	v_mov_b64_e32 v[62:63], v[232:233]
	v_mov_b64_e32 v[58:59], v[236:237]
	v_mov_b64_e32 v[54:55], v[240:241]
	v_mov_b64_e32 v[50:51], v[244:245]
	s_add_i32 s22, s18, 24
	v_readlane_b32 s20, v104, s22
	s_nop 1
	v_mad_i64_i32 v[108:109], s[6:7], s20, v194, v[96:97]
	global_load_dwordx4 v[230:233], v[108:109], off
	v_mad_i64_i32 v[108:109], s[6:7], s20, v194, v[98:99]
	global_load_dwordx2 a[44:45], v[108:109], off
	s_add_i32 s22, s18, 25
	v_readlane_b32 s20, v104, s22
	s_nop 1
	v_mad_i64_i32 v[108:109], s[6:7], s20, v194, v[96:97]
	global_load_dwordx4 v[234:237], v[108:109], off
	v_mad_i64_i32 v[108:109], s[6:7], s20, v194, v[98:99]
	global_load_dwordx2 a[46:47], v[108:109], off
	s_add_i32 s22, s18, 26
	v_readlane_b32 s20, v104, s22
	s_nop 1
	v_mad_i64_i32 v[108:109], s[6:7], s20, v194, v[96:97]
	global_load_dwordx4 v[238:241], v[108:109], off
	v_mad_i64_i32 v[108:109], s[6:7], s20, v194, v[98:99]
	global_load_dwordx2 a[48:49], v[108:109], off
	s_add_i32 s22, s18, 27
	v_readlane_b32 s20, v104, s22
	s_nop 1
	v_mad_i64_i32 v[108:109], s[6:7], s20, v194, v[96:97]
	global_load_dwordx4 v[242:245], v[108:109], off
	v_mad_i64_i32 v[108:109], s[6:7], s20, v194, v[98:99]
	global_load_dwordx2 a[50:51], v[108:109], off
	s_waitcnt vmcnt(24)
	v_accvgpr_read_b32 v153, a25
	v_accvgpr_read_b32 v151, a23
	v_accvgpr_read_b32 v149, a21
	v_accvgpr_read_b32 v147, a27
	v_mov_b64_e32 v[44:45], v[246:247]
	v_mov_b64_e32 v[40:41], v[210:211]
	v_mov_b64_e32 v[36:37], v[206:207]
	v_mov_b64_e32 v[32:33], v[202:203]
	v_accvgpr_read_b32 v152, a24
	v_accvgpr_read_b32 v150, a22
	v_accvgpr_read_b32 v148, a20
	v_accvgpr_read_b32 v146, a26
	v_mov_b64_e32 v[46:47], v[248:249]
	v_mov_b64_e32 v[42:43], v[212:213]
	v_mov_b64_e32 v[38:39], v[208:209]
	v_mov_b64_e32 v[34:35], v[204:205]
	s_add_i32 s22, s18, 28
	v_readlane_b32 s20, v104, s22
	s_nop 1
	v_mad_i64_i32 v[108:109], s[6:7], s20, v194, v[96:97]
	global_load_dwordx4 v[246:249], v[108:109], off
	v_mad_i64_i32 v[108:109], s[6:7], s20, v194, v[98:99]
	global_load_dwordx2 a[24:25], v[108:109], off
	s_add_i32 s22, s18, 29
	v_readlane_b32 s20, v104, s22
	s_nop 1
	v_mad_i64_i32 v[108:109], s[6:7], s20, v194, v[96:97]
	global_load_dwordx4 v[210:213], v[108:109], off
	v_mad_i64_i32 v[108:109], s[6:7], s20, v194, v[98:99]
	global_load_dwordx2 a[22:23], v[108:109], off
	s_add_i32 s22, s18, 30
	v_readlane_b32 s20, v104, s22
	s_nop 1
	v_mad_i64_i32 v[108:109], s[6:7], s20, v194, v[96:97]
	global_load_dwordx4 v[206:209], v[108:109], off
	v_mad_i64_i32 v[108:109], s[6:7], s20, v194, v[98:99]
	global_load_dwordx2 a[20:21], v[108:109], off
	s_add_i32 s22, s18, 31
	v_readlane_b32 s20, v104, s22
	s_nop 1
	v_mad_i64_i32 v[108:109], s[6:7], s20, v194, v[96:97]
	global_load_dwordx4 v[202:205], v[108:109], off
	v_mad_i64_i32 v[108:109], s[6:7], s20, v194, v[98:99]
	global_load_dwordx2 a[26:27], v[108:109], off
	s_cmp_lg_u32 s18, 64
	s_cbranch_scc1 .LBB0_2573
	v_ashrrev_i32_e32 v115, 31, v114
	v_ashrrev_i32_e32 v117, 31, v116
	v_lshlrev_b64 v[138:139], 2, v[116:117]
	v_lshl_add_u64 v[142:143], s[12:13], 0, v[138:139]
	v_lshl_add_u64 v[138:139], s[14:15], 0, v[138:139]
	v_lshlrev_b64 v[140:141], 2, v[114:115]
	v_lshl_add_u64 v[144:145], s[12:13], 0, v[140:141]
	v_lshl_add_u64 v[140:141], s[14:15], 0, v[140:141]
	global_load_dword a53, v[144:145], off
	global_load_dword a54, v[142:143], off
	global_load_dword v103, v[140:141], off
	global_load_dword v101, v[138:139], off
	s_branch .LBB0_2573
